# P5 K-loop head spurious vmcnt(0) removed + s_setprio/lgkmcnt moved in front of the MFMA-phase barrier in all K-loops (size-neutral)
# speedup vs baseline: 1.0194x; 1.0099x over previous
; #define PG8_STAGE(bufoff, gbase, voff) do { const char* _gb = (const char*)(gbase); asm volatile("" : "+s"(_gb)); _Pragma("unroll") for (int _i = 0; _i < 2; ++_i) { asm volatile("" : "+v"((voff)[_i])); \
;         __builtin_amdgcn_global_load_lds((const unsigned*)(_gb + (voff)[_i]), (PG8_LAS unsigned*)(lds + (bufoff) + ldsw + _i * 8192), 16, 0, 0); } } while (0)
; #define PG8_LDA(dst, b, h) do { _Pragma("unroll") for (int m = 0; m < 4; ++m) _Pragma("unroll") for (int k = 0; k < 2; ++k) dst[m][k] = *(const PG8_LAS bf16x8*)(lds + PG8_SA(b, h) + aoff + m * 2048 + k * 1024); } while (0)
; #define PG8_LDB(dst, b, h) do { _Pragma("unroll") for (int n = 0; n < 2; ++n) _Pragma("unroll") for (int k = 0; k < 2; ++k) dst[n][k] = *(const PG8_LAS bf16x8*)(lds + PG8_SB(b, h) + boff + n * 2048 + k * 1024); } while (0)
; #define PG8_WAIT_V(n) asm volatile("s_waitcnt vmcnt(" #n ")" ::: "memory")
; #define PG8_WAIT_L(n) asm volatile("s_waitcnt lgkmcnt(" #n ")" ::: "memory")
; #define PG8_BAR __builtin_amdgcn_s_barrier()
; #define PG8_SCHED __builtin_amdgcn_sched_barrier(0)
; #define PG8_STAGE(bufoff, gbase, voff) do { const char* _gb = (const char*)(gbase); asm volatile("" : "+s"(_gb)); _Pragma("unroll") for (int _i = 0; _i < 2; ++_i) { asm volatile("" : "+v"((voff)[_i])); \
;         __builtin_amdgcn_global_load_lds((const unsigned*)(_gb + (voff)[_i]), (PG8_LAS unsigned*)(lds + (bufoff) + ldsw + _i * 8192), 16, 0, 0); } } while (0)
; #define PG8_LDA(dst, b, h) do { _Pragma("unroll") for (int m = 0; m < 4; ++m) _Pragma("unroll") for (int k = 0; k < 2; ++k) dst[m][k] = *(const PG8_LAS bf16x8*)(lds + PG8_SA(b, h) + aoff + m * 2048 + k * 1024); } while (0)
; #define PG8_WAIT_V(n) asm volatile("s_waitcnt vmcnt(" #n ")" ::: "memory")
; template <class Epi, class Sched, bool ALIGN_EPI = false, bool SP2 = false>
; __device__ __forceinline__ void gemm_phase(PG8_LAS unsigned char* lds, const Gemm g, const Sched& S, const Epi& E) {
;     ...
;             PG8_LDB(B0, 0, 0); PG8_LDB(B1, 0, 1); PG8_SCHED; PG8_LDA(At, 0, 0); PG8_STAGE(PG8_SA(1, 1), a1 + hstep, voffA);
;             PG8_WAIT_V(8); PG8_WAIT_L(0); PG8_BAR; PG8_MMA2(0); PG8_BAR; PG8_SCHED;
;             PG8_LDA(At, 0, 1); PG8_STAGE(PG8_SB(0, 0), b2, voffB); PG8_STAGE(PG8_SB(0, 1), b2 + hstep, voffB); PG8_STAGE(PG8_SA(0, 0), a2, voffA);
;             PG8_WAIT_V(8); PG8_WAIT_L(0); PG8_BAR; PG8_MMA2(1); PG8_BAR; PG8_SCHED;
.LBB0_313:
	ds_read_b128 v[136:139], v150
	ds_read_b128 v[140:143], v150 offset:1024
	ds_read_b128 v[154:157], v150 offset:2048
	ds_read_b128 v[158:161], v150 offset:3072
	ds_read_b128 v[162:165], v151
	ds_read_b128 v[166:169], v151 offset:1024
	ds_read_b128 v[170:173], v151 offset:2048
	ds_read_b128 v[174:177], v151 offset:3072
	s_add_u32 s14, s8, 0x100
	s_addc_u32 s15, s9, 0
	s_cmp_eq_u32 s43, 60
	s_cselect_b32 s24, s13, s14
	s_cselect_b32 s25, s11, s15
	s_cselect_b32 s16, s36, s37
	s_cselect_b32 s17, s33, s42
	s_add_u32 s2, s24, 0x80
	s_addc_u32 s3, s25, 0
	s_add_u32 s8, s8, 0x100080
	s_addc_u32 s9, s9, 0
	s_add_i32 m0, s63, 0xc000
	ds_read_b128 v[178:181], v152
	ds_read_b128 v[182:185], v152 offset:1024
	ds_read_b128 v[186:189], v152 offset:2048
	ds_read_b128 v[190:193], v152 offset:3072
	ds_read_b128 v[194:197], v152 offset:4096
	ds_read_b128 v[198:201], v152 offset:5120
	ds_read_b128 v[202:205], v152 offset:6144
	ds_read_b128 v[206:209], v152 offset:7168
	s_nop 0
	global_load_lds_dwordx4 v1, s[8:9]
	s_add_i32 m0, s63, 0xe000
	s_nop 0
	global_load_lds_dwordx4 v145, s[8:9]
	s_waitcnt vmcnt(8)
	s_waitcnt lgkmcnt(0)
	s_setprio 1
	s_waitcnt lgkmcnt(0)
	s_barrier
	v_mfma_f32_16x16x32_bf16 v[126:129], v[136:139], v[178:181], v[126:129]
	v_mfma_f32_16x16x32_bf16 v[122:125], v[154:157], v[178:181], v[122:125]
	v_mfma_f32_16x16x32_bf16 v[110:113], v[136:139], v[186:189], v[110:113]
	v_mfma_f32_16x16x32_bf16 v[106:109], v[154:157], v[186:189], v[106:109]
	v_mfma_f32_16x16x32_bf16 v[94:97], v[136:139], v[194:197], v[94:97]
	v_mfma_f32_16x16x32_bf16 v[90:93], v[154:157], v[194:197], v[90:93]
	v_mfma_f32_16x16x32_bf16 v[78:81], v[136:139], v[202:205], v[78:81]
	v_mfma_f32_16x16x32_bf16 v[74:77], v[154:157], v[202:205], v[74:77]
	v_mfma_f32_16x16x32_bf16 v[118:121], v[162:165], v[178:181], v[118:121]
	v_mfma_f32_16x16x32_bf16 v[114:117], v[170:173], v[178:181], v[114:117]
	v_mfma_f32_16x16x32_bf16 v[102:105], v[162:165], v[186:189], v[102:105]
	v_mfma_f32_16x16x32_bf16 v[98:101], v[170:173], v[186:189], v[98:101]
	v_mfma_f32_16x16x32_bf16 v[86:89], v[162:165], v[194:197], v[86:89]
	v_mfma_f32_16x16x32_bf16 v[82:85], v[170:173], v[194:197], v[82:85]
	v_mfma_f32_16x16x32_bf16 v[70:73], v[162:165], v[202:205], v[70:73]
	v_mfma_f32_16x16x32_bf16 v[66:69], v[170:173], v[202:205], v[66:69]
	v_mfma_f32_16x16x32_bf16 v[126:129], v[140:143], v[182:185], v[126:129]
	v_mfma_f32_16x16x32_bf16 v[122:125], v[158:161], v[182:185], v[122:125]
	v_mfma_f32_16x16x32_bf16 v[110:113], v[140:143], v[190:193], v[110:113]
	v_mfma_f32_16x16x32_bf16 v[106:109], v[158:161], v[190:193], v[106:109]
	v_mfma_f32_16x16x32_bf16 v[94:97], v[140:143], v[198:201], v[94:97]
	v_mfma_f32_16x16x32_bf16 v[90:93], v[158:161], v[198:201], v[90:93]
	v_mfma_f32_16x16x32_bf16 v[78:81], v[140:143], v[206:209], v[78:81]
	v_mfma_f32_16x16x32_bf16 v[74:77], v[158:161], v[206:209], v[74:77]
	v_mfma_f32_16x16x32_bf16 v[118:121], v[166:169], v[182:185], v[118:121]
	v_mfma_f32_16x16x32_bf16 v[114:117], v[174:177], v[182:185], v[114:117]
	v_mfma_f32_16x16x32_bf16 v[102:105], v[166:169], v[190:193], v[102:105]
	v_mfma_f32_16x16x32_bf16 v[98:101], v[174:177], v[190:193], v[98:101]
	v_mfma_f32_16x16x32_bf16 v[86:89], v[166:169], v[198:201], v[86:89]
	v_mfma_f32_16x16x32_bf16 v[82:85], v[174:177], v[198:201], v[82:85]
	v_mfma_f32_16x16x32_bf16 v[70:73], v[166:169], v[206:209], v[70:73]
	v_mfma_f32_16x16x32_bf16 v[66:69], v[174:177], v[206:209], v[66:69]
	s_setprio 0
	s_barrier
	s_add_i32 s44, s95, s61
	s_mov_b64 s[8:9], s[16:17]
	s_mov_b32 m0, s44
	ds_read_b128 v[178:181], v152 offset:16384
	ds_read_b128 v[182:185], v152 offset:17408
	ds_read_b128 v[186:189], v152 offset:18432
	ds_read_b128 v[190:193], v152 offset:19456
	ds_read_b128 v[194:197], v152 offset:20480
	ds_read_b128 v[198:201], v152 offset:21504
	ds_read_b128 v[202:205], v152 offset:22528
	ds_read_b128 v[206:209], v152 offset:23552
	s_nop 0
	global_load_lds_dwordx4 v144, s[8:9]
	s_add_i32 m0, s44, 0x2000
	s_nop 0
	global_load_lds_dwordx4 v146, s[8:9]
	s_add_u32 s8, s16, 0x100000
	s_addc_u32 s9, s17, 0
	s_add_i32 s44, s96, s61
	s_mov_b32 m0, s44
	s_nop 0
	global_load_lds_dwordx4 v144, s[8:9]
	s_add_i32 m0, s44, 0x2000
	s_nop 0
	global_load_lds_dwordx4 v146, s[8:9]
	s_mov_b64 s[8:9], s[24:25]
	s_mov_b32 m0, s63
	s_nop 0
	global_load_lds_dwordx4 v1, s[8:9]
	s_mov_b32 m0, s65
	s_nop 0
	global_load_lds_dwordx4 v145, s[8:9]
	s_waitcnt vmcnt(8)
	s_waitcnt lgkmcnt(0)
	s_setprio 1
	s_waitcnt lgkmcnt(0)
	s_barrier
	v_mfma_f32_16x16x32_bf16 v[62:65], v[136:139], v[178:181], v[62:65]
	v_mfma_f32_16x16x32_bf16 v[58:61], v[154:157], v[178:181], v[58:61]
	v_mfma_f32_16x16x32_bf16 v[46:49], v[136:139], v[186:189], v[46:49]
	v_mfma_f32_16x16x32_bf16 v[42:45], v[154:157], v[186:189], v[42:45]
	v_mfma_f32_16x16x32_bf16 v[30:33], v[136:139], v[194:197], v[30:33]
	v_mfma_f32_16x16x32_bf16 v[26:29], v[154:157], v[194:197], v[26:29]
	v_mfma_f32_16x16x32_bf16 v[14:17], v[136:139], v[202:205], v[14:17]
	v_mfma_f32_16x16x32_bf16 v[10:13], v[154:157], v[202:205], v[10:13]
	v_mfma_f32_16x16x32_bf16 v[54:57], v[162:165], v[178:181], v[54:57]
	v_mfma_f32_16x16x32_bf16 v[50:53], v[170:173], v[178:181], v[50:53]
	v_mfma_f32_16x16x32_bf16 v[38:41], v[162:165], v[186:189], v[38:41]
	v_mfma_f32_16x16x32_bf16 v[34:37], v[170:173], v[186:189], v[34:37]
	v_mfma_f32_16x16x32_bf16 v[22:25], v[162:165], v[194:197], v[22:25]
	v_mfma_f32_16x16x32_bf16 v[18:21], v[170:173], v[194:197], v[18:21]
	v_mfma_f32_16x16x32_bf16 v[6:9], v[162:165], v[202:205], v[6:9]
	v_mfma_f32_16x16x32_bf16 v[2:5], v[170:173], v[202:205], v[2:5]
	v_mfma_f32_16x16x32_bf16 v[62:65], v[140:143], v[182:185], v[62:65]
	v_mfma_f32_16x16x32_bf16 v[58:61], v[158:161], v[182:185], v[58:61]
	v_mfma_f32_16x16x32_bf16 v[46:49], v[140:143], v[190:193], v[46:49]
	v_mfma_f32_16x16x32_bf16 v[42:45], v[158:161], v[190:193], v[42:45]
	v_mfma_f32_16x16x32_bf16 v[30:33], v[140:143], v[198:201], v[30:33]
	v_mfma_f32_16x16x32_bf16 v[26:29], v[158:161], v[198:201], v[26:29]
	v_mfma_f32_16x16x32_bf16 v[14:17], v[140:143], v[206:209], v[14:17]
	v_mfma_f32_16x16x32_bf16 v[10:13], v[158:161], v[206:209], v[10:13]
	v_mfma_f32_16x16x32_bf16 v[54:57], v[166:169], v[182:185], v[54:57]
	v_mfma_f32_16x16x32_bf16 v[50:53], v[174:177], v[182:185], v[50:53]
	v_mfma_f32_16x16x32_bf16 v[38:41], v[166:169], v[190:193], v[38:41]
	v_mfma_f32_16x16x32_bf16 v[34:37], v[174:177], v[190:193], v[34:37]
	v_mfma_f32_16x16x32_bf16 v[22:25], v[166:169], v[198:201], v[22:25]
	v_mfma_f32_16x16x32_bf16 v[18:21], v[174:177], v[198:201], v[18:21]
	v_mfma_f32_16x16x32_bf16 v[6:9], v[166:169], v[206:209], v[6:9]
	v_mfma_f32_16x16x32_bf16 v[2:5], v[174:177], v[206:209], v[2:5]
	s_setprio 0
	s_barrier
; #define PG8_STAGE(bufoff, gbase, voff) do { const char* _gb = (const char*)(gbase); asm volatile("" : "+s"(_gb)); _Pragma("unroll") for (int _i = 0; _i < 2; ++_i) { asm volatile("" : "+v"((voff)[_i])); \
;         __builtin_amdgcn_global_load_lds((const unsigned*)(_gb + (voff)[_i]), (PG8_LAS unsigned*)(lds + (bufoff) + ldsw + _i * 8192), 16, 0, 0); } } while (0)
; #define PG8_LDA(dst, b, h) do { _Pragma("unroll") for (int m = 0; m < 4; ++m) _Pragma("unroll") for (int k = 0; k < 2; ++k) dst[m][k] = *(const PG8_LAS bf16x8*)(lds + PG8_SA(b, h) + aoff + m * 2048 + k * 1024); } while (0)
; #define PG8_LDB(dst, b, h) do { _Pragma("unroll") for (int n = 0; n < 2; ++n) _Pragma("unroll") for (int k = 0; k < 2; ++k) dst[n][k] = *(const PG8_LAS bf16x8*)(lds + PG8_SB(b, h) + boff + n * 2048 + k * 1024); } while (0)
; #define PG8_WAIT_V(n) asm volatile("s_waitcnt vmcnt(" #n ")" ::: "memory")
; #define PG8_WAIT_L(n) asm volatile("s_waitcnt lgkmcnt(" #n ")" ::: "memory")
; #define PG8_BAR __builtin_amdgcn_s_barrier()
; #define PG8_SCHED __builtin_amdgcn_sched_barrier(0)
; #define PG8_STAGE(bufoff, gbase, voff) do { const char* _gb = (const char*)(gbase); asm volatile("" : "+s"(_gb)); _Pragma("unroll") for (int _i = 0; _i < 2; ++_i) { asm volatile("" : "+v"((voff)[_i])); \
;         __builtin_amdgcn_global_load_lds((const unsigned*)(_gb + (voff)[_i]), (PG8_LAS unsigned*)(lds + (bufoff) + ldsw + _i * 8192), 16, 0, 0); } } while (0)
; #define PG8_LDA(dst, b, h) do { _Pragma("unroll") for (int m = 0; m < 4; ++m) _Pragma("unroll") for (int k = 0; k < 2; ++k) dst[m][k] = *(const PG8_LAS bf16x8*)(lds + PG8_SA(b, h) + aoff + m * 2048 + k * 1024); } while (0)
; #define PG8_WAIT_V(n) asm volatile("s_waitcnt vmcnt(" #n ")" ::: "memory")
; template <class Epi, class Sched, bool ALIGN_EPI = false, bool SP2 = false>
; __device__ __forceinline__ void gemm_phase(PG8_LAS unsigned char* lds, const Gemm g, const Sched& S, const Epi& E) {
;     ...
;             PG8_LDB(B0, 1, 0); PG8_LDB(B1, 1, 1); PG8_SCHED; PG8_LDA(At, 1, 0); PG8_STAGE(PG8_SA(0, 1), a2 + hstep, voffA);
;             PG8_WAIT_V(8); PG8_WAIT_L(0); PG8_BAR; PG8_MMA2(0); PG8_BAR; PG8_SCHED;
;             PG8_LDA(At, 1, 1); PG8_STAGE(PG8_SB(1, 0), b3, voffB); PG8_STAGE(PG8_SB(1, 1), b3 + hstep, voffB); PG8_STAGE(PG8_SA(1, 0), a3, voffA);
;             PG8_WAIT_V(8); PG8_WAIT_L(0); PG8_BAR; PG8_MMA2(1); PG8_BAR; PG8_SCHED;
	s_add_i32 s44, 0, 0x18000
	v_add_u32_e32 v135, s44, v148
	s_add_i32 s45, 0, 0x1c000
	ds_read_b128 v[136:139], v135
	ds_read_b128 v[140:143], v135 offset:1024
	ds_read_b128 v[154:157], v135 offset:2048
	ds_read_b128 v[158:161], v135 offset:3072
	v_add_u32_e32 v135, s45, v148
	ds_read_b128 v[162:165], v135
	ds_read_b128 v[166:169], v135 offset:1024
	ds_read_b128 v[170:173], v135 offset:2048
	ds_read_b128 v[174:177], v135 offset:3072
	s_add_u32 s8, s24, 0x100000
	s_addc_u32 s9, s25, 0
	s_mov_b32 m0, s88
	ds_read_b128 v[178:181], v152 offset:32768
	ds_read_b128 v[182:185], v152 offset:33792
	ds_read_b128 v[186:189], v152 offset:34816
	ds_read_b128 v[190:193], v152 offset:35840
	ds_read_b128 v[194:197], v152 offset:36864
	ds_read_b128 v[198:201], v152 offset:37888
	ds_read_b128 v[202:205], v152 offset:38912
	ds_read_b128 v[206:209], v152 offset:39936
	s_nop 0
	global_load_lds_dwordx4 v1, s[8:9]
	s_mov_b32 m0, s89
	s_nop 0
	global_load_lds_dwordx4 v145, s[8:9]
	s_waitcnt vmcnt(8)
	s_waitcnt lgkmcnt(0)
	s_setprio 1
	s_waitcnt lgkmcnt(0)
	s_barrier
	v_mfma_f32_16x16x32_bf16 v[126:129], v[136:139], v[178:181], v[126:129]
	v_mfma_f32_16x16x32_bf16 v[122:125], v[154:157], v[178:181], v[122:125]
	v_mfma_f32_16x16x32_bf16 v[110:113], v[136:139], v[186:189], v[110:113]
	v_mfma_f32_16x16x32_bf16 v[106:109], v[154:157], v[186:189], v[106:109]
	v_mfma_f32_16x16x32_bf16 v[94:97], v[136:139], v[194:197], v[94:97]
	v_mfma_f32_16x16x32_bf16 v[90:93], v[154:157], v[194:197], v[90:93]
	v_mfma_f32_16x16x32_bf16 v[78:81], v[136:139], v[202:205], v[78:81]
	v_mfma_f32_16x16x32_bf16 v[74:77], v[154:157], v[202:205], v[74:77]
	v_mfma_f32_16x16x32_bf16 v[118:121], v[162:165], v[178:181], v[118:121]
	v_mfma_f32_16x16x32_bf16 v[114:117], v[170:173], v[178:181], v[114:117]
	v_mfma_f32_16x16x32_bf16 v[102:105], v[162:165], v[186:189], v[102:105]
	v_mfma_f32_16x16x32_bf16 v[98:101], v[170:173], v[186:189], v[98:101]
	v_mfma_f32_16x16x32_bf16 v[86:89], v[162:165], v[194:197], v[86:89]
	v_mfma_f32_16x16x32_bf16 v[82:85], v[170:173], v[194:197], v[82:85]
	v_mfma_f32_16x16x32_bf16 v[70:73], v[162:165], v[202:205], v[70:73]
	v_mfma_f32_16x16x32_bf16 v[66:69], v[170:173], v[202:205], v[66:69]
	v_mfma_f32_16x16x32_bf16 v[126:129], v[140:143], v[182:185], v[126:129]
	v_mfma_f32_16x16x32_bf16 v[122:125], v[158:161], v[182:185], v[122:125]
	v_mfma_f32_16x16x32_bf16 v[110:113], v[140:143], v[190:193], v[110:113]
	v_mfma_f32_16x16x32_bf16 v[106:109], v[158:161], v[190:193], v[106:109]
	v_mfma_f32_16x16x32_bf16 v[94:97], v[140:143], v[198:201], v[94:97]
	v_mfma_f32_16x16x32_bf16 v[90:93], v[158:161], v[198:201], v[90:93]
	v_mfma_f32_16x16x32_bf16 v[78:81], v[140:143], v[206:209], v[78:81]
	v_mfma_f32_16x16x32_bf16 v[74:77], v[158:161], v[206:209], v[74:77]
	v_mfma_f32_16x16x32_bf16 v[118:121], v[166:169], v[182:185], v[118:121]
	v_mfma_f32_16x16x32_bf16 v[114:117], v[174:177], v[182:185], v[114:117]
	v_mfma_f32_16x16x32_bf16 v[102:105], v[166:169], v[190:193], v[102:105]
	v_mfma_f32_16x16x32_bf16 v[98:101], v[174:177], v[190:193], v[98:101]
	v_mfma_f32_16x16x32_bf16 v[86:89], v[166:169], v[198:201], v[86:89]
	v_mfma_f32_16x16x32_bf16 v[82:85], v[174:177], v[198:201], v[82:85]
	v_mfma_f32_16x16x32_bf16 v[70:73], v[166:169], v[206:209], v[70:73]
	v_mfma_f32_16x16x32_bf16 v[66:69], v[174:177], v[206:209], v[66:69]
	s_setprio 0
	s_barrier
	s_add_u32 s8, s16, 0x80
	s_addc_u32 s9, s17, 0
	s_add_i32 s24, s44, s61
	s_mov_b32 m0, s24
	ds_read_b128 v[178:181], v152 offset:49152
	ds_read_b128 v[182:185], v152 offset:50176
	ds_read_b128 v[186:189], v152 offset:51200
	ds_read_b128 v[190:193], v152 offset:52224
	ds_read_b128 v[194:197], v152 offset:53248
	ds_read_b128 v[198:201], v152 offset:54272
	ds_read_b128 v[202:205], v152 offset:55296
	ds_read_b128 v[206:209], v152 offset:56320
	s_nop 0
	global_load_lds_dwordx4 v144, s[8:9]
	s_add_i32 m0, s24, 0x2000
	s_nop 0
	global_load_lds_dwordx4 v146, s[8:9]
	s_add_u32 s8, s16, 0x100080
	s_addc_u32 s9, s17, 0
	s_add_i32 s16, s45, s61
	s_mov_b32 m0, s16
	s_nop 0
	global_load_lds_dwordx4 v144, s[8:9]
	s_add_i32 m0, s16, 0x2000
	s_nop 0
	global_load_lds_dwordx4 v146, s[8:9]
	s_mov_b32 m0, s91
	s_nop 0
	global_load_lds_dwordx4 v1, s[2:3]
	s_mov_b32 m0, s92
	s_nop 0
	global_load_lds_dwordx4 v145, s[2:3]
	s_waitcnt vmcnt(8)
	s_waitcnt lgkmcnt(0)
	s_setprio 1
	s_waitcnt lgkmcnt(0)
	s_barrier
	v_mfma_f32_16x16x32_bf16 v[62:65], v[136:139], v[178:181], v[62:65]
	v_mfma_f32_16x16x32_bf16 v[58:61], v[154:157], v[178:181], v[58:61]
	v_mfma_f32_16x16x32_bf16 v[46:49], v[136:139], v[186:189], v[46:49]
	v_mfma_f32_16x16x32_bf16 v[42:45], v[154:157], v[186:189], v[42:45]
	v_mfma_f32_16x16x32_bf16 v[30:33], v[136:139], v[194:197], v[30:33]
	v_mfma_f32_16x16x32_bf16 v[26:29], v[154:157], v[194:197], v[26:29]
	v_mfma_f32_16x16x32_bf16 v[14:17], v[136:139], v[202:205], v[14:17]
	v_mfma_f32_16x16x32_bf16 v[10:13], v[154:157], v[202:205], v[10:13]
	v_mfma_f32_16x16x32_bf16 v[54:57], v[162:165], v[178:181], v[54:57]
	v_mfma_f32_16x16x32_bf16 v[50:53], v[170:173], v[178:181], v[50:53]
	v_mfma_f32_16x16x32_bf16 v[38:41], v[162:165], v[186:189], v[38:41]
	v_mfma_f32_16x16x32_bf16 v[34:37], v[170:173], v[186:189], v[34:37]
	v_mfma_f32_16x16x32_bf16 v[22:25], v[162:165], v[194:197], v[22:25]
	v_mfma_f32_16x16x32_bf16 v[18:21], v[170:173], v[194:197], v[18:21]
	v_mfma_f32_16x16x32_bf16 v[6:9], v[162:165], v[202:205], v[6:9]
	v_mfma_f32_16x16x32_bf16 v[2:5], v[170:173], v[202:205], v[2:5]
	v_mfma_f32_16x16x32_bf16 v[62:65], v[140:143], v[182:185], v[62:65]
	v_mfma_f32_16x16x32_bf16 v[58:61], v[158:161], v[182:185], v[58:61]
	v_mfma_f32_16x16x32_bf16 v[46:49], v[140:143], v[190:193], v[46:49]
	v_mfma_f32_16x16x32_bf16 v[42:45], v[158:161], v[190:193], v[42:45]
	v_mfma_f32_16x16x32_bf16 v[30:33], v[140:143], v[198:201], v[30:33]
	v_mfma_f32_16x16x32_bf16 v[26:29], v[158:161], v[198:201], v[26:29]
	v_mfma_f32_16x16x32_bf16 v[14:17], v[140:143], v[206:209], v[14:17]
	v_mfma_f32_16x16x32_bf16 v[10:13], v[158:161], v[206:209], v[10:13]
	v_mfma_f32_16x16x32_bf16 v[54:57], v[166:169], v[182:185], v[54:57]
	v_mfma_f32_16x16x32_bf16 v[50:53], v[174:177], v[182:185], v[50:53]
	v_mfma_f32_16x16x32_bf16 v[38:41], v[166:169], v[190:193], v[38:41]
	v_mfma_f32_16x16x32_bf16 v[34:37], v[174:177], v[190:193], v[34:37]
	v_mfma_f32_16x16x32_bf16 v[22:25], v[166:169], v[198:201], v[22:25]
	v_mfma_f32_16x16x32_bf16 v[18:21], v[174:177], v[198:201], v[18:21]
	v_mfma_f32_16x16x32_bf16 v[6:9], v[166:169], v[206:209], v[6:9]
	v_mfma_f32_16x16x32_bf16 v[2:5], v[174:177], v[206:209], v[2:5]
	s_setprio 0
	s_barrier
	s_add_i32 s43, s43, 2
	s_add_u32 s37, s37, 0x100
	s_addc_u32 s42, s42, 0
	s_cmp_gt_u32 s43, 61
	s_mov_b64 s[8:9], s[14:15]
	s_cbranch_scc0 .LBB0_313
	s_and_b64 vcc, exec, s[58:59]
	s_cbranch_vccz .LBB0_333
	s_barrier
	s_cmp_lt_i32 s12, 24
	s_cbranch_scc0 .LBB0_334

.LBB0_746:
	ds_read_b128 v[118:121], v172
	ds_read_b128 v[134:137], v172 offset:1024
	ds_read_b128 v[138:141], v172 offset:2048
	ds_read_b128 v[142:145], v172 offset:3072
	ds_read_b128 v[146:149], v173
	ds_read_b128 v[150:153], v173 offset:1024
	ds_read_b128 v[154:157], v173 offset:2048
	ds_read_b128 v[176:179], v173 offset:3072
	s_add_u32 s16, s0, 0x100
	s_addc_u32 s17, s1, 0
	s_cmp_eq_u32 s33, 28
	s_cselect_b32 s26, s30, s16
	s_cselect_b32 s27, s31, s17
	s_cselect_b32 s24, s78, s5
	s_cselect_b32 s25, s79, s21
	s_add_u32 s2, s26, 0x80
	s_addc_u32 s3, s27, 0
	s_add_u32 s0, s0, 0x100080
	s_addc_u32 s1, s1, 0
	s_add_i32 s76, s46, 0xc000
	s_mov_b32 m0, s76
	s_add_i32 s77, s46, 0xe000
	ds_read_b128 v[180:183], v174
	ds_read_b128 v[184:187], v174 offset:1024
	ds_read_b128 v[188:191], v174 offset:2048
	ds_read_b128 v[192:195], v174 offset:3072
	ds_read_b128 v[196:199], v174 offset:4096
	ds_read_b128 v[200:203], v174 offset:5120
	ds_read_b128 v[204:207], v174 offset:6144
	ds_read_b128 v[208:211], v174 offset:7168
	s_nop 0
	global_load_lds_dwordx4 v1, s[0:1]
	s_mov_b32 m0, s77
	s_nop 0
	global_load_lds_dwordx4 v165, s[0:1]
	s_waitcnt vmcnt(8)
	s_waitcnt lgkmcnt(0)
	s_setprio 1
	s_waitcnt lgkmcnt(0)
	s_barrier
	v_mfma_f32_16x16x32_bf16 v[34:37], v[118:121], v[180:183], v[34:37]
	v_mfma_f32_16x16x32_bf16 v[30:33], v[138:141], v[180:183], v[30:33]
	v_mfma_f32_16x16x32_bf16 v[46:49], v[118:121], v[188:191], v[46:49]
	v_mfma_f32_16x16x32_bf16 v[62:65], v[138:141], v[188:191], v[62:65]
	v_mfma_f32_16x16x32_bf16 v[78:81], v[118:121], v[196:199], v[78:81]
	v_mfma_f32_16x16x32_bf16 v[90:93], v[138:141], v[196:199], v[90:93]
	v_mfma_f32_16x16x32_bf16 v[130:133], v[118:121], v[204:207], v[130:133]
	v_mfma_f32_16x16x32_bf16 v[114:117], v[138:141], v[204:207], v[114:117]
	v_mfma_f32_16x16x32_bf16 v[26:29], v[146:149], v[180:183], v[26:29]
	v_mfma_f32_16x16x32_bf16 v[50:53], v[154:157], v[180:183], v[50:53]
	v_mfma_f32_16x16x32_bf16 v[58:61], v[146:149], v[188:191], v[58:61]
	v_mfma_f32_16x16x32_bf16 v[82:85], v[154:157], v[188:191], v[82:85]
	v_mfma_f32_16x16x32_bf16 v[110:113], v[146:149], v[196:199], v[110:113]
	v_mfma_f32_16x16x32_bf16 v[106:109], v[154:157], v[196:199], v[106:109]
	v_mfma_f32_16x16x32_bf16 v[122:125], v[146:149], v[204:207], v[122:125]
	v_mfma_f32_16x16x32_bf16 v[126:129], v[154:157], v[204:207], v[126:129]
	v_mfma_f32_16x16x32_bf16 v[34:37], v[134:137], v[184:187], v[34:37]
	v_mfma_f32_16x16x32_bf16 v[30:33], v[142:145], v[184:187], v[30:33]
	v_mfma_f32_16x16x32_bf16 v[46:49], v[134:137], v[192:195], v[46:49]
	v_mfma_f32_16x16x32_bf16 v[62:65], v[142:145], v[192:195], v[62:65]
	v_mfma_f32_16x16x32_bf16 v[78:81], v[134:137], v[200:203], v[78:81]
	v_mfma_f32_16x16x32_bf16 v[90:93], v[142:145], v[200:203], v[90:93]
	v_mfma_f32_16x16x32_bf16 v[130:133], v[134:137], v[208:211], v[130:133]
	v_mfma_f32_16x16x32_bf16 v[114:117], v[142:145], v[208:211], v[114:117]
	v_mfma_f32_16x16x32_bf16 v[26:29], v[150:153], v[184:187], v[26:29]
	v_mfma_f32_16x16x32_bf16 v[50:53], v[176:179], v[184:187], v[50:53]
	v_mfma_f32_16x16x32_bf16 v[58:61], v[150:153], v[192:195], v[58:61]
	v_mfma_f32_16x16x32_bf16 v[82:85], v[176:179], v[192:195], v[82:85]
	v_mfma_f32_16x16x32_bf16 v[110:113], v[150:153], v[200:203], v[110:113]
	v_mfma_f32_16x16x32_bf16 v[106:109], v[176:179], v[200:203], v[106:109]
	v_mfma_f32_16x16x32_bf16 v[122:125], v[150:153], v[208:211], v[122:125]
	v_mfma_f32_16x16x32_bf16 v[126:129], v[176:179], v[208:211], v[126:129]
	s_setprio 0
	s_barrier
	s_add_i32 s80, s72, s45
	s_mov_b64 s[0:1], s[24:25]
	s_mov_b32 m0, s80
	s_add_i32 s81, s80, 0x2000
	ds_read_b128 v[180:183], v174 offset:16384
	ds_read_b128 v[184:187], v174 offset:17408
	ds_read_b128 v[188:191], v174 offset:18432
	ds_read_b128 v[192:195], v174 offset:19456
	ds_read_b128 v[196:199], v174 offset:20480
	ds_read_b128 v[200:203], v174 offset:21504
	ds_read_b128 v[204:207], v174 offset:22528
	ds_read_b128 v[208:211], v174 offset:23552
	s_nop 0
	global_load_lds_dwordx4 v164, s[0:1]
	s_mov_b32 m0, s81
	s_nop 0
	global_load_lds_dwordx4 v166, s[0:1]
	s_add_u32 s0, s24, 0x100000
	s_addc_u32 s1, s25, 0
	s_add_i32 s82, s73, s45
	s_mov_b32 m0, s82
	s_add_i32 s83, s82, 0x2000
	s_nop 0
	global_load_lds_dwordx4 v164, s[0:1]
	s_mov_b32 m0, s83
	s_nop 0
	global_load_lds_dwordx4 v166, s[0:1]
	s_mov_b64 s[0:1], s[26:27]
	s_mov_b32 m0, s46
	s_nop 0
	global_load_lds_dwordx4 v1, s[0:1]
	s_mov_b32 m0, s47
	s_nop 0
	global_load_lds_dwordx4 v165, s[0:1]
	s_waitcnt vmcnt(8)
	s_waitcnt lgkmcnt(0)
	s_setprio 1
	s_waitcnt lgkmcnt(0)
	s_barrier
	v_mfma_f32_16x16x32_bf16 v[102:105], v[118:121], v[180:183], v[102:105]
	v_mfma_f32_16x16x32_bf16 v[98:101], v[138:141], v[180:183], v[98:101]
	v_mfma_f32_16x16x32_bf16 v[74:77], v[118:121], v[188:191], v[74:77]
	v_mfma_f32_16x16x32_bf16 v[70:73], v[138:141], v[188:191], v[70:73]
	v_mfma_f32_16x16x32_bf16 v[42:45], v[118:121], v[196:199], v[42:45]
	v_mfma_f32_16x16x32_bf16 v[38:41], v[138:141], v[196:199], v[38:41]
	v_mfma_f32_16x16x32_bf16 v[18:21], v[118:121], v[204:207], v[18:21]
	v_mfma_f32_16x16x32_bf16 v[10:13], v[138:141], v[204:207], v[10:13]
	v_mfma_f32_16x16x32_bf16 v[94:97], v[146:149], v[180:183], v[94:97]
	v_mfma_f32_16x16x32_bf16 v[86:89], v[154:157], v[180:183], v[86:89]
	v_mfma_f32_16x16x32_bf16 v[66:69], v[146:149], v[188:191], v[66:69]
	v_mfma_f32_16x16x32_bf16 v[54:57], v[154:157], v[188:191], v[54:57]
	v_mfma_f32_16x16x32_bf16 v[22:25], v[146:149], v[196:199], v[22:25]
	v_mfma_f32_16x16x32_bf16 v[14:17], v[154:157], v[196:199], v[14:17]
	v_mfma_f32_16x16x32_bf16 v[6:9], v[146:149], v[204:207], v[6:9]
	v_mfma_f32_16x16x32_bf16 v[2:5], v[154:157], v[204:207], v[2:5]
	v_mfma_f32_16x16x32_bf16 v[102:105], v[134:137], v[184:187], v[102:105]
	v_mfma_f32_16x16x32_bf16 v[98:101], v[142:145], v[184:187], v[98:101]
	v_mfma_f32_16x16x32_bf16 v[74:77], v[134:137], v[192:195], v[74:77]
	v_mfma_f32_16x16x32_bf16 v[70:73], v[142:145], v[192:195], v[70:73]
	v_mfma_f32_16x16x32_bf16 v[42:45], v[134:137], v[200:203], v[42:45]
	v_mfma_f32_16x16x32_bf16 v[38:41], v[142:145], v[200:203], v[38:41]
	v_mfma_f32_16x16x32_bf16 v[18:21], v[134:137], v[208:211], v[18:21]
	v_mfma_f32_16x16x32_bf16 v[10:13], v[142:145], v[208:211], v[10:13]
	v_mfma_f32_16x16x32_bf16 v[94:97], v[150:153], v[184:187], v[94:97]
	v_mfma_f32_16x16x32_bf16 v[86:89], v[176:179], v[184:187], v[86:89]
	v_mfma_f32_16x16x32_bf16 v[66:69], v[150:153], v[192:195], v[66:69]
	v_mfma_f32_16x16x32_bf16 v[54:57], v[176:179], v[192:195], v[54:57]
	v_mfma_f32_16x16x32_bf16 v[22:25], v[150:153], v[200:203], v[22:25]
	v_mfma_f32_16x16x32_bf16 v[14:17], v[176:179], v[200:203], v[14:17]
	v_mfma_f32_16x16x32_bf16 v[6:9], v[150:153], v[208:211], v[6:9]
	v_mfma_f32_16x16x32_bf16 v[2:5], v[176:179], v[208:211], v[2:5]
	s_setprio 0
	s_barrier
	s_add_i32 s84, 0, 0x18000
	s_add_i32 s86, 0, 0x1c000
	v_add_u32_e32 v175, s84, v170
	v_add_u32_e32 v176, s86, v170
	ds_read_b128 v[118:121], v175
	ds_read_b128 v[134:137], v175 offset:1024
	ds_read_b128 v[138:141], v175 offset:2048
	ds_read_b128 v[142:145], v175 offset:3072
	ds_read_b128 v[146:149], v176
	ds_read_b128 v[150:153], v176 offset:1024
	ds_read_b128 v[154:157], v176 offset:2048
	ds_read_b128 v[178:181], v176 offset:3072
	s_add_u32 s0, s26, 0x100000
	s_addc_u32 s1, s27, 0
	s_mov_b32 m0, s48
	ds_read_b128 v[182:185], v174 offset:32768
	ds_read_b128 v[186:189], v174 offset:33792
	ds_read_b128 v[190:193], v174 offset:34816
	ds_read_b128 v[194:197], v174 offset:35840
	ds_read_b128 v[198:201], v174 offset:36864
	ds_read_b128 v[202:205], v174 offset:37888
	ds_read_b128 v[206:209], v174 offset:38912
	ds_read_b128 v[210:213], v174 offset:39936
	s_nop 0
	global_load_lds_dwordx4 v1, s[0:1]
	s_mov_b32 m0, s49
	s_nop 0
	global_load_lds_dwordx4 v165, s[0:1]
	s_waitcnt vmcnt(8)
	s_waitcnt lgkmcnt(0)
	s_setprio 1
	s_waitcnt lgkmcnt(0)
	s_barrier
	v_mfma_f32_16x16x32_bf16 v[34:37], v[118:121], v[182:185], v[34:37]
	v_mfma_f32_16x16x32_bf16 v[30:33], v[138:141], v[182:185], v[30:33]
	v_mfma_f32_16x16x32_bf16 v[46:49], v[118:121], v[190:193], v[46:49]
	v_mfma_f32_16x16x32_bf16 v[62:65], v[138:141], v[190:193], v[62:65]
	v_mfma_f32_16x16x32_bf16 v[78:81], v[118:121], v[198:201], v[78:81]
	v_mfma_f32_16x16x32_bf16 v[90:93], v[138:141], v[198:201], v[90:93]
	v_mfma_f32_16x16x32_bf16 v[130:133], v[118:121], v[206:209], v[130:133]
	v_mfma_f32_16x16x32_bf16 v[114:117], v[138:141], v[206:209], v[114:117]
	v_mfma_f32_16x16x32_bf16 v[26:29], v[146:149], v[182:185], v[26:29]
	v_mfma_f32_16x16x32_bf16 v[50:53], v[154:157], v[182:185], v[50:53]
	v_mfma_f32_16x16x32_bf16 v[58:61], v[146:149], v[190:193], v[58:61]
	v_mfma_f32_16x16x32_bf16 v[82:85], v[154:157], v[190:193], v[82:85]
	v_mfma_f32_16x16x32_bf16 v[110:113], v[146:149], v[198:201], v[110:113]
	v_mfma_f32_16x16x32_bf16 v[106:109], v[154:157], v[198:201], v[106:109]
	v_mfma_f32_16x16x32_bf16 v[122:125], v[146:149], v[206:209], v[122:125]
	v_mfma_f32_16x16x32_bf16 v[126:129], v[154:157], v[206:209], v[126:129]
	v_mfma_f32_16x16x32_bf16 v[34:37], v[134:137], v[186:189], v[34:37]
	v_mfma_f32_16x16x32_bf16 v[30:33], v[142:145], v[186:189], v[30:33]
	v_mfma_f32_16x16x32_bf16 v[46:49], v[134:137], v[194:197], v[46:49]
	v_mfma_f32_16x16x32_bf16 v[62:65], v[142:145], v[194:197], v[62:65]
	v_mfma_f32_16x16x32_bf16 v[78:81], v[134:137], v[202:205], v[78:81]
	v_mfma_f32_16x16x32_bf16 v[90:93], v[142:145], v[202:205], v[90:93]
	v_mfma_f32_16x16x32_bf16 v[130:133], v[134:137], v[210:213], v[130:133]
	v_mfma_f32_16x16x32_bf16 v[114:117], v[142:145], v[210:213], v[114:117]
	v_mfma_f32_16x16x32_bf16 v[26:29], v[150:153], v[186:189], v[26:29]
	v_mfma_f32_16x16x32_bf16 v[50:53], v[178:181], v[186:189], v[50:53]
	v_mfma_f32_16x16x32_bf16 v[58:61], v[150:153], v[194:197], v[58:61]
	v_mfma_f32_16x16x32_bf16 v[82:85], v[178:181], v[194:197], v[82:85]
	v_mfma_f32_16x16x32_bf16 v[110:113], v[150:153], v[202:205], v[110:113]
	v_mfma_f32_16x16x32_bf16 v[106:109], v[178:181], v[202:205], v[106:109]
	v_mfma_f32_16x16x32_bf16 v[122:125], v[150:153], v[210:213], v[122:125]
	v_mfma_f32_16x16x32_bf16 v[126:129], v[178:181], v[210:213], v[126:129]
	s_setprio 0
	s_barrier
;     __device__ __forceinline__ void mid(f32x4 (&acc)[2][2][4][2], const Unit& u, int wr, int wc, int fr, int fq) const {
;     ...
;             for (int m = 0; m < 4; ++m) { const size_t off = (size_t)(row0 + ai * HALF + m * 16) * 4096 + col0;
; #pragma unroll
;                 for (int bj = 0; bj < 2; ++bj) { const u32x4 ga = *(const u32x4*)(SGA + off + bj * HALF), gb = *(const u32x4*)(SGB + off + bj * HALF);
	s_add_u32 s0, s24, 0x80
	s_addc_u32 s1, s25, 0
	s_add_i32 s84, s84, s45
	s_mov_b32 m0, s84
	s_add_i32 s85, s84, 0x2000
	ds_read_b128 v[182:185], v174 offset:49152
	ds_read_b128 v[186:189], v174 offset:50176
	ds_read_b128 v[190:193], v174 offset:51200
	ds_read_b128 v[194:197], v174 offset:52224
	ds_read_b128 v[198:201], v174 offset:53248
	ds_read_b128 v[202:205], v174 offset:54272
	ds_read_b128 v[206:209], v174 offset:55296
	ds_read_b128 v[210:213], v174 offset:56320
	s_nop 0
	global_load_lds_dwordx4 v164, s[0:1]
	s_mov_b32 m0, s85
	s_nop 0
	global_load_lds_dwordx4 v166, s[0:1]
	s_add_u32 s0, s24, 0x100080
	s_addc_u32 s1, s25, 0
	s_add_i32 s86, s86, s45
	s_mov_b32 m0, s86
	s_add_i32 s87, s86, 0x2000
	s_nop 0
	global_load_lds_dwordx4 v164, s[0:1]
	s_mov_b32 m0, s87
	s_nop 0
	global_load_lds_dwordx4 v166, s[0:1]
	s_mov_b32 m0, s57
	s_nop 0
	global_load_lds_dwordx4 v1, s[2:3]
	s_mov_b32 m0, s62
	s_nop 0
	global_load_lds_dwordx4 v165, s[2:3]
	s_waitcnt vmcnt(8)
	s_waitcnt lgkmcnt(0)
	s_setprio 1
	s_waitcnt lgkmcnt(0)
	s_barrier
	v_mfma_f32_16x16x32_bf16 v[102:105], v[118:121], v[182:185], v[102:105]
	v_mfma_f32_16x16x32_bf16 v[98:101], v[138:141], v[182:185], v[98:101]
	v_mfma_f32_16x16x32_bf16 v[74:77], v[118:121], v[190:193], v[74:77]
	v_mfma_f32_16x16x32_bf16 v[70:73], v[138:141], v[190:193], v[70:73]
	v_mfma_f32_16x16x32_bf16 v[42:45], v[118:121], v[198:201], v[42:45]
	v_mfma_f32_16x16x32_bf16 v[38:41], v[138:141], v[198:201], v[38:41]
	v_mfma_f32_16x16x32_bf16 v[18:21], v[118:121], v[206:209], v[18:21]
	v_mfma_f32_16x16x32_bf16 v[10:13], v[138:141], v[206:209], v[10:13]
	v_mfma_f32_16x16x32_bf16 v[94:97], v[146:149], v[182:185], v[94:97]
	v_mfma_f32_16x16x32_bf16 v[86:89], v[154:157], v[182:185], v[86:89]
	v_mfma_f32_16x16x32_bf16 v[66:69], v[146:149], v[190:193], v[66:69]
	v_mfma_f32_16x16x32_bf16 v[54:57], v[154:157], v[190:193], v[54:57]
	v_mfma_f32_16x16x32_bf16 v[22:25], v[146:149], v[198:201], v[22:25]
	v_mfma_f32_16x16x32_bf16 v[14:17], v[154:157], v[198:201], v[14:17]
	v_mfma_f32_16x16x32_bf16 v[6:9], v[146:149], v[206:209], v[6:9]
	v_mfma_f32_16x16x32_bf16 v[2:5], v[154:157], v[206:209], v[2:5]
	v_mfma_f32_16x16x32_bf16 v[102:105], v[134:137], v[186:189], v[102:105]
	v_mfma_f32_16x16x32_bf16 v[98:101], v[142:145], v[186:189], v[98:101]
	v_mfma_f32_16x16x32_bf16 v[74:77], v[134:137], v[194:197], v[74:77]
	v_mfma_f32_16x16x32_bf16 v[70:73], v[142:145], v[194:197], v[70:73]
	v_mfma_f32_16x16x32_bf16 v[42:45], v[134:137], v[202:205], v[42:45]
	v_mfma_f32_16x16x32_bf16 v[38:41], v[142:145], v[202:205], v[38:41]
	v_mfma_f32_16x16x32_bf16 v[18:21], v[134:137], v[210:213], v[18:21]
	v_mfma_f32_16x16x32_bf16 v[10:13], v[142:145], v[210:213], v[10:13]
	v_mfma_f32_16x16x32_bf16 v[94:97], v[150:153], v[186:189], v[94:97]
	v_mfma_f32_16x16x32_bf16 v[86:89], v[178:181], v[186:189], v[86:89]
	v_mfma_f32_16x16x32_bf16 v[66:69], v[150:153], v[194:197], v[66:69]
	v_mfma_f32_16x16x32_bf16 v[54:57], v[178:181], v[194:197], v[54:57]
	v_mfma_f32_16x16x32_bf16 v[22:25], v[150:153], v[202:205], v[22:25]
	v_mfma_f32_16x16x32_bf16 v[14:17], v[178:181], v[202:205], v[14:17]
	v_mfma_f32_16x16x32_bf16 v[6:9], v[150:153], v[210:213], v[6:9]
	v_mfma_f32_16x16x32_bf16 v[2:5], v[178:181], v[210:213], v[2:5]
	s_setprio 0
	s_barrier
	s_add_i32 s33, s33, 2
	s_add_u32 s5, s5, 0x100
	s_addc_u32 s21, s21, 0
	s_cmp_gt_u32 s33, 29
	s_mov_b64 s[0:1], s[16:17]
	s_cbranch_scc0 .LBB0_746
	v_mov_b32_e32 v119, v167
	v_mov_b32_e32 v118, v168
	s_lshl_b32 s89, s20, 8
	s_lshl_b32 s88, s4, 8
	s_or_b32 s0, s89, s56
	v_lshl_add_u32 v118, v118, 3, s0
	s_add_i32 s0, s88, s55
	v_add_u32_e32 v120, s0, v119
	v_ashrrev_i32_e32 v121, 31, v120
	v_ashrrev_i32_e32 v119, 31, v118
	v_lshlrev_b64 v[120:121], 12, v[120:121]
	v_lshl_add_u64 v[118:119], v[120:121], 0, v[118:119]
	v_lshlrev_b64 v[162:163], 1, v[118:119]
	v_lshl_add_u64 v[138:139], s[12:13], 0, v[162:163]
	global_load_dwordx4 v[134:137], v[138:139], off
	v_lshl_add_u64 v[140:141], s[10:11], 0, v[162:163]
	global_load_dwordx4 v[118:121], v[140:141], off
	global_load_dwordx4 v[150:153], v[138:139], off offset:256
	global_load_dwordx4 v[146:149], v[140:141], off offset:256
	s_mov_b64 s[0:1], 0x20000
	v_lshl_add_u64 v[138:139], v[162:163], 0, s[0:1]
	v_lshl_add_u64 v[154:155], s[10:11], 0, v[138:139]
	v_lshl_add_u64 v[156:157], s[12:13], 0, v[138:139]
	global_load_dwordx4 v[138:141], v[154:155], off
	global_load_dwordx4 v[142:145], v[156:157], off
	s_mov_b64 s[0:1], 0x40000
	s_add_i32 s50, s50, 1
	v_readlane_b32 s2, v238, 45
	s_waitcnt vmcnt(0)
; __device__ __forceinline__ float bf_lo(unsigned w) { return __uint_as_float(w << 16); }
; __device__ __forceinline__ float bf_hi(unsigned w) { return __uint_as_float(w & 0xffff0000u); }
;     __device__ __forceinline__ void mid(f32x4 (&acc)[2][2][4][2], const Unit& u, int wr, int wc, int fr, int fq) const {
;     ...
;             for (int m = 0; m < 4; ++m) { const size_t off = (size_t)(row0 + ai * HALF + m * 16) * 4096 + col0;
; #pragma unroll
;                 for (int bj = 0; bj < 2; ++bj) { const u32x4 ga = *(const u32x4*)(SGA + off + bj * HALF), gb = *(const u32x4*)(SGB + off + bj * HALF);
;                     const unsigned wa[4] = {ga.x, ga.y, ga.z, ga.w}, wb[4] = {gb.x, gb.y, gb.z, gb.w};
; #pragma unroll
;                     for (int p = 0; p < 4; ++p) { const float rl = bf_lo(wa[p]) * __builtin_amdgcn_rcpf(fmaxf(bf_lo(wb[p]), 1e-20f)), rh = bf_hi(wa[p]) * __builtin_amdgcn_rcpf(fmaxf(bf_hi(wb[p]), 1e-20f));
;                         acc[ai][bj][m][p >> 1][(p & 1) * 2] *= rl; acc[ai][bj][m][p >> 1][(p & 1) * 2 + 1] *= rh; } }
	v_lshlrev_b32_e32 v178, 16, v118
	v_and_b32_e32 v180, 0xffff0000, v134
	v_lshlrev_b32_e32 v181, 16, v135
	v_and_b32_e32 v182, 0xffff0000, v135
	v_lshlrev_b32_e32 v183, 16, v136
	v_and_b32_e32 v184, 0xffff0000, v136
	v_lshlrev_b32_e32 v185, 16, v137
	v_and_b32_e32 v186, 0xffff0000, v137
	v_lshlrev_b32_e32 v187, 16, v150
	v_and_b32_e32 v150, 0xffff0000, v150
	v_lshlrev_b32_e32 v188, 16, v151
	v_and_b32_e32 v151, 0xffff0000, v151
	v_max_f32_e32 v180, v180, v180
	v_max_f32_e32 v181, v181, v181
	v_max_f32_e32 v182, v182, v182
	v_max_f32_e32 v183, v183, v183
	v_max_f32_e32 v184, v184, v184
	v_max_f32_e32 v185, v185, v185
	v_max_f32_e32 v186, v186, v186
	v_max_f32_e32 v187, v187, v187
	v_max_f32_e32 v150, v150, v150
	v_max_f32_e32 v188, v188, v188
	v_max_f32_e32 v151, v151, v151
	v_max_f32_e32 v180, 0x1e3ce508, v180
	v_max_f32_e32 v181, 0x1e3ce508, v181
	v_max_f32_e32 v182, 0x1e3ce508, v182
	v_max_f32_e32 v183, 0x1e3ce508, v183
	v_max_f32_e32 v184, 0x1e3ce508, v184
	v_max_f32_e32 v185, 0x1e3ce508, v185
	v_max_f32_e32 v186, 0x1e3ce508, v186
	v_max_f32_e32 v187, 0x1e3ce508, v187
	v_max_f32_e32 v189, 0x1e3ce508, v150
	v_max_f32_e32 v188, 0x1e3ce508, v188
	v_max_f32_e32 v190, 0x1e3ce508, v151
	v_rcp_f32_e32 v151, v180
	v_rcp_f32_e32 v180, v181
	v_rcp_f32_e32 v181, v182
	v_rcp_f32_e32 v182, v183
	v_rcp_f32_e32 v183, v184
	v_rcp_f32_e32 v184, v185
	v_rcp_f32_e32 v185, v186
	v_rcp_f32_e32 v186, v187
	v_rcp_f32_e32 v187, v189
	v_rcp_f32_e32 v188, v188
	v_rcp_f32_e32 v189, v190
	v_and_b32_e32 v179, 0xffff0000, v118
	v_lshlrev_b32_e32 v118, 16, v119
	v_and_b32_e32 v119, 0xffff0000, v119
	v_lshlrev_b32_e32 v177, 16, v134
	v_lshlrev_b32_e32 v134, 16, v120
	v_and_b32_e32 v135, 0xffff0000, v120
	v_lshlrev_b32_e32 v120, 16, v121
	v_and_b32_e32 v121, 0xffff0000, v121
	v_lshlrev_b32_e32 v136, 16, v146
	v_and_b32_e32 v137, 0xffff0000, v146
	v_lshlrev_b32_e32 v146, 16, v147
	v_and_b32_e32 v147, 0xffff0000, v147
	v_pk_mul_f32 v[118:119], v[180:181], v[118:119]
	v_pk_mul_f32 v[134:135], v[182:183], v[134:135]
	v_pk_mul_f32 v[120:121], v[184:185], v[120:121]
	v_pk_mul_f32 v[36:37], v[36:37], v[118:119]
	v_pk_mul_f32 v[118:119], v[188:189], v[146:147]
	v_pk_mul_f32 v[30:31], v[30:31], v[134:135]
	v_pk_mul_f32 v[32:33], v[32:33], v[120:121]
	v_pk_mul_f32 v[28:29], v[28:29], v[118:119]
	global_load_dwordx4 v[118:121], v[156:157], off offset:256
	v_lshlrev_b32_e32 v134, 16, v152
	v_max_f32_e32 v134, v134, v134
	v_max_f32_e32 v134, 0x1e3ce508, v134
	v_rcp_f32_e32 v146, v134
	v_and_b32_e32 v134, 0xffff0000, v152
	v_max_f32_e32 v134, v134, v134
	v_pk_mul_f32 v[136:137], v[186:187], v[136:137]
	v_max_f32_e32 v134, 0x1e3ce508, v134
	v_pk_mul_f32 v[26:27], v[26:27], v[136:137]
	v_rcp_f32_e32 v147, v134
	global_load_dwordx4 v[134:137], v[154:155], off offset:256
	v_max_f32_e32 v177, v177, v177
	v_max_f32_e32 v177, 0x1e3ce508, v177
	v_rcp_f32_e32 v150, v177
	s_nop 0
	v_pk_mul_f32 v[150:151], v[150:151], v[178:179]
	s_nop 0
	v_pk_mul_f32 v[34:35], v[34:35], v[150:151]
	v_lshlrev_b32_e32 v150, 16, v148
	v_and_b32_e32 v151, 0xffff0000, v148
	v_lshlrev_b32_e32 v148, 16, v153
	v_max_f32_e32 v148, v148, v148
	v_max_f32_e32 v148, 0x1e3ce508, v148
	v_pk_mul_f32 v[146:147], v[146:147], v[150:151]
	v_rcp_f32_e32 v150, v148
	v_and_b32_e32 v148, 0xffff0000, v153
	v_max_f32_e32 v148, v148, v148
	v_max_f32_e32 v148, 0x1e3ce508, v148
	v_rcp_f32_e32 v151, v148
	v_pk_mul_f32 v[50:51], v[50:51], v[146:147]
	v_lshlrev_b32_e32 v146, 16, v149
	v_and_b32_e32 v147, 0xffff0000, v149
	v_pk_mul_f32 v[146:147], v[150:151], v[146:147]
	v_lshlrev_b32_e32 v148, 16, v142
	v_and_b32_e32 v142, 0xffff0000, v142
	v_pk_mul_f32 v[52:53], v[52:53], v[146:147]
	v_lshlrev_b32_e32 v146, 16, v138
	v_and_b32_e32 v147, 0xffff0000, v138
	v_lshlrev_b32_e32 v138, 16, v143
	v_max_f32_e32 v148, v148, v148
	v_max_f32_e32 v142, v142, v142
	v_max_f32_e32 v138, v138, v138
	v_max_f32_e32 v148, 0x1e3ce508, v148
	v_max_f32_e32 v142, 0x1e3ce508, v142
	v_max_f32_e32 v138, 0x1e3ce508, v138
	v_rcp_f32_e32 v148, v148
	v_rcp_f32_e32 v149, v142
	v_rcp_f32_e32 v142, v138
	v_and_b32_e32 v138, 0xffff0000, v143
	v_max_f32_e32 v138, v138, v138
	v_max_f32_e32 v138, 0x1e3ce508, v138
	v_rcp_f32_e32 v143, v138
	v_lshl_add_u64 v[150:151], v[162:163], 0, s[0:1]
	v_pk_mul_f32 v[146:147], v[148:149], v[146:147]
	v_lshl_add_u64 v[154:155], s[12:13], 0, v[150:151]
	v_pk_mul_f32 v[46:47], v[46:47], v[146:147]
	global_load_dwordx4 v[146:149], v[154:155], off
	v_lshlrev_b32_e32 v138, 16, v139
	v_and_b32_e32 v139, 0xffff0000, v139
	v_pk_mul_f32 v[138:139], v[142:143], v[138:139]
	v_lshlrev_b32_e32 v142, 16, v144
	v_max_f32_e32 v142, v142, v142
	v_max_f32_e32 v142, 0x1e3ce508, v142
	v_rcp_f32_e32 v156, v142
	v_lshl_add_u64 v[142:143], s[10:11], 0, v[150:151]
	global_load_dwordx4 v[150:153], v[142:143], off
	v_and_b32_e32 v144, 0xffff0000, v144
	v_pk_mul_f32 v[48:49], v[48:49], v[138:139]
	v_lshlrev_b32_e32 v138, 16, v140
	v_and_b32_e32 v139, 0xffff0000, v140
	v_lshlrev_b32_e32 v140, 16, v145
	v_max_f32_e32 v144, v144, v144
	v_max_f32_e32 v140, v140, v140
	v_max_f32_e32 v144, 0x1e3ce508, v144
	v_max_f32_e32 v140, 0x1e3ce508, v140
	v_rcp_f32_e32 v157, v144
	v_rcp_f32_e32 v144, v140
	v_and_b32_e32 v140, 0xffff0000, v145
	v_max_f32_e32 v140, v140, v140
	v_max_f32_e32 v140, 0x1e3ce508, v140
	v_rcp_f32_e32 v145, v140
	s_waitcnt vmcnt(3)
	v_lshlrev_b32_e32 v140, 16, v118
	v_and_b32_e32 v118, 0xffff0000, v118
	v_max_f32_e32 v140, v140, v140
	v_max_f32_e32 v118, v118, v118
	v_pk_mul_f32 v[138:139], v[156:157], v[138:139]
	v_max_f32_e32 v140, 0x1e3ce508, v140
	v_max_f32_e32 v118, 0x1e3ce508, v118
	v_pk_mul_f32 v[62:63], v[62:63], v[138:139]
	v_lshlrev_b32_e32 v138, 16, v141
	v_and_b32_e32 v139, 0xffff0000, v141
	v_rcp_f32_e32 v140, v140
	v_rcp_f32_e32 v141, v118
	v_pk_mul_f32 v[138:139], v[144:145], v[138:139]
	global_load_dwordx4 v[142:145], v[142:143], off offset:256
	v_pk_mul_f32 v[64:65], v[64:65], v[138:139]
	s_waitcnt vmcnt(3)
; __device__ __forceinline__ float bf_lo(unsigned w) { return __uint_as_float(w << 16); }
; __device__ __forceinline__ float bf_hi(unsigned w) { return __uint_as_float(w & 0xffff0000u); }
;     __device__ __forceinline__ void mid(f32x4 (&acc)[2][2][4][2], const Unit& u, int wr, int wc, int fr, int fq) const {
;     ...
;                 for (int bj = 0; bj < 2; ++bj) { const u32x4 ga = *(const u32x4*)(SGA + off + bj * HALF), gb = *(const u32x4*)(SGB + off + bj * HALF);
;                     const unsigned wa[4] = {ga.x, ga.y, ga.z, ga.w}, wb[4] = {gb.x, gb.y, gb.z, gb.w};
; #pragma unroll
;                     for (int p = 0; p < 4; ++p) { const float rl = bf_lo(wa[p]) * __builtin_amdgcn_rcpf(fmaxf(bf_lo(wb[p]), 1e-20f)), rh = bf_hi(wa[p]) * __builtin_amdgcn_rcpf(fmaxf(bf_hi(wb[p]), 1e-20f));
;                         acc[ai][bj][m][p >> 1][(p & 1) * 2] *= rl; acc[ai][bj][m][p >> 1][(p & 1) * 2 + 1] *= rh; } }
	v_lshlrev_b32_e32 v138, 16, v134
	v_and_b32_e32 v139, 0xffff0000, v134
	v_pk_mul_f32 v[138:139], v[140:141], v[138:139]
	v_lshlrev_b32_e32 v118, 16, v119
	v_pk_mul_f32 v[58:59], v[58:59], v[138:139]
	global_load_dwordx4 v[138:141], v[154:155], off offset:256
	v_and_b32_e32 v119, 0xffff0000, v119
	v_max_f32_e32 v118, v118, v118
	v_max_f32_e32 v119, v119, v119
	v_max_f32_e32 v118, 0x1e3ce508, v118
	v_max_f32_e32 v119, 0x1e3ce508, v119
	v_rcp_f32_e32 v118, v118
	v_rcp_f32_e32 v119, v119
	v_lshlrev_b32_e32 v134, 16, v135
	v_and_b32_e32 v135, 0xffff0000, v135
	s_mov_b64 s[0:1], 0x60000
	v_pk_mul_f32 v[118:119], v[118:119], v[134:135]
	v_lshlrev_b32_e32 v134, 16, v136
	v_pk_mul_f32 v[60:61], v[60:61], v[118:119]
	v_lshlrev_b32_e32 v118, 16, v120
	v_and_b32_e32 v119, 0xffff0000, v120
	v_max_f32_e32 v118, v118, v118
	v_max_f32_e32 v119, v119, v119
	v_max_f32_e32 v118, 0x1e3ce508, v118
	v_max_f32_e32 v119, 0x1e3ce508, v119
	v_lshlrev_b32_e32 v120, 16, v121
	v_and_b32_e32 v121, 0xffff0000, v121
	v_rcp_f32_e32 v118, v118
	v_rcp_f32_e32 v119, v119
	v_max_f32_e32 v120, v120, v120
	v_max_f32_e32 v121, v121, v121
	v_max_f32_e32 v120, 0x1e3ce508, v120
	v_max_f32_e32 v121, 0x1e3ce508, v121
	v_rcp_f32_e32 v120, v120
	v_rcp_f32_e32 v121, v121
	v_and_b32_e32 v135, 0xffff0000, v136
	v_pk_mul_f32 v[118:119], v[118:119], v[134:135]
	s_nop 0
	v_pk_mul_f32 v[82:83], v[82:83], v[118:119]
	v_lshlrev_b32_e32 v118, 16, v137
	v_and_b32_e32 v119, 0xffff0000, v137
	v_pk_mul_f32 v[118:119], v[120:121], v[118:119]
	s_waitcnt vmcnt(3)
	v_lshlrev_b32_e32 v120, 16, v146
	v_and_b32_e32 v121, 0xffff0000, v146
	v_max_f32_e32 v120, v120, v120
	v_max_f32_e32 v121, v121, v121
	v_max_f32_e32 v120, 0x1e3ce508, v120
	v_max_f32_e32 v121, 0x1e3ce508, v121
	v_rcp_f32_e32 v120, v120
	v_rcp_f32_e32 v121, v121
	v_pk_mul_f32 v[84:85], v[84:85], v[118:119]
	s_waitcnt vmcnt(2)
	v_lshlrev_b32_e32 v118, 16, v150
	v_and_b32_e32 v119, 0xffff0000, v150
	v_pk_mul_f32 v[118:119], v[120:121], v[118:119]
	v_lshlrev_b32_e32 v150, 16, v151
	v_pk_mul_f32 v[78:79], v[78:79], v[118:119]
	v_lshlrev_b32_e32 v118, 16, v147
	v_and_b32_e32 v119, 0xffff0000, v147
	v_lshl_add_u64 v[146:147], v[162:163], 0, s[0:1]
	v_lshl_add_u64 v[120:121], s[12:13], 0, v[146:147]
	v_max_f32_e32 v118, v118, v118
	v_max_f32_e32 v119, v119, v119
	global_load_dwordx4 v[134:137], v[120:121], off
	v_max_f32_e32 v118, 0x1e3ce508, v118
	v_max_f32_e32 v119, 0x1e3ce508, v119
	v_rcp_f32_e32 v118, v118
	v_rcp_f32_e32 v119, v119
	v_and_b32_e32 v151, 0xffff0000, v151
	s_mov_b64 s[0:1], 0x120000
	v_pk_mul_f32 v[150:151], v[118:119], v[150:151]
	v_lshlrev_b32_e32 v118, 16, v148
	v_max_f32_e32 v118, v118, v118
	v_max_f32_e32 v118, 0x1e3ce508, v118
	v_rcp_f32_e32 v178, v118
	v_lshl_add_u64 v[118:119], s[10:11], 0, v[146:147]
	global_load_dwordx4 v[154:157], v[118:119], off
	v_and_b32_e32 v146, 0xffff0000, v148
	v_max_f32_e32 v146, v146, v146
	v_max_f32_e32 v146, 0x1e3ce508, v146
	v_lshlrev_b32_e32 v148, 16, v149
	v_and_b32_e32 v149, 0xffff0000, v149
	v_rcp_f32_e32 v179, v146
	v_max_f32_e32 v148, v148, v148
	v_max_f32_e32 v149, v149, v149
	v_max_f32_e32 v148, 0x1e3ce508, v148
	v_max_f32_e32 v149, 0x1e3ce508, v149
	v_rcp_f32_e32 v148, v148
	v_rcp_f32_e32 v149, v149
	v_lshlrev_b32_e32 v146, 16, v152
	v_and_b32_e32 v147, 0xffff0000, v152
	v_pk_mul_f32 v[146:147], v[178:179], v[146:147]
	v_pk_mul_f32 v[80:81], v[80:81], v[150:151]
	v_pk_mul_f32 v[90:91], v[90:91], v[146:147]
	v_lshlrev_b32_e32 v146, 16, v153
	v_and_b32_e32 v147, 0xffff0000, v153
	v_pk_mul_f32 v[146:147], v[148:149], v[146:147]
	s_waitcnt vmcnt(2)
	v_lshlrev_b32_e32 v148, 16, v138
	v_and_b32_e32 v138, 0xffff0000, v138
	v_max_f32_e32 v148, v148, v148
	v_max_f32_e32 v138, v138, v138
	v_max_f32_e32 v148, 0x1e3ce508, v148
	v_max_f32_e32 v138, 0x1e3ce508, v138
	global_load_dwordx4 v[150:153], v[120:121], off offset:256
	v_rcp_f32_e32 v148, v148
	v_rcp_f32_e32 v149, v138
	v_pk_mul_f32 v[92:93], v[92:93], v[146:147]
	v_lshlrev_b32_e32 v146, 16, v142
	v_and_b32_e32 v147, 0xffff0000, v142
	v_pk_mul_f32 v[146:147], v[148:149], v[146:147]
	v_lshlrev_b32_e32 v138, 16, v139
	v_pk_mul_f32 v[110:111], v[110:111], v[146:147]
	global_load_dwordx4 v[146:149], v[118:119], off offset:256
	v_and_b32_e32 v139, 0xffff0000, v139
	v_max_f32_e32 v138, v138, v138
	v_max_f32_e32 v139, v139, v139
	v_max_f32_e32 v138, 0x1e3ce508, v138
	v_max_f32_e32 v120, 0x1e3ce508, v139
	v_rcp_f32_e32 v138, v138
	v_rcp_f32_e32 v139, v120
	v_lshlrev_b32_e32 v120, 16, v143
	v_and_b32_e32 v121, 0xffff0000, v143
	v_and_b32_e32 v119, 0xffff0000, v140
	v_pk_mul_f32 v[120:121], v[138:139], v[120:121]
	v_lshlrev_b32_e32 v138, 16, v140
	v_max_f32_e32 v138, v138, v138
	v_max_f32_e32 v119, v119, v119
	v_max_f32_e32 v118, 0x1e3ce508, v138
	v_max_f32_e32 v119, 0x1e3ce508, v119
	v_rcp_f32_e32 v118, v118
	v_rcp_f32_e32 v119, v119
	v_pk_mul_f32 v[112:113], v[112:113], v[120:121]
	v_lshlrev_b32_e32 v120, 16, v144
	v_and_b32_e32 v121, 0xffff0000, v144
	v_pk_mul_f32 v[118:119], v[118:119], v[120:121]
	v_lshlrev_b32_e32 v120, 16, v141
	v_and_b32_e32 v121, 0xffff0000, v141
	v_max_f32_e32 v120, v120, v120
	v_max_f32_e32 v121, v121, v121
	v_max_f32_e32 v120, 0x1e3ce508, v120
	v_max_f32_e32 v121, 0x1e3ce508, v121
	v_rcp_f32_e32 v120, v120
	v_rcp_f32_e32 v121, v121
	v_pk_mul_f32 v[118:119], v[106:107], v[118:119]
	v_lshlrev_b32_e32 v106, 16, v145
	v_and_b32_e32 v107, 0xffff0000, v145
	v_pk_mul_f32 v[106:107], v[120:121], v[106:107]
	s_waitcnt vmcnt(3)
; __device__ __forceinline__ float bf_lo(unsigned w) { return __uint_as_float(w << 16); }
; __device__ __forceinline__ float bf_hi(unsigned w) { return __uint_as_float(w & 0xffff0000u); }
;     __device__ __forceinline__ void mid(f32x4 (&acc)[2][2][4][2], const Unit& u, int wr, int wc, int fr, int fq) const {
;     ...
;                 for (int bj = 0; bj < 2; ++bj) { const u32x4 ga = *(const u32x4*)(SGA + off + bj * HALF), gb = *(const u32x4*)(SGB + off + bj * HALF);
;                     const unsigned wa[4] = {ga.x, ga.y, ga.z, ga.w}, wb[4] = {gb.x, gb.y, gb.z, gb.w};
; #pragma unroll
;                     for (int p = 0; p < 4; ++p) { const float rl = bf_lo(wa[p]) * __builtin_amdgcn_rcpf(fmaxf(bf_lo(wb[p]), 1e-20f)), rh = bf_hi(wa[p]) * __builtin_amdgcn_rcpf(fmaxf(bf_hi(wb[p]), 1e-20f));
;                         acc[ai][bj][m][p >> 1][(p & 1) * 2] *= rl; acc[ai][bj][m][p >> 1][(p & 1) * 2 + 1] *= rh; } }
	v_lshlrev_b32_e32 v120, 16, v134
	v_max_f32_e32 v120, v120, v120
	v_max_f32_e32 v120, 0x1e3ce508, v120
	v_rcp_f32_e32 v138, v120
	v_and_b32_e32 v120, 0xffff0000, v134
	v_max_f32_e32 v120, v120, v120
	v_max_f32_e32 v120, 0x1e3ce508, v120
	v_rcp_f32_e32 v139, v120
	v_pk_mul_f32 v[120:121], v[108:109], v[106:107]
	v_lshlrev_b32_e32 v108, 16, v135
	v_and_b32_e32 v109, 0xffff0000, v135
	v_max_f32_e32 v108, v108, v108
	v_max_f32_e32 v109, v109, v109
	v_max_f32_e32 v108, 0x1e3ce508, v108
	v_max_f32_e32 v109, 0x1e3ce508, v109
	v_rcp_f32_e32 v108, v108
	v_rcp_f32_e32 v109, v109
	s_waitcnt vmcnt(2)
	v_lshlrev_b32_e32 v106, 16, v154
	v_and_b32_e32 v107, 0xffff0000, v154
	v_pk_mul_f32 v[106:107], v[138:139], v[106:107]
	v_lshl_add_u64 v[140:141], v[162:163], 0, s[0:1]
	v_pk_mul_f32 v[106:107], v[130:131], v[106:107]
	v_lshlrev_b32_e32 v130, 16, v155
	v_and_b32_e32 v131, 0xffff0000, v155
	v_pk_mul_f32 v[108:109], v[108:109], v[130:131]
	v_lshlrev_b32_e32 v130, 16, v136
	v_and_b32_e32 v131, 0xffff0000, v136
	v_max_f32_e32 v130, v130, v130
	v_max_f32_e32 v131, v131, v131
	v_max_f32_e32 v130, 0x1e3ce508, v130
	v_max_f32_e32 v131, 0x1e3ce508, v131
	v_rcp_f32_e32 v130, v130
	v_rcp_f32_e32 v131, v131
	v_pk_mul_f32 v[108:109], v[132:133], v[108:109]
	v_lshlrev_b32_e32 v132, 16, v156
	v_and_b32_e32 v133, 0xffff0000, v156
	v_pk_mul_f32 v[130:131], v[130:131], v[132:133]
	v_lshlrev_b32_e32 v132, 16, v137
	v_and_b32_e32 v133, 0xffff0000, v137
	v_max_f32_e32 v132, v132, v132
	v_max_f32_e32 v133, v133, v133
	v_max_f32_e32 v132, 0x1e3ce508, v132
	v_max_f32_e32 v133, 0x1e3ce508, v133
	v_rcp_f32_e32 v132, v132
	v_rcp_f32_e32 v133, v133
	v_pk_mul_f32 v[114:115], v[114:115], v[130:131]
	v_lshlrev_b32_e32 v130, 16, v157
	v_and_b32_e32 v131, 0xffff0000, v157
	v_pk_mul_f32 v[130:131], v[132:133], v[130:131]
	s_waitcnt vmcnt(1)
	v_lshlrev_b32_e32 v132, 16, v150
	v_and_b32_e32 v133, 0xffff0000, v150
	v_max_f32_e32 v132, v132, v132
	v_max_f32_e32 v133, v133, v133
	v_max_f32_e32 v132, 0x1e3ce508, v132
	v_max_f32_e32 v133, 0x1e3ce508, v133
	v_rcp_f32_e32 v132, v132
	v_rcp_f32_e32 v133, v133
	v_pk_mul_f32 v[116:117], v[116:117], v[130:131]
	s_waitcnt vmcnt(0)
	v_lshlrev_b32_e32 v130, 16, v146
	v_and_b32_e32 v131, 0xffff0000, v146
	v_pk_mul_f32 v[130:131], v[132:133], v[130:131]
	v_lshlrev_b32_e32 v132, 16, v151
	v_and_b32_e32 v133, 0xffff0000, v151
	v_max_f32_e32 v132, v132, v132
	v_max_f32_e32 v133, v133, v133
	v_max_f32_e32 v132, 0x1e3ce508, v132
	v_max_f32_e32 v133, 0x1e3ce508, v133
	v_rcp_f32_e32 v132, v132
	v_rcp_f32_e32 v133, v133
	v_pk_mul_f32 v[122:123], v[122:123], v[130:131]
	v_lshlrev_b32_e32 v130, 16, v147
	v_and_b32_e32 v131, 0xffff0000, v147
	v_pk_mul_f32 v[130:131], v[132:133], v[130:131]
	v_lshlrev_b32_e32 v132, 16, v152
	v_and_b32_e32 v133, 0xffff0000, v152
	v_max_f32_e32 v132, v132, v132
	v_max_f32_e32 v133, v133, v133
	v_max_f32_e32 v132, 0x1e3ce508, v132
	v_max_f32_e32 v133, 0x1e3ce508, v133
	v_rcp_f32_e32 v132, v132
	v_rcp_f32_e32 v133, v133
	v_pk_mul_f32 v[124:125], v[124:125], v[130:131]
	v_lshlrev_b32_e32 v130, 16, v148
	v_and_b32_e32 v131, 0xffff0000, v148
	v_pk_mul_f32 v[130:131], v[132:133], v[130:131]
	v_lshlrev_b32_e32 v132, 16, v153
	v_and_b32_e32 v133, 0xffff0000, v153
	v_max_f32_e32 v132, v132, v132
	v_max_f32_e32 v133, v133, v133
	v_max_f32_e32 v132, 0x1e3ce508, v132
	v_max_f32_e32 v133, 0x1e3ce508, v133
	v_rcp_f32_e32 v132, v132
	v_rcp_f32_e32 v133, v133
	v_pk_mul_f32 v[126:127], v[126:127], v[130:131]
	v_lshlrev_b32_e32 v130, 16, v149
	v_and_b32_e32 v131, 0xffff0000, v149
	v_pk_mul_f32 v[130:131], v[132:133], v[130:131]
	v_lshl_add_u64 v[154:155], s[12:13], 0, v[140:141]
	v_pk_mul_f32 v[128:129], v[128:129], v[130:131]
	v_lshl_add_u64 v[130:131], v[162:163], 0, s[8:9]
	v_lshl_add_u64 v[132:133], s[12:13], 0, v[130:131]
	global_load_dwordx4 v[150:153], v[132:133], off
	v_lshl_add_u64 v[130:131], s[10:11], 0, v[130:131]
	global_load_dwordx4 v[146:149], v[130:131], off
	global_load_dwordx4 v[142:145], v[132:133], off offset:256
	global_load_dwordx4 v[134:137], v[130:131], off offset:256
	s_mov_b64 s[0:1], 0x140000
	s_waitcnt vmcnt(3)
	v_lshlrev_b32_e32 v130, 16, v150
	v_and_b32_e32 v131, 0xffff0000, v150
	v_max_f32_e32 v130, v130, v130
	v_max_f32_e32 v131, v131, v131
	v_max_f32_e32 v130, 0x1e3ce508, v130
	v_max_f32_e32 v131, 0x1e3ce508, v131
	v_rcp_f32_e32 v130, v130
	v_rcp_f32_e32 v131, v131
	s_waitcnt vmcnt(2)
	v_lshlrev_b32_e32 v132, 16, v146
	v_and_b32_e32 v133, 0xffff0000, v146
	v_lshlrev_b32_e32 v146, 16, v147
	v_pk_mul_f32 v[130:131], v[130:131], v[132:133]
	v_and_b32_e32 v147, 0xffff0000, v147
	v_pk_mul_f32 v[102:103], v[102:103], v[130:131]
	v_lshlrev_b32_e32 v130, 16, v151
	v_max_f32_e32 v130, v130, v130
	v_max_f32_e32 v130, 0x1e3ce508, v130
	v_rcp_f32_e32 v138, v130
	v_and_b32_e32 v130, 0xffff0000, v151
	v_max_f32_e32 v130, v130, v130
	v_max_f32_e32 v130, 0x1e3ce508, v130
	v_rcp_f32_e32 v139, v130
	global_load_dwordx4 v[130:133], v[154:155], off
	v_lshl_add_u64 v[150:151], s[10:11], 0, v[140:141]
	v_pk_mul_f32 v[146:147], v[138:139], v[146:147]
	v_lshlrev_b32_e32 v138, 16, v152
	v_max_f32_e32 v138, v138, v138
	v_max_f32_e32 v138, 0x1e3ce508, v138
	v_rcp_f32_e32 v156, v138
	global_load_dwordx4 v[138:141], v[150:151], off
	v_and_b32_e32 v152, 0xffff0000, v152
	v_pk_mul_f32 v[104:105], v[104:105], v[146:147]
	v_lshlrev_b32_e32 v146, 16, v148
	v_and_b32_e32 v147, 0xffff0000, v148
	v_lshlrev_b32_e32 v148, 16, v153
	v_max_f32_e32 v152, v152, v152
	v_max_f32_e32 v148, v148, v148
	v_max_f32_e32 v152, 0x1e3ce508, v152
	v_max_f32_e32 v148, 0x1e3ce508, v148
	v_rcp_f32_e32 v157, v152
	v_rcp_f32_e32 v152, v148
	v_and_b32_e32 v148, 0xffff0000, v153
	v_max_f32_e32 v148, v148, v148
	v_max_f32_e32 v148, 0x1e3ce508, v148
	v_rcp_f32_e32 v153, v148
	s_waitcnt vmcnt(3)
; __device__ __forceinline__ float bf_lo(unsigned w) { return __uint_as_float(w << 16); }
; __device__ __forceinline__ float bf_hi(unsigned w) { return __uint_as_float(w & 0xffff0000u); }
;     __device__ __forceinline__ void mid(f32x4 (&acc)[2][2][4][2], const Unit& u, int wr, int wc, int fr, int fq) const {
;     ...
;                 for (int bj = 0; bj < 2; ++bj) { const u32x4 ga = *(const u32x4*)(SGA + off + bj * HALF), gb = *(const u32x4*)(SGB + off + bj * HALF);
;                     const unsigned wa[4] = {ga.x, ga.y, ga.z, ga.w}, wb[4] = {gb.x, gb.y, gb.z, gb.w};
; #pragma unroll
;                     for (int p = 0; p < 4; ++p) { const float rl = bf_lo(wa[p]) * __builtin_amdgcn_rcpf(fmaxf(bf_lo(wb[p]), 1e-20f)), rh = bf_hi(wa[p]) * __builtin_amdgcn_rcpf(fmaxf(bf_hi(wb[p]), 1e-20f));
;                         acc[ai][bj][m][p >> 1][(p & 1) * 2] *= rl; acc[ai][bj][m][p >> 1][(p & 1) * 2 + 1] *= rh; } }
	v_lshlrev_b32_e32 v148, 16, v142
	v_and_b32_e32 v142, 0xffff0000, v142
	v_max_f32_e32 v148, v148, v148
	v_max_f32_e32 v142, v142, v142
	v_pk_mul_f32 v[146:147], v[156:157], v[146:147]
	v_max_f32_e32 v148, 0x1e3ce508, v148
	v_max_f32_e32 v142, 0x1e3ce508, v142
	v_pk_mul_f32 v[98:99], v[98:99], v[146:147]
	v_lshlrev_b32_e32 v146, 16, v149
	v_and_b32_e32 v147, 0xffff0000, v149
	v_rcp_f32_e32 v148, v148
	v_rcp_f32_e32 v149, v142
	v_pk_mul_f32 v[146:147], v[152:153], v[146:147]
	global_load_dwordx4 v[150:153], v[150:151], off offset:256
	v_pk_mul_f32 v[100:101], v[100:101], v[146:147]
	s_waitcnt vmcnt(3)
	v_lshlrev_b32_e32 v146, 16, v134
	v_and_b32_e32 v147, 0xffff0000, v134
	v_pk_mul_f32 v[146:147], v[148:149], v[146:147]
	v_lshlrev_b32_e32 v134, 16, v143
	v_pk_mul_f32 v[94:95], v[94:95], v[146:147]
	global_load_dwordx4 v[146:149], v[154:155], off offset:256
	v_max_f32_e32 v134, v134, v134
	v_max_f32_e32 v134, 0x1e3ce508, v134
	v_rcp_f32_e32 v142, v134
	v_and_b32_e32 v134, 0xffff0000, v143
	v_max_f32_e32 v134, v134, v134
	v_max_f32_e32 v134, 0x1e3ce508, v134
	v_rcp_f32_e32 v143, v134
	v_lshlrev_b32_e32 v134, 16, v135
	v_and_b32_e32 v135, 0xffff0000, v135
	v_pk_mul_f32 v[134:135], v[142:143], v[134:135]
	s_nop 0
	v_pk_mul_f32 v[96:97], v[96:97], v[134:135]
	v_lshlrev_b32_e32 v134, 16, v144
	v_and_b32_e32 v135, 0xffff0000, v144
	v_max_f32_e32 v134, v134, v134
	v_max_f32_e32 v135, v135, v135
	v_max_f32_e32 v134, 0x1e3ce508, v134
	v_max_f32_e32 v135, 0x1e3ce508, v135
	v_rcp_f32_e32 v134, v134
	v_rcp_f32_e32 v135, v135
	v_lshlrev_b32_e32 v142, 16, v136
	v_and_b32_e32 v143, 0xffff0000, v136
	v_lshlrev_b32_e32 v136, 16, v145
	v_max_f32_e32 v136, v136, v136
	v_max_f32_e32 v136, 0x1e3ce508, v136
	v_pk_mul_f32 v[134:135], v[134:135], v[142:143]
	v_rcp_f32_e32 v142, v136
	v_and_b32_e32 v136, 0xffff0000, v145
	v_max_f32_e32 v136, v136, v136
	v_max_f32_e32 v136, 0x1e3ce508, v136
	v_rcp_f32_e32 v143, v136
	v_pk_mul_f32 v[86:87], v[86:87], v[134:135]
	v_lshlrev_b32_e32 v134, 16, v137
	v_and_b32_e32 v135, 0xffff0000, v137
	v_pk_mul_f32 v[134:135], v[142:143], v[134:135]
	s_waitcnt vmcnt(3)
	v_lshlrev_b32_e32 v136, 16, v130
	v_and_b32_e32 v130, 0xffff0000, v130
	v_max_f32_e32 v130, v130, v130
	v_max_f32_e32 v130, 0x1e3ce508, v130
	v_rcp_f32_e32 v137, v130
	v_lshlrev_b32_e32 v130, 16, v131
	v_max_f32_e32 v136, v136, v136
	v_max_f32_e32 v130, v130, v130
	v_max_f32_e32 v136, 0x1e3ce508, v136
	v_max_f32_e32 v130, 0x1e3ce508, v130
	v_rcp_f32_e32 v136, v136
	v_rcp_f32_e32 v142, v130
	v_and_b32_e32 v130, 0xffff0000, v131
	v_max_f32_e32 v130, v130, v130
	v_max_f32_e32 v130, 0x1e3ce508, v130
	v_pk_mul_f32 v[88:89], v[88:89], v[134:135]
	s_waitcnt vmcnt(2)
	v_lshlrev_b32_e32 v134, 16, v138
	v_and_b32_e32 v135, 0xffff0000, v138
	v_rcp_f32_e32 v143, v130
	v_lshl_add_u64 v[144:145], v[162:163], 0, s[0:1]
	v_pk_mul_f32 v[134:135], v[136:137], v[134:135]
	v_lshl_add_u64 v[130:131], s[12:13], 0, v[144:145]
	v_pk_mul_f32 v[74:75], v[74:75], v[134:135]
	global_load_dwordx4 v[134:137], v[130:131], off
	v_lshlrev_b32_e32 v138, 16, v139
	v_and_b32_e32 v139, 0xffff0000, v139
	v_pk_mul_f32 v[154:155], v[142:143], v[138:139]
	v_lshlrev_b32_e32 v138, 16, v132
	v_max_f32_e32 v138, v138, v138
	v_and_b32_e32 v132, 0xffff0000, v132
	v_max_f32_e32 v138, 0x1e3ce508, v138
	v_max_f32_e32 v132, v132, v132
	v_rcp_f32_e32 v156, v138
	v_lshl_add_u64 v[138:139], s[10:11], 0, v[144:145]
	v_max_f32_e32 v132, 0x1e3ce508, v132
	global_load_dwordx4 v[142:145], v[138:139], off
	v_rcp_f32_e32 v157, v132
	v_lshlrev_b32_e32 v132, 16, v133
	v_and_b32_e32 v133, 0xffff0000, v133
	v_max_f32_e32 v132, v132, v132
	v_max_f32_e32 v133, v133, v133
	v_max_f32_e32 v132, 0x1e3ce508, v132
	v_max_f32_e32 v133, 0x1e3ce508, v133
	v_rcp_f32_e32 v132, v132
	v_rcp_f32_e32 v133, v133
	v_pk_mul_f32 v[76:77], v[76:77], v[154:155]
	v_lshlrev_b32_e32 v154, 16, v140
	v_and_b32_e32 v155, 0xffff0000, v140
	v_lshlrev_b32_e32 v140, 16, v141
	v_and_b32_e32 v141, 0xffff0000, v141
	v_pk_mul_f32 v[132:133], v[132:133], v[140:141]
	s_waitcnt vmcnt(2)
	v_lshlrev_b32_e32 v140, 16, v146
	v_and_b32_e32 v141, 0xffff0000, v146
	v_max_f32_e32 v140, v140, v140
	v_max_f32_e32 v141, v141, v141
	v_max_f32_e32 v140, 0x1e3ce508, v140
	v_max_f32_e32 v141, 0x1e3ce508, v141
	v_rcp_f32_e32 v140, v140
	v_rcp_f32_e32 v141, v141
	v_pk_mul_f32 v[72:73], v[72:73], v[132:133]
	v_lshlrev_b32_e32 v132, 16, v150
	v_and_b32_e32 v133, 0xffff0000, v150
	v_pk_mul_f32 v[132:133], v[140:141], v[132:133]
	v_lshlrev_b32_e32 v140, 16, v147
	v_and_b32_e32 v141, 0xffff0000, v147
	v_max_f32_e32 v140, v140, v140
	v_max_f32_e32 v141, v141, v141
	v_max_f32_e32 v140, 0x1e3ce508, v140
	v_max_f32_e32 v141, 0x1e3ce508, v141
	v_rcp_f32_e32 v140, v140
	v_rcp_f32_e32 v141, v141
	v_pk_mul_f32 v[66:67], v[66:67], v[132:133]
	v_lshlrev_b32_e32 v132, 16, v151
	v_and_b32_e32 v133, 0xffff0000, v151
	v_pk_mul_f32 v[132:133], v[140:141], v[132:133]
	v_lshlrev_b32_e32 v140, 16, v148
	v_pk_mul_f32 v[68:69], v[68:69], v[132:133]
	global_load_dwordx4 v[130:133], v[130:131], off offset:256
	v_max_f32_e32 v140, v140, v140
	v_max_f32_e32 v140, 0x1e3ce508, v140
	v_rcp_f32_e32 v146, v140
	v_and_b32_e32 v140, 0xffff0000, v148
	v_max_f32_e32 v140, v140, v140
	v_max_f32_e32 v140, 0x1e3ce508, v140
	v_rcp_f32_e32 v147, v140
	global_load_dwordx4 v[138:141], v[138:139], off offset:256
	v_lshlrev_b32_e32 v148, 16, v149
	v_and_b32_e32 v149, 0xffff0000, v149
	v_max_f32_e32 v148, v148, v148
	v_max_f32_e32 v149, v149, v149
	v_max_f32_e32 v148, 0x1e3ce508, v148
	v_max_f32_e32 v149, 0x1e3ce508, v149
	v_rcp_f32_e32 v148, v148
	v_rcp_f32_e32 v149, v149
	v_lshlrev_b32_e32 v150, 16, v152
	v_and_b32_e32 v151, 0xffff0000, v152
	v_pk_mul_f32 v[146:147], v[146:147], v[150:151]
	s_mov_b64 s[0:1], 0x160000
	v_pk_mul_f32 v[54:55], v[54:55], v[146:147]
	v_lshlrev_b32_e32 v146, 16, v153
	v_and_b32_e32 v147, 0xffff0000, v153
	v_pk_mul_f32 v[146:147], v[148:149], v[146:147]
	v_pk_mul_f32 v[154:155], v[156:157], v[154:155]
	s_waitcnt vmcnt(3)
; __device__ __forceinline__ float bf_lo(unsigned w) { return __uint_as_float(w << 16); }
; __device__ __forceinline__ float bf_hi(unsigned w) { return __uint_as_float(w & 0xffff0000u); }
;     __host__ __device__ bool next(int i, Unit& u) const {
;         const long L = (long)i * G + c; if (L >= nwg) return false;
;     __device__ __forceinline__ void mid(f32x4 (&acc)[2][2][4][2], const Unit& u, int wr, int wc, int fr, int fq) const {
;     ...
;                 for (int bj = 0; bj < 2; ++bj) { const u32x4 ga = *(const u32x4*)(SGA + off + bj * HALF), gb = *(const u32x4*)(SGB + off + bj * HALF);
;                     const unsigned wa[4] = {ga.x, ga.y, ga.z, ga.w}, wb[4] = {gb.x, gb.y, gb.z, gb.w};
; #pragma unroll
;                     for (int p = 0; p < 4; ++p) { const float rl = bf_lo(wa[p]) * __builtin_amdgcn_rcpf(fmaxf(bf_lo(wb[p]), 1e-20f)), rh = bf_hi(wa[p]) * __builtin_amdgcn_rcpf(fmaxf(bf_hi(wb[p]), 1e-20f));
;                         acc[ai][bj][m][p >> 1][(p & 1) * 2] *= rl; acc[ai][bj][m][p >> 1][(p & 1) * 2 + 1] *= rh; } }
	v_lshlrev_b32_e32 v148, 16, v134
	v_and_b32_e32 v134, 0xffff0000, v134
	v_max_f32_e32 v148, v148, v148
	v_max_f32_e32 v134, v134, v134
	v_max_f32_e32 v148, 0x1e3ce508, v148
	v_max_f32_e32 v134, 0x1e3ce508, v134
	v_rcp_f32_e32 v148, v148
	v_rcp_f32_e32 v149, v134
	v_pk_mul_f32 v[56:57], v[56:57], v[146:147]
	v_lshl_add_u64 v[150:151], v[162:163], 0, s[0:1]
	v_pk_mul_f32 v[70:71], v[70:71], v[154:155]
	v_lshlrev_b32_e32 v134, 16, v135
	s_waitcnt vmcnt(2)
	v_lshlrev_b32_e32 v146, 16, v142
	v_and_b32_e32 v147, 0xffff0000, v142
	v_pk_mul_f32 v[146:147], v[148:149], v[146:147]
	v_and_b32_e32 v135, 0xffff0000, v135
	v_lshl_add_u64 v[154:155], s[12:13], 0, v[150:151]
	v_pk_mul_f32 v[42:43], v[42:43], v[146:147]
	v_max_f32_e32 v134, v134, v134
	v_max_f32_e32 v135, v135, v135
	global_load_dwordx4 v[146:149], v[154:155], off
	v_max_f32_e32 v134, 0x1e3ce508, v134
	v_max_f32_e32 v135, 0x1e3ce508, v135
	v_rcp_f32_e32 v134, v134
	v_rcp_f32_e32 v135, v135
	v_lshlrev_b32_e32 v142, 16, v143
	v_and_b32_e32 v143, 0xffff0000, v143
	s_mul_i32 s0, s50, s63
	v_pk_mul_f32 v[142:143], v[134:135], v[142:143]
	v_lshlrev_b32_e32 v134, 16, v136
	v_max_f32_e32 v134, v134, v134
	v_max_f32_e32 v134, 0x1e3ce508, v134
	v_rcp_f32_e32 v156, v134
	v_lshl_add_u64 v[134:135], s[10:11], 0, v[150:151]
	global_load_dwordx4 v[150:153], v[134:135], off
	v_and_b32_e32 v136, 0xffff0000, v136
	v_max_f32_e32 v136, v136, v136
	v_max_f32_e32 v136, 0x1e3ce508, v136
	v_rcp_f32_e32 v157, v136
	v_lshlrev_b32_e32 v136, 16, v137
	v_and_b32_e32 v137, 0xffff0000, v137
	v_max_f32_e32 v136, v136, v136
	v_max_f32_e32 v137, v137, v137
	v_max_f32_e32 v136, 0x1e3ce508, v136
	v_max_f32_e32 v137, 0x1e3ce508, v137
	v_rcp_f32_e32 v136, v136
	v_rcp_f32_e32 v137, v137
	v_pk_mul_f32 v[44:45], v[44:45], v[142:143]
	v_lshlrev_b32_e32 v142, 16, v144
	v_and_b32_e32 v143, 0xffff0000, v144
	v_pk_mul_f32 v[142:143], v[156:157], v[142:143]
	s_mul_hi_u32 s1, s50, s2
	v_pk_mul_f32 v[38:39], v[38:39], v[142:143]
	v_lshlrev_b32_e32 v142, 16, v145
	v_and_b32_e32 v143, 0xffff0000, v145
	v_pk_mul_f32 v[136:137], v[136:137], v[142:143]
	s_waitcnt vmcnt(3)
	v_lshlrev_b32_e32 v142, 16, v130
	v_and_b32_e32 v130, 0xffff0000, v130
	v_max_f32_e32 v142, v142, v142
	v_max_f32_e32 v130, v130, v130
	v_max_f32_e32 v142, 0x1e3ce508, v142
	v_max_f32_e32 v130, 0x1e3ce508, v130
	v_rcp_f32_e32 v142, v142
	v_rcp_f32_e32 v143, v130
	v_lshlrev_b32_e32 v130, 16, v131
	v_and_b32_e32 v131, 0xffff0000, v131
	v_pk_mul_f32 v[40:41], v[40:41], v[136:137]
	s_waitcnt vmcnt(2)
	v_lshlrev_b32_e32 v136, 16, v138
	v_and_b32_e32 v137, 0xffff0000, v138
	v_max_f32_e32 v130, v130, v130
	v_max_f32_e32 v131, v131, v131
	v_pk_mul_f32 v[136:137], v[142:143], v[136:137]
	v_max_f32_e32 v130, 0x1e3ce508, v130
	global_load_dwordx4 v[142:145], v[154:155], off offset:256
	v_max_f32_e32 v131, 0x1e3ce508, v131
	v_rcp_f32_e32 v130, v130
	v_rcp_f32_e32 v131, v131
	v_pk_mul_f32 v[22:23], v[22:23], v[136:137]
	v_lshlrev_b32_e32 v136, 16, v139
	v_and_b32_e32 v137, 0xffff0000, v139
	v_pk_mul_f32 v[130:131], v[130:131], v[136:137]
	v_lshlrev_b32_e32 v136, 16, v132
	v_max_f32_e32 v138, v136, v136
	global_load_dwordx4 v[134:137], v[134:135], off offset:256
	v_and_b32_e32 v132, 0xffff0000, v132
	v_max_f32_e32 v132, v132, v132
	v_max_f32_e32 v132, 0x1e3ce508, v132
	v_max_f32_e32 v138, 0x1e3ce508, v138
	v_rcp_f32_e32 v139, v132
	v_lshlrev_b32_e32 v132, 16, v133
	v_and_b32_e32 v133, 0xffff0000, v133
	v_rcp_f32_e32 v138, v138
	v_max_f32_e32 v132, v132, v132
	v_max_f32_e32 v133, v133, v133
	v_max_f32_e32 v132, 0x1e3ce508, v132
	v_max_f32_e32 v133, 0x1e3ce508, v133
	v_rcp_f32_e32 v132, v132
	v_rcp_f32_e32 v133, v133
	v_pk_mul_f32 v[24:25], v[24:25], v[130:131]
	v_lshlrev_b32_e32 v130, 16, v140
	v_and_b32_e32 v131, 0xffff0000, v140
	v_pk_mul_f32 v[130:131], v[138:139], v[130:131]
	s_add_i32 s1, s1, s0
	v_pk_mul_f32 v[130:131], v[14:15], v[130:131]
	v_lshlrev_b32_e32 v14, 16, v141
	v_and_b32_e32 v15, 0xffff0000, v141
	v_pk_mul_f32 v[14:15], v[132:133], v[14:15]
	s_waitcnt vmcnt(3)
; __device__ __forceinline__ float bf_lo(unsigned w) { return __uint_as_float(w << 16); }
; __device__ __forceinline__ float bf_hi(unsigned w) { return __uint_as_float(w & 0xffff0000u); }
;     __host__ __device__ bool next(int i, Unit& u) const {
;         const long L = (long)i * G + c; if (L >= nwg) return false;
;         int wgid = (int)L; { const int q = nwg / NXCD, r = nwg % NXCD, xcd = wgid % NXCD, off = wgid / NXCD; wgid = (xcd < r ? xcd * (q + 1) : r * (q + 1) + (xcd - r) * q) + off; }
;     __device__ __forceinline__ void mid(f32x4 (&acc)[2][2][4][2], const Unit& u, int wr, int wc, int fr, int fq) const {
;     ...
;                 for (int bj = 0; bj < 2; ++bj) { const u32x4 ga = *(const u32x4*)(SGA + off + bj * HALF), gb = *(const u32x4*)(SGB + off + bj * HALF);
;                     const unsigned wa[4] = {ga.x, ga.y, ga.z, ga.w}, wb[4] = {gb.x, gb.y, gb.z, gb.w};
; #pragma unroll
;                     for (int p = 0; p < 4; ++p) { const float rl = bf_lo(wa[p]) * __builtin_amdgcn_rcpf(fmaxf(bf_lo(wb[p]), 1e-20f)), rh = bf_hi(wa[p]) * __builtin_amdgcn_rcpf(fmaxf(bf_hi(wb[p]), 1e-20f));
;                         acc[ai][bj][m][p >> 1][(p & 1) * 2] *= rl; acc[ai][bj][m][p >> 1][(p & 1) * 2 + 1] *= rh; } }
	v_lshlrev_b32_e32 v132, 16, v146
	v_max_f32_e32 v132, v132, v132
	v_max_f32_e32 v132, 0x1e3ce508, v132
	v_rcp_f32_e32 v138, v132
	v_and_b32_e32 v132, 0xffff0000, v146
	v_max_f32_e32 v132, v132, v132
	v_max_f32_e32 v132, 0x1e3ce508, v132
	v_rcp_f32_e32 v139, v132
	v_pk_mul_f32 v[132:133], v[16:17], v[14:15]
	v_lshlrev_b32_e32 v16, 16, v147
	v_and_b32_e32 v17, 0xffff0000, v147
	v_max_f32_e32 v16, v16, v16
	v_max_f32_e32 v17, v17, v17
	v_max_f32_e32 v16, 0x1e3ce508, v16
	v_max_f32_e32 v17, 0x1e3ce508, v17
	v_rcp_f32_e32 v16, v16
	v_rcp_f32_e32 v17, v17
	s_waitcnt vmcnt(2)
	v_lshlrev_b32_e32 v14, 16, v150
	v_and_b32_e32 v15, 0xffff0000, v150
	v_pk_mul_f32 v[14:15], v[138:139], v[14:15]
	s_mul_i32 s0, s50, s2
	v_pk_mul_f32 v[14:15], v[18:19], v[14:15]
	v_lshlrev_b32_e32 v18, 16, v151
	v_and_b32_e32 v19, 0xffff0000, v151
	v_pk_mul_f32 v[16:17], v[16:17], v[18:19]
	v_lshlrev_b32_e32 v18, 16, v148
	v_and_b32_e32 v19, 0xffff0000, v148
	v_max_f32_e32 v18, v18, v18
	v_max_f32_e32 v19, v19, v19
	v_max_f32_e32 v18, 0x1e3ce508, v18
	v_max_f32_e32 v19, 0x1e3ce508, v19
	v_rcp_f32_e32 v18, v18
	v_rcp_f32_e32 v19, v19
	v_pk_mul_f32 v[16:17], v[20:21], v[16:17]
	v_lshlrev_b32_e32 v20, 16, v152
	v_and_b32_e32 v21, 0xffff0000, v152
	v_pk_mul_f32 v[18:19], v[18:19], v[20:21]
	v_lshlrev_b32_e32 v20, 16, v149
	v_and_b32_e32 v21, 0xffff0000, v149
	v_max_f32_e32 v20, v20, v20
	v_max_f32_e32 v21, v21, v21
	v_max_f32_e32 v20, 0x1e3ce508, v20
	v_max_f32_e32 v21, 0x1e3ce508, v21
	v_rcp_f32_e32 v20, v20
	v_rcp_f32_e32 v21, v21
	v_pk_mul_f32 v[10:11], v[10:11], v[18:19]
	v_lshlrev_b32_e32 v18, 16, v153
	v_and_b32_e32 v19, 0xffff0000, v153
	v_pk_mul_f32 v[18:19], v[20:21], v[18:19]
	s_waitcnt vmcnt(1)
	v_lshlrev_b32_e32 v20, 16, v142
	v_and_b32_e32 v21, 0xffff0000, v142
	v_max_f32_e32 v20, v20, v20
	v_max_f32_e32 v21, v21, v21
	v_max_f32_e32 v20, 0x1e3ce508, v20
	v_max_f32_e32 v21, 0x1e3ce508, v21
	v_rcp_f32_e32 v20, v20
	v_rcp_f32_e32 v21, v21
	v_pk_mul_f32 v[12:13], v[12:13], v[18:19]
	s_waitcnt vmcnt(0)
	v_lshlrev_b32_e32 v18, 16, v134
	v_and_b32_e32 v19, 0xffff0000, v134
	v_pk_mul_f32 v[18:19], v[20:21], v[18:19]
	v_lshlrev_b32_e32 v20, 16, v143
	v_and_b32_e32 v21, 0xffff0000, v143
	v_max_f32_e32 v20, v20, v20
	v_max_f32_e32 v21, v21, v21
	v_max_f32_e32 v20, 0x1e3ce508, v20
	v_max_f32_e32 v21, 0x1e3ce508, v21
	v_rcp_f32_e32 v20, v20
	v_rcp_f32_e32 v21, v21
	v_pk_mul_f32 v[6:7], v[6:7], v[18:19]
	v_lshlrev_b32_e32 v18, 16, v135
	v_and_b32_e32 v19, 0xffff0000, v135
	v_pk_mul_f32 v[18:19], v[20:21], v[18:19]
	v_lshlrev_b32_e32 v20, 16, v144
	v_and_b32_e32 v21, 0xffff0000, v144
	v_max_f32_e32 v20, v20, v20
	v_max_f32_e32 v21, v21, v21
	v_max_f32_e32 v20, 0x1e3ce508, v20
	v_max_f32_e32 v21, 0x1e3ce508, v21
	v_rcp_f32_e32 v20, v20
	v_rcp_f32_e32 v21, v21
	v_pk_mul_f32 v[8:9], v[8:9], v[18:19]
	v_lshlrev_b32_e32 v18, 16, v136
	v_and_b32_e32 v19, 0xffff0000, v136
	v_pk_mul_f32 v[18:19], v[20:21], v[18:19]
	v_lshlrev_b32_e32 v20, 16, v145
	v_and_b32_e32 v21, 0xffff0000, v145
	v_max_f32_e32 v20, v20, v20
	v_max_f32_e32 v21, v21, v21
	v_max_f32_e32 v20, 0x1e3ce508, v20
	v_max_f32_e32 v21, 0x1e3ce508, v21
	v_rcp_f32_e32 v20, v20
	v_rcp_f32_e32 v21, v21
	v_pk_mul_f32 v[2:3], v[2:3], v[18:19]
	v_lshlrev_b32_e32 v18, 16, v137
	v_and_b32_e32 v19, 0xffff0000, v137
	v_pk_mul_f32 v[18:19], v[20:21], v[18:19]
	v_readlane_b32 s2, v238, 44
	v_pk_mul_f32 v[4:5], v[4:5], v[18:19]
	s_add_u32 s2, s0, s2
	s_addc_u32 s3, s1, s28
	v_cmp_gt_i64_e32 vcc, s[2:3], v[160:161]
	v_cmp_lt_i64_e64 s[0:1], s[2:3], v[158:159]
	s_cbranch_vccnz .LBB0_753
	s_ashr_i32 s3, s2, 31
	s_lshr_b32 s3, s3, 29
	s_add_i32 s4, s2, s3
	s_and_b32 s3, s4, -8
	s_sub_i32 s5, s2, s3
	s_cmp_gt_i32 s5, -1
	s_mov_b64 s[2:3], -1
	s_cbranch_scc0 .LBB0_750
	s_lshl_b32 s16, s5, 6
	s_mov_b64 s[2:3], 0

.LBB0_754:
	ds_read_b128 v[18:21], v172
	ds_read_b128 v[134:137], v172 offset:1024
	ds_read_b128 v[138:141], v172 offset:2048
	ds_read_b128 v[142:145], v172 offset:3072
	ds_read_b128 v[146:149], v173
	ds_read_b128 v[150:153], v173 offset:1024
	ds_read_b128 v[154:157], v173 offset:2048
	ds_read_b128 v[178:181], v173 offset:3072
	s_add_u32 s2, s30, 0x100
	s_addc_u32 s3, s31, 0
	s_cmp_eq_u32 s37, 60
	s_cselect_b32 s26, s33, s2
	s_cselect_b32 s27, s5, s3
	s_cselect_b32 s24, s36, s34
	s_cselect_b32 s25, s21, s35
	s_add_u32 s16, s26, 0x80
	s_addc_u32 s17, s27, 0
	s_add_u32 s30, s30, 0x100080
	s_addc_u32 s31, s31, 0
	s_mov_b32 m0, s76
	ds_read_b128 v[182:185], v174
	ds_read_b128 v[186:189], v174 offset:1024
	ds_read_b128 v[190:193], v174 offset:2048
	ds_read_b128 v[194:197], v174 offset:3072
	ds_read_b128 v[198:201], v174 offset:4096
	ds_read_b128 v[202:205], v174 offset:5120
	ds_read_b128 v[206:209], v174 offset:6144
	ds_read_b128 v[210:213], v174 offset:7168
	s_nop 0
	global_load_lds_dwordx4 v1, s[30:31]
	s_mov_b32 m0, s77
	s_nop 0
	global_load_lds_dwordx4 v165, s[30:31]
	s_waitcnt vmcnt(8)
	s_waitcnt lgkmcnt(0)
	s_setprio 1
	s_waitcnt lgkmcnt(0)
	s_barrier
	v_mfma_f32_16x16x32_bf16 v[34:37], v[18:21], v[182:185], v[34:37]
	v_mfma_f32_16x16x32_bf16 v[30:33], v[138:141], v[182:185], v[30:33]
	v_mfma_f32_16x16x32_bf16 v[46:49], v[18:21], v[190:193], v[46:49]
	v_mfma_f32_16x16x32_bf16 v[62:65], v[138:141], v[190:193], v[62:65]
	v_mfma_f32_16x16x32_bf16 v[78:81], v[18:21], v[198:201], v[78:81]
	v_mfma_f32_16x16x32_bf16 v[90:93], v[138:141], v[198:201], v[90:93]
	v_mfma_f32_16x16x32_bf16 v[106:109], v[18:21], v[206:209], v[106:109]
	v_mfma_f32_16x16x32_bf16 v[114:117], v[138:141], v[206:209], v[114:117]
	v_mfma_f32_16x16x32_bf16 v[26:29], v[146:149], v[182:185], v[26:29]
	v_mfma_f32_16x16x32_bf16 v[50:53], v[154:157], v[182:185], v[50:53]
	v_mfma_f32_16x16x32_bf16 v[58:61], v[146:149], v[190:193], v[58:61]
	v_mfma_f32_16x16x32_bf16 v[82:85], v[154:157], v[190:193], v[82:85]
	v_mfma_f32_16x16x32_bf16 v[110:113], v[146:149], v[198:201], v[110:113]
	v_mfma_f32_16x16x32_bf16 v[118:121], v[154:157], v[198:201], v[118:121]
	v_mfma_f32_16x16x32_bf16 v[122:125], v[146:149], v[206:209], v[122:125]
	v_mfma_f32_16x16x32_bf16 v[126:129], v[154:157], v[206:209], v[126:129]
	v_mfma_f32_16x16x32_bf16 v[34:37], v[134:137], v[186:189], v[34:37]
	v_mfma_f32_16x16x32_bf16 v[30:33], v[142:145], v[186:189], v[30:33]
	v_mfma_f32_16x16x32_bf16 v[46:49], v[134:137], v[194:197], v[46:49]
	v_mfma_f32_16x16x32_bf16 v[62:65], v[142:145], v[194:197], v[62:65]
	v_mfma_f32_16x16x32_bf16 v[78:81], v[134:137], v[202:205], v[78:81]
	v_mfma_f32_16x16x32_bf16 v[90:93], v[142:145], v[202:205], v[90:93]
	v_mfma_f32_16x16x32_bf16 v[106:109], v[134:137], v[210:213], v[106:109]
	v_mfma_f32_16x16x32_bf16 v[114:117], v[142:145], v[210:213], v[114:117]
	v_mfma_f32_16x16x32_bf16 v[26:29], v[150:153], v[186:189], v[26:29]
	v_mfma_f32_16x16x32_bf16 v[50:53], v[178:181], v[186:189], v[50:53]
	v_mfma_f32_16x16x32_bf16 v[58:61], v[150:153], v[194:197], v[58:61]
	v_mfma_f32_16x16x32_bf16 v[82:85], v[178:181], v[194:197], v[82:85]
	v_mfma_f32_16x16x32_bf16 v[110:113], v[150:153], v[202:205], v[110:113]
	v_mfma_f32_16x16x32_bf16 v[118:121], v[178:181], v[202:205], v[118:121]
	v_mfma_f32_16x16x32_bf16 v[122:125], v[150:153], v[210:213], v[122:125]
	v_mfma_f32_16x16x32_bf16 v[126:129], v[178:181], v[210:213], v[126:129]
	s_setprio 0
	s_barrier
	s_mov_b32 m0, s80
	s_mov_b64 s[30:31], s[24:25]
	ds_read_b128 v[182:185], v174 offset:16384
	ds_read_b128 v[186:189], v174 offset:17408
	ds_read_b128 v[190:193], v174 offset:18432
	ds_read_b128 v[194:197], v174 offset:19456
	ds_read_b128 v[198:201], v174 offset:20480
	ds_read_b128 v[202:205], v174 offset:21504
	ds_read_b128 v[206:209], v174 offset:22528
	ds_read_b128 v[210:213], v174 offset:23552
	s_nop 0
	global_load_lds_dwordx4 v164, s[30:31]
	s_mov_b32 m0, s81
	s_nop 0
	global_load_lds_dwordx4 v166, s[30:31]
	s_add_u32 s30, s24, 0x100000
	s_addc_u32 s31, s25, 0
	s_mov_b32 m0, s82
	s_nop 0
	global_load_lds_dwordx4 v164, s[30:31]
	s_mov_b32 m0, s83
	s_nop 0
	global_load_lds_dwordx4 v166, s[30:31]
	s_mov_b64 s[30:31], s[26:27]
	s_mov_b32 m0, s46
	s_nop 0
	global_load_lds_dwordx4 v1, s[30:31]
	s_mov_b32 m0, s47
	s_nop 0
	global_load_lds_dwordx4 v165, s[30:31]
	s_waitcnt vmcnt(8)
	s_waitcnt lgkmcnt(0)
	s_setprio 1
	s_waitcnt lgkmcnt(0)
	s_barrier
	v_mfma_f32_16x16x32_bf16 v[102:105], v[18:21], v[182:185], v[102:105]
	v_mfma_f32_16x16x32_bf16 v[98:101], v[138:141], v[182:185], v[98:101]
	v_mfma_f32_16x16x32_bf16 v[74:77], v[18:21], v[190:193], v[74:77]
	v_mfma_f32_16x16x32_bf16 v[70:73], v[138:141], v[190:193], v[70:73]
	v_mfma_f32_16x16x32_bf16 v[42:45], v[18:21], v[198:201], v[42:45]
	v_mfma_f32_16x16x32_bf16 v[38:41], v[138:141], v[198:201], v[38:41]
	v_mfma_f32_16x16x32_bf16 v[14:17], v[18:21], v[206:209], v[14:17]
	v_mfma_f32_16x16x32_bf16 v[10:13], v[138:141], v[206:209], v[10:13]
	v_mfma_f32_16x16x32_bf16 v[18:21], v[146:149], v[182:185], v[94:97]
	v_mfma_f32_16x16x32_bf16 v[86:89], v[154:157], v[182:185], v[86:89]
	v_mfma_f32_16x16x32_bf16 v[66:69], v[146:149], v[190:193], v[66:69]
	v_mfma_f32_16x16x32_bf16 v[54:57], v[154:157], v[190:193], v[54:57]
	v_mfma_f32_16x16x32_bf16 v[22:25], v[146:149], v[198:201], v[22:25]
	v_mfma_f32_16x16x32_bf16 v[94:97], v[154:157], v[198:201], v[130:133]
	v_mfma_f32_16x16x32_bf16 v[6:9], v[146:149], v[206:209], v[6:9]
	v_mfma_f32_16x16x32_bf16 v[2:5], v[154:157], v[206:209], v[2:5]
	v_mfma_f32_16x16x32_bf16 v[102:105], v[134:137], v[186:189], v[102:105]
	v_mfma_f32_16x16x32_bf16 v[98:101], v[142:145], v[186:189], v[98:101]
	v_mfma_f32_16x16x32_bf16 v[74:77], v[134:137], v[194:197], v[74:77]
	v_mfma_f32_16x16x32_bf16 v[70:73], v[142:145], v[194:197], v[70:73]
	v_mfma_f32_16x16x32_bf16 v[42:45], v[134:137], v[202:205], v[42:45]
	v_mfma_f32_16x16x32_bf16 v[38:41], v[142:145], v[202:205], v[38:41]
	v_mfma_f32_16x16x32_bf16 v[14:17], v[134:137], v[210:213], v[14:17]
	v_mfma_f32_16x16x32_bf16 v[10:13], v[142:145], v[210:213], v[10:13]
	v_mfma_f32_16x16x32_bf16 v[86:89], v[178:181], v[186:189], v[86:89]
	v_mfma_f32_16x16x32_bf16 v[66:69], v[150:153], v[194:197], v[66:69]
	v_mfma_f32_16x16x32_bf16 v[54:57], v[178:181], v[194:197], v[54:57]
	v_mfma_f32_16x16x32_bf16 v[22:25], v[150:153], v[202:205], v[22:25]
	v_mfma_f32_16x16x32_bf16 v[130:133], v[178:181], v[202:205], v[94:97]
	v_mfma_f32_16x16x32_bf16 v[6:9], v[150:153], v[210:213], v[6:9]
	v_mfma_f32_16x16x32_bf16 v[2:5], v[178:181], v[210:213], v[2:5]
	v_mfma_f32_16x16x32_bf16 v[18:21], v[150:153], v[186:189], v[18:21]
	s_setprio 0
	s_barrier
;     __device__ bool next(int i, Unit& u) const { if (i > 1) return false; const int xcd = c & 7, idx = c >> 3; u.pm = 16 * i + 4 * (xcd >> 1) + (idx & 3); u.pn = 8 * (xcd & 1) + (idx >> 2); return true; }
; #define PG8_BAR __builtin_amdgcn_s_barrier()
; #define PG8_BAR __builtin_amdgcn_s_barrier()
; template <class Epi, class Sched>
; __device__ __forceinline__ void gemm_phase_dual(PG8_LAS unsigned char* lds, const Gemm g  , const bf16_t* A0, const bf16_t* Bt0, int K0, const Sched& S, const Epi& E) {
;     ...
;     const int nt0 = K0 / BK, nt1 = K / BK;
;     for (;;) {
;         const char* mA = (const char*)g.A + (size_t)cur.pm * tstep; const char* mB = (const char*)g.Bt + (size_t)cur.pn * tstep;
;         PG8_KLOOP(nt0, cA, cB, mA, mB)
;         E.mid(acc, cur, wr, wc, fr, fq);
;         const bool has_next = S.next(ui + 1, nxt);
;         const char* nA = has_next ? (const char*)A0 + (size_t)nxt.pm * tstep : mA; const char* nB = has_next ? (const char*)Bt0 + (size_t)nxt.pn * tstep : mB;
;         PG8_KLOOP(nt1, mA, mB, nA, nB)
;         if (wr == 0) PG8_BAR;
	ds_read_b128 v[94:97], v175
	ds_read_b128 v[134:137], v175 offset:1024
	ds_read_b128 v[138:141], v175 offset:2048
	ds_read_b128 v[142:145], v175 offset:3072
	ds_read_b128 v[146:149], v176
	ds_read_b128 v[150:153], v176 offset:1024
	ds_read_b128 v[154:157], v176 offset:2048
	ds_read_b128 v[178:181], v176 offset:3072
	s_add_u32 s26, s26, 0x100000
	s_addc_u32 s27, s27, 0
	s_mov_b32 m0, s48
	ds_read_b128 v[182:185], v174 offset:32768
	ds_read_b128 v[186:189], v174 offset:33792
	ds_read_b128 v[190:193], v174 offset:34816
	ds_read_b128 v[194:197], v174 offset:35840
	ds_read_b128 v[198:201], v174 offset:36864
	ds_read_b128 v[202:205], v174 offset:37888
	ds_read_b128 v[206:209], v174 offset:38912
	ds_read_b128 v[210:213], v174 offset:39936
	s_nop 0
	global_load_lds_dwordx4 v1, s[26:27]
	s_mov_b32 m0, s49
	s_nop 0
	global_load_lds_dwordx4 v165, s[26:27]
	s_waitcnt vmcnt(8)
	s_waitcnt lgkmcnt(0)
	s_setprio 1
	s_waitcnt lgkmcnt(0)
	s_barrier
	v_mfma_f32_16x16x32_bf16 v[34:37], v[94:97], v[182:185], v[34:37]
	v_mfma_f32_16x16x32_bf16 v[30:33], v[138:141], v[182:185], v[30:33]
	v_mfma_f32_16x16x32_bf16 v[46:49], v[94:97], v[190:193], v[46:49]
	v_mfma_f32_16x16x32_bf16 v[62:65], v[138:141], v[190:193], v[62:65]
	v_mfma_f32_16x16x32_bf16 v[78:81], v[94:97], v[198:201], v[78:81]
	v_mfma_f32_16x16x32_bf16 v[90:93], v[138:141], v[198:201], v[90:93]
	v_mfma_f32_16x16x32_bf16 v[106:109], v[94:97], v[206:209], v[106:109]
	v_mfma_f32_16x16x32_bf16 v[114:117], v[138:141], v[206:209], v[114:117]
	v_mfma_f32_16x16x32_bf16 v[26:29], v[146:149], v[182:185], v[26:29]
	v_mfma_f32_16x16x32_bf16 v[50:53], v[154:157], v[182:185], v[50:53]
	v_mfma_f32_16x16x32_bf16 v[58:61], v[146:149], v[190:193], v[58:61]
	v_mfma_f32_16x16x32_bf16 v[82:85], v[154:157], v[190:193], v[82:85]
	v_mfma_f32_16x16x32_bf16 v[110:113], v[146:149], v[198:201], v[110:113]
	v_mfma_f32_16x16x32_bf16 v[118:121], v[154:157], v[198:201], v[118:121]
	v_mfma_f32_16x16x32_bf16 v[122:125], v[146:149], v[206:209], v[122:125]
	v_mfma_f32_16x16x32_bf16 v[126:129], v[154:157], v[206:209], v[126:129]
	v_mfma_f32_16x16x32_bf16 v[34:37], v[134:137], v[186:189], v[34:37]
	v_mfma_f32_16x16x32_bf16 v[30:33], v[142:145], v[186:189], v[30:33]
	v_mfma_f32_16x16x32_bf16 v[46:49], v[134:137], v[194:197], v[46:49]
	v_mfma_f32_16x16x32_bf16 v[62:65], v[142:145], v[194:197], v[62:65]
	v_mfma_f32_16x16x32_bf16 v[78:81], v[134:137], v[202:205], v[78:81]
	v_mfma_f32_16x16x32_bf16 v[90:93], v[142:145], v[202:205], v[90:93]
	v_mfma_f32_16x16x32_bf16 v[106:109], v[134:137], v[210:213], v[106:109]
	v_mfma_f32_16x16x32_bf16 v[114:117], v[142:145], v[210:213], v[114:117]
	v_mfma_f32_16x16x32_bf16 v[26:29], v[150:153], v[186:189], v[26:29]
	v_mfma_f32_16x16x32_bf16 v[50:53], v[178:181], v[186:189], v[50:53]
	v_mfma_f32_16x16x32_bf16 v[58:61], v[150:153], v[194:197], v[58:61]
	v_mfma_f32_16x16x32_bf16 v[82:85], v[178:181], v[194:197], v[82:85]
	v_mfma_f32_16x16x32_bf16 v[110:113], v[150:153], v[202:205], v[110:113]
	v_mfma_f32_16x16x32_bf16 v[118:121], v[178:181], v[202:205], v[118:121]
	v_mfma_f32_16x16x32_bf16 v[122:125], v[150:153], v[210:213], v[122:125]
	v_mfma_f32_16x16x32_bf16 v[126:129], v[178:181], v[210:213], v[126:129]
	s_setprio 0
	s_barrier
	s_add_u32 s26, s24, 0x80
	s_mov_b32 m0, s84
	s_addc_u32 s27, s25, 0
	ds_read_b128 v[182:185], v174 offset:49152
	ds_read_b128 v[186:189], v174 offset:50176
	ds_read_b128 v[190:193], v174 offset:51200
	ds_read_b128 v[194:197], v174 offset:52224
	ds_read_b128 v[198:201], v174 offset:53248
	ds_read_b128 v[202:205], v174 offset:54272
	ds_read_b128 v[206:209], v174 offset:55296
	ds_read_b128 v[210:213], v174 offset:56320
	s_add_u32 s24, s24, 0x100080
	global_load_lds_dwordx4 v164, s[26:27]
	s_mov_b32 m0, s85
	s_addc_u32 s25, s25, 0
	global_load_lds_dwordx4 v166, s[26:27]
	s_mov_b32 m0, s86
	s_nop 0
	global_load_lds_dwordx4 v164, s[24:25]
	s_mov_b32 m0, s87
	s_nop 0
	global_load_lds_dwordx4 v166, s[24:25]
	s_mov_b32 m0, s57
	s_nop 0
	global_load_lds_dwordx4 v1, s[16:17]
	s_mov_b32 m0, s62
	s_nop 0
	global_load_lds_dwordx4 v165, s[16:17]
	s_waitcnt vmcnt(8)
	s_waitcnt lgkmcnt(0)
	s_setprio 1
	s_waitcnt lgkmcnt(0)
	s_barrier
	v_mfma_f32_16x16x32_bf16 v[18:21], v[146:149], v[182:185], v[18:21]
	v_mfma_f32_16x16x32_bf16 v[102:105], v[94:97], v[182:185], v[102:105]
	v_mfma_f32_16x16x32_bf16 v[74:77], v[94:97], v[190:193], v[74:77]
	v_mfma_f32_16x16x32_bf16 v[42:45], v[94:97], v[198:201], v[42:45]
	v_mfma_f32_16x16x32_bf16 v[14:17], v[94:97], v[206:209], v[14:17]
	v_mfma_f32_16x16x32_bf16 v[94:97], v[150:153], v[186:189], v[18:21]
	v_mfma_f32_16x16x32_bf16 v[18:21], v[154:157], v[182:185], v[86:89]
	v_mfma_f32_16x16x32_bf16 v[86:89], v[178:181], v[186:189], v[18:21]
	v_mfma_f32_16x16x32_bf16 v[18:21], v[146:149], v[190:193], v[66:69]
	v_mfma_f32_16x16x32_bf16 v[66:69], v[150:153], v[194:197], v[18:21]
	v_mfma_f32_16x16x32_bf16 v[18:21], v[154:157], v[190:193], v[54:57]
	v_mfma_f32_16x16x32_bf16 v[54:57], v[178:181], v[194:197], v[18:21]
	v_mfma_f32_16x16x32_bf16 v[18:21], v[146:149], v[198:201], v[22:25]
	v_mfma_f32_16x16x32_bf16 v[98:101], v[138:141], v[182:185], v[98:101]
	v_mfma_f32_16x16x32_bf16 v[70:73], v[138:141], v[190:193], v[70:73]
	v_mfma_f32_16x16x32_bf16 v[38:41], v[138:141], v[198:201], v[38:41]
	v_mfma_f32_16x16x32_bf16 v[10:13], v[138:141], v[206:209], v[10:13]
	v_mfma_f32_16x16x32_bf16 v[22:25], v[150:153], v[202:205], v[18:21]
	v_mfma_f32_16x16x32_bf16 v[18:21], v[154:157], v[198:201], v[130:133]
	v_mfma_f32_16x16x32_bf16 v[6:9], v[146:149], v[206:209], v[6:9]
	v_mfma_f32_16x16x32_bf16 v[2:5], v[154:157], v[206:209], v[2:5]
	v_mfma_f32_16x16x32_bf16 v[102:105], v[134:137], v[186:189], v[102:105]
	v_mfma_f32_16x16x32_bf16 v[98:101], v[142:145], v[186:189], v[98:101]
	v_mfma_f32_16x16x32_bf16 v[74:77], v[134:137], v[194:197], v[74:77]
	v_mfma_f32_16x16x32_bf16 v[70:73], v[142:145], v[194:197], v[70:73]
	v_mfma_f32_16x16x32_bf16 v[42:45], v[134:137], v[202:205], v[42:45]
	v_mfma_f32_16x16x32_bf16 v[38:41], v[142:145], v[202:205], v[38:41]
	v_mfma_f32_16x16x32_bf16 v[14:17], v[134:137], v[210:213], v[14:17]
	v_mfma_f32_16x16x32_bf16 v[10:13], v[142:145], v[210:213], v[10:13]
	v_mfma_f32_16x16x32_bf16 v[130:133], v[178:181], v[202:205], v[18:21]
	v_mfma_f32_16x16x32_bf16 v[6:9], v[150:153], v[210:213], v[6:9]
	v_mfma_f32_16x16x32_bf16 v[2:5], v[178:181], v[210:213], v[2:5]
	s_setprio 0
	s_barrier
	s_add_i32 s37, s37, 2
	s_add_u32 s34, s34, 0x100
	s_addc_u32 s35, s35, 0
	s_cmp_gt_u32 s37, 61
	s_mov_b64 s[30:31], s[2:3]
	s_cbranch_scc0 .LBB0_754
	s_and_b64 vcc, exec, s[18:19]
	s_cbranch_vccz .LBB0_757
	s_barrier

; #define PG8_STAGE(bufoff, gbase, voff) do { const char* _gb = (const char*)(gbase); asm volatile("" : "+s"(_gb)); _Pragma("unroll") for (int _i = 0; _i < 2; ++_i) { asm volatile("" : "+v"((voff)[_i])); \
;         __builtin_amdgcn_global_load_lds((const unsigned*)(_gb + (voff)[_i]), (PG8_LAS unsigned*)(lds + (bufoff) + ldsw + _i * 8192), 16, 0, 0); } } while (0)
; #define PG8_LDA(dst, b, h) do { _Pragma("unroll") for (int m = 0; m < 4; ++m) _Pragma("unroll") for (int k = 0; k < 2; ++k) dst[m][k] = *(const PG8_LAS bf16x8*)(lds + PG8_SA(b, h) + aoff + m * 2048 + k * 1024); } while (0)
; #define PG8_LDB(dst, b, h) do { _Pragma("unroll") for (int n = 0; n < 2; ++n) _Pragma("unroll") for (int k = 0; k < 2; ++k) dst[n][k] = *(const PG8_LAS bf16x8*)(lds + PG8_SB(b, h) + boff + n * 2048 + k * 1024); } while (0)
; #define PG8_WAIT_V(n) asm volatile("s_waitcnt vmcnt(" #n ")" ::: "memory")
; #define PG8_WAIT_L(n) asm volatile("s_waitcnt lgkmcnt(" #n ")" ::: "memory")
; #define PG8_BAR __builtin_amdgcn_s_barrier()
; #define PG8_SCHED __builtin_amdgcn_sched_barrier(0)
; #define PG8_STAGE(bufoff, gbase, voff) do { const char* _gb = (const char*)(gbase); asm volatile("" : "+s"(_gb)); _Pragma("unroll") for (int _i = 0; _i < 2; ++_i) { asm volatile("" : "+v"((voff)[_i])); \
;         __builtin_amdgcn_global_load_lds((const unsigned*)(_gb + (voff)[_i]), (PG8_LAS unsigned*)(lds + (bufoff) + ldsw + _i * 8192), 16, 0, 0); } } while (0)
; #define PG8_LDA(dst, b, h) do { _Pragma("unroll") for (int m = 0; m < 4; ++m) _Pragma("unroll") for (int k = 0; k < 2; ++k) dst[m][k] = *(const PG8_LAS bf16x8*)(lds + PG8_SA(b, h) + aoff + m * 2048 + k * 1024); } while (0)
; #define PG8_WAIT_V(n) asm volatile("s_waitcnt vmcnt(" #n ")" ::: "memory")
; template <class Epi, class Sched, bool ALIGN_EPI = false, bool SP2 = false>
; __device__ __forceinline__ void gemm_phase(PG8_LAS unsigned char* lds, const Gemm g, const Sched& S, const Epi& E) {
;     ...
;             PG8_LDB(B0, 0, 0); PG8_LDB(B1, 0, 1); PG8_SCHED; PG8_LDA(At, 0, 0); PG8_STAGE(PG8_SA(1, 1), a1 + hstep, voffA);
;             PG8_WAIT_V(8); PG8_WAIT_L(0); PG8_BAR; PG8_MMA2(0); PG8_BAR; PG8_SCHED;
;             PG8_LDA(At, 0, 1); PG8_STAGE(PG8_SB(0, 0), b2, voffB); PG8_STAGE(PG8_SB(0, 1), b2 + hstep, voffB); PG8_STAGE(PG8_SA(0, 0), a2, voffA);
;             PG8_WAIT_V(8); PG8_WAIT_L(0); PG8_BAR; PG8_MMA2(1); PG8_BAR; PG8_SCHED;
.LBB0_833:
	ds_read_b128 v[130:133], v180
	ds_read_b128 v[134:137], v180 offset:1024
	ds_read_b128 v[138:141], v180 offset:2048
	ds_read_b128 v[142:145], v180 offset:3072
	ds_read_b128 v[146:149], v181
	ds_read_b128 v[150:153], v181 offset:1024
	ds_read_b128 v[154:157], v181 offset:2048
	ds_read_b128 v[158:161], v181 offset:3072
	s_add_u32 s24, s16, 0x100
	s_addc_u32 s25, s17, 0
	s_cmp_eq_u32 s87, 60
	s_cselect_b32 s28, s83, s24
	s_cselect_b32 s29, s55, s25
	s_cselect_b32 s26, s84, s85
	s_cselect_b32 s27, s53, s86
	s_add_u32 s2, s28, 0x80
	s_addc_u32 s3, s29, 0
	s_add_u32 s16, s16, 0x100080
	s_addc_u32 s17, s17, 0
	s_add_i32 m0, s69, 0xc000
	ds_read_b128 v[166:169], v182
	ds_read_b128 v[170:173], v182 offset:1024
	ds_read_b128 v[184:187], v182 offset:2048
	ds_read_b128 v[188:191], v182 offset:3072
	ds_read_b128 v[192:195], v182 offset:4096
	ds_read_b128 v[196:199], v182 offset:5120
	ds_read_b128 v[200:203], v182 offset:6144
	ds_read_b128 v[204:207], v182 offset:7168
	s_nop 0
	global_load_lds_dwordx4 v1, s[16:17]
	s_add_i32 m0, s69, 0xe000
	s_nop 0
	global_load_lds_dwordx4 v175, s[16:17]
	s_waitcnt vmcnt(8)
	s_waitcnt lgkmcnt(0)
	s_setprio 1
	s_waitcnt lgkmcnt(0)
	s_barrier
	v_mfma_f32_16x16x32_bf16 v[126:129], v[130:133], v[166:169], v[126:129]
	v_mfma_f32_16x16x32_bf16 v[122:125], v[138:141], v[166:169], v[122:125]
	v_mfma_f32_16x16x32_bf16 v[110:113], v[130:133], v[184:187], v[110:113]
	v_mfma_f32_16x16x32_bf16 v[106:109], v[138:141], v[184:187], v[106:109]
	v_mfma_f32_16x16x32_bf16 v[94:97], v[130:133], v[192:195], v[94:97]
	v_mfma_f32_16x16x32_bf16 v[90:93], v[138:141], v[192:195], v[90:93]
	v_mfma_f32_16x16x32_bf16 v[78:81], v[130:133], v[200:203], v[78:81]
	v_mfma_f32_16x16x32_bf16 v[74:77], v[138:141], v[200:203], v[74:77]
	v_mfma_f32_16x16x32_bf16 v[118:121], v[146:149], v[166:169], v[118:121]
	v_mfma_f32_16x16x32_bf16 v[114:117], v[154:157], v[166:169], v[114:117]
	v_mfma_f32_16x16x32_bf16 v[102:105], v[146:149], v[184:187], v[102:105]
	v_mfma_f32_16x16x32_bf16 v[98:101], v[154:157], v[184:187], v[98:101]
	v_mfma_f32_16x16x32_bf16 v[86:89], v[146:149], v[192:195], v[86:89]
	v_mfma_f32_16x16x32_bf16 v[82:85], v[154:157], v[192:195], v[82:85]
	v_mfma_f32_16x16x32_bf16 v[70:73], v[146:149], v[200:203], v[70:73]
	v_mfma_f32_16x16x32_bf16 v[66:69], v[154:157], v[200:203], v[66:69]
	v_mfma_f32_16x16x32_bf16 v[126:129], v[134:137], v[170:173], v[126:129]
	v_mfma_f32_16x16x32_bf16 v[122:125], v[142:145], v[170:173], v[122:125]
	v_mfma_f32_16x16x32_bf16 v[110:113], v[134:137], v[188:191], v[110:113]
	v_mfma_f32_16x16x32_bf16 v[106:109], v[142:145], v[188:191], v[106:109]
	v_mfma_f32_16x16x32_bf16 v[94:97], v[134:137], v[196:199], v[94:97]
	v_mfma_f32_16x16x32_bf16 v[90:93], v[142:145], v[196:199], v[90:93]
	v_mfma_f32_16x16x32_bf16 v[78:81], v[134:137], v[204:207], v[78:81]
	v_mfma_f32_16x16x32_bf16 v[74:77], v[142:145], v[204:207], v[74:77]
	v_mfma_f32_16x16x32_bf16 v[118:121], v[150:153], v[170:173], v[118:121]
	v_mfma_f32_16x16x32_bf16 v[114:117], v[158:161], v[170:173], v[114:117]
	v_mfma_f32_16x16x32_bf16 v[102:105], v[150:153], v[188:191], v[102:105]
	v_mfma_f32_16x16x32_bf16 v[98:101], v[158:161], v[188:191], v[98:101]
	v_mfma_f32_16x16x32_bf16 v[86:89], v[150:153], v[196:199], v[86:89]
	v_mfma_f32_16x16x32_bf16 v[82:85], v[158:161], v[196:199], v[82:85]
	v_mfma_f32_16x16x32_bf16 v[70:73], v[150:153], v[204:207], v[70:73]
	v_mfma_f32_16x16x32_bf16 v[66:69], v[158:161], v[204:207], v[66:69]
	s_setprio 0
	s_barrier
	s_add_i32 s88, s81, s73
	s_mov_b64 s[16:17], s[26:27]
	s_mov_b32 m0, s88
	ds_read_b128 v[166:169], v182 offset:16384
	ds_read_b128 v[170:173], v182 offset:17408
	ds_read_b128 v[184:187], v182 offset:18432
	ds_read_b128 v[188:191], v182 offset:19456
	ds_read_b128 v[192:195], v182 offset:20480
	ds_read_b128 v[196:199], v182 offset:21504
	ds_read_b128 v[200:203], v182 offset:22528
	ds_read_b128 v[204:207], v182 offset:23552
	s_nop 0
	global_load_lds_dwordx4 v174, s[16:17]
	s_add_i32 m0, s88, 0x2000
	s_nop 0
	global_load_lds_dwordx4 v176, s[16:17]
	s_add_u32 s16, s26, 0x100000
	s_addc_u32 s17, s27, 0
	s_add_i32 s88, s82, s73
	s_mov_b32 m0, s88
	s_nop 0
	global_load_lds_dwordx4 v174, s[16:17]
	s_add_i32 m0, s88, 0x2000
	s_nop 0
	global_load_lds_dwordx4 v176, s[16:17]
	s_mov_b64 s[16:17], s[28:29]
	s_mov_b32 m0, s69
	s_nop 0
	global_load_lds_dwordx4 v1, s[16:17]
	s_mov_b32 m0, s71
	s_nop 0
	global_load_lds_dwordx4 v175, s[16:17]
	s_waitcnt vmcnt(8)
	s_waitcnt lgkmcnt(0)
	s_setprio 1
	s_waitcnt lgkmcnt(0)
	s_barrier
	v_mfma_f32_16x16x32_bf16 v[62:65], v[130:133], v[166:169], v[62:65]
	v_mfma_f32_16x16x32_bf16 v[58:61], v[138:141], v[166:169], v[58:61]
	v_mfma_f32_16x16x32_bf16 v[46:49], v[130:133], v[184:187], v[46:49]
	v_mfma_f32_16x16x32_bf16 v[42:45], v[138:141], v[184:187], v[42:45]
	v_mfma_f32_16x16x32_bf16 v[30:33], v[130:133], v[192:195], v[30:33]
	v_mfma_f32_16x16x32_bf16 v[26:29], v[138:141], v[192:195], v[26:29]
	v_mfma_f32_16x16x32_bf16 v[14:17], v[130:133], v[200:203], v[14:17]
	v_mfma_f32_16x16x32_bf16 v[10:13], v[138:141], v[200:203], v[10:13]
	v_mfma_f32_16x16x32_bf16 v[54:57], v[146:149], v[166:169], v[54:57]
	v_mfma_f32_16x16x32_bf16 v[50:53], v[154:157], v[166:169], v[50:53]
	v_mfma_f32_16x16x32_bf16 v[38:41], v[146:149], v[184:187], v[38:41]
	v_mfma_f32_16x16x32_bf16 v[34:37], v[154:157], v[184:187], v[34:37]
	v_mfma_f32_16x16x32_bf16 v[22:25], v[146:149], v[192:195], v[22:25]
	v_mfma_f32_16x16x32_bf16 v[18:21], v[154:157], v[192:195], v[18:21]
	v_mfma_f32_16x16x32_bf16 v[6:9], v[146:149], v[200:203], v[6:9]
	v_mfma_f32_16x16x32_bf16 v[2:5], v[154:157], v[200:203], v[2:5]
	v_mfma_f32_16x16x32_bf16 v[62:65], v[134:137], v[170:173], v[62:65]
	v_mfma_f32_16x16x32_bf16 v[58:61], v[142:145], v[170:173], v[58:61]
	v_mfma_f32_16x16x32_bf16 v[46:49], v[134:137], v[188:191], v[46:49]
	v_mfma_f32_16x16x32_bf16 v[42:45], v[142:145], v[188:191], v[42:45]
	v_mfma_f32_16x16x32_bf16 v[30:33], v[134:137], v[196:199], v[30:33]
	v_mfma_f32_16x16x32_bf16 v[26:29], v[142:145], v[196:199], v[26:29]
	v_mfma_f32_16x16x32_bf16 v[14:17], v[134:137], v[204:207], v[14:17]
	v_mfma_f32_16x16x32_bf16 v[10:13], v[142:145], v[204:207], v[10:13]
	v_mfma_f32_16x16x32_bf16 v[54:57], v[150:153], v[170:173], v[54:57]
	v_mfma_f32_16x16x32_bf16 v[50:53], v[158:161], v[170:173], v[50:53]
	v_mfma_f32_16x16x32_bf16 v[38:41], v[150:153], v[188:191], v[38:41]
	v_mfma_f32_16x16x32_bf16 v[34:37], v[158:161], v[188:191], v[34:37]
	v_mfma_f32_16x16x32_bf16 v[22:25], v[150:153], v[196:199], v[22:25]
	v_mfma_f32_16x16x32_bf16 v[18:21], v[158:161], v[196:199], v[18:21]
	v_mfma_f32_16x16x32_bf16 v[6:9], v[150:153], v[204:207], v[6:9]
	v_mfma_f32_16x16x32_bf16 v[2:5], v[158:161], v[204:207], v[2:5]
	s_setprio 0
	s_barrier
; #define PG8_STAGE(bufoff, gbase, voff) do { const char* _gb = (const char*)(gbase); asm volatile("" : "+s"(_gb)); _Pragma("unroll") for (int _i = 0; _i < 2; ++_i) { asm volatile("" : "+v"((voff)[_i])); \
;         __builtin_amdgcn_global_load_lds((const unsigned*)(_gb + (voff)[_i]), (PG8_LAS unsigned*)(lds + (bufoff) + ldsw + _i * 8192), 16, 0, 0); } } while (0)
; template <class Epi, class Sched, bool ALIGN_EPI = false, bool SP2 = false>
; __device__ __forceinline__ void gemm_phase(PG8_LAS unsigned char* lds, const Gemm g, const Sched& S, const Epi& E) {
;     ...
;             PG8_LDB(B0, 1, 0); PG8_LDB(B1, 1, 1); PG8_SCHED; PG8_LDA(At, 1, 0); PG8_STAGE(PG8_SA(0, 1), a2 + hstep, voffA);
;             PG8_WAIT_V(8); PG8_WAIT_L(0); PG8_BAR; PG8_MMA2(0); PG8_BAR; PG8_SCHED;
;             PG8_LDA(At, 1, 1); PG8_STAGE(PG8_SB(1, 0), b3, voffB); PG8_STAGE(PG8_SB(1, 1), b3 + hstep, voffB); PG8_STAGE(PG8_SA(1, 0), a3, voffA);
;             PG8_WAIT_V(8); PG8_WAIT_L(0); PG8_BAR; PG8_MMA2(1); PG8_BAR; PG8_SCHED;
;             } else {
;             PG8_LDB(B0, 0, 0); PG8_SCHED; PG8_LDA(At, 0, 0); PG8_STAGE(PG8_SA(1, 1), a1 + hstep, voffA);
;             PG8_WAIT_L(8); PG8_BAR; PG8_WAIT_L(0); PG8_MMA(0, 0, At, B0); PG8_BAR; PG8_SCHED;
;             PG8_LDB(B1, 0, 1); PG8_STAGE(PG8_SB(0, 0), b2, voffB);
;             PG8_BAR; PG8_WAIT_L(0); PG8_MMA(0, 1, At, B1); PG8_BAR;
;             PG8_LDA(At, 0, 1); PG8_STAGE(PG8_SA(0, 0), a2, voffA);
;             PG8_BAR; PG8_WAIT_L(0); PG8_MMA(1, 0, At, B0); PG8_BAR; PG8_SCHED;
;             PG8_STAGE(PG8_SB(0, 1), b2 + hstep, voffB);
;             PG8_WAIT_V(6); PG8_BAR; PG8_MMA(1, 1, At, B1); PG8_BAR;
;             PG8_LDB(B0, 1, 0); PG8_SCHED; PG8_LDA(At, 1, 0); PG8_STAGE(PG8_SA(0, 1), a2 + hstep, voffA);
;             PG8_WAIT_L(8); PG8_BAR; PG8_WAIT_L(0); PG8_MMA(0, 0, At, B0); PG8_BAR; PG8_SCHED;
;             PG8_LDB(B1, 1, 1); PG8_STAGE(PG8_SB(1, 0), b3, voffB);
;             PG8_BAR; PG8_WAIT_L(0); PG8_MMA(0, 1, At, B1); PG8_BAR;
;             PG8_LDA(At, 1, 1); PG8_STAGE(PG8_SA(1, 0), a3, voffA);
;             PG8_BAR; PG8_WAIT_L(0); PG8_MMA(1, 0, At, B0); PG8_BAR; PG8_SCHED;
;             PG8_STAGE(PG8_SB(1, 1), b3 + hstep, voffB);
;             PG8_WAIT_V(6); PG8_BAR; PG8_MMA(1, 1, At, B1); PG8_BAR;
;             }
;         }
;         if constexpr (ALIGN_EPI) { if (wr == 0) PG8_BAR; }
	s_add_i32 s88, 0, 0x18000
	s_add_i32 s89, 0, 0x1c000
	v_add_u32_e32 v142, s88, v178
	v_add_u32_e32 v158, s89, v178
	ds_read_b128 v[130:133], v142
	ds_read_b128 v[134:137], v142 offset:1024
	ds_read_b128 v[138:141], v142 offset:2048
	ds_read_b128 v[142:145], v142 offset:3072
	ds_read_b128 v[146:149], v158
	ds_read_b128 v[150:153], v158 offset:1024
	ds_read_b128 v[154:157], v158 offset:2048
	ds_read_b128 v[158:161], v158 offset:3072
	s_add_u32 s16, s28, 0x100000
	s_addc_u32 s17, s29, 0
	s_mov_b32 m0, s74
	ds_read_b128 v[166:169], v182 offset:32768
	ds_read_b128 v[170:173], v182 offset:33792
	ds_read_b128 v[184:187], v182 offset:34816
	ds_read_b128 v[188:191], v182 offset:35840
	ds_read_b128 v[192:195], v182 offset:36864
	ds_read_b128 v[196:199], v182 offset:37888
	ds_read_b128 v[200:203], v182 offset:38912
	ds_read_b128 v[204:207], v182 offset:39936
	s_nop 0
	global_load_lds_dwordx4 v1, s[16:17]
	s_mov_b32 m0, s75
	s_nop 0
	global_load_lds_dwordx4 v175, s[16:17]
	s_waitcnt vmcnt(8)
	s_waitcnt lgkmcnt(0)
	s_setprio 1
	s_waitcnt lgkmcnt(0)
	s_barrier
	v_mfma_f32_16x16x32_bf16 v[126:129], v[130:133], v[166:169], v[126:129]
	v_mfma_f32_16x16x32_bf16 v[122:125], v[138:141], v[166:169], v[122:125]
	v_mfma_f32_16x16x32_bf16 v[110:113], v[130:133], v[184:187], v[110:113]
	v_mfma_f32_16x16x32_bf16 v[106:109], v[138:141], v[184:187], v[106:109]
	v_mfma_f32_16x16x32_bf16 v[94:97], v[130:133], v[192:195], v[94:97]
	v_mfma_f32_16x16x32_bf16 v[90:93], v[138:141], v[192:195], v[90:93]
	v_mfma_f32_16x16x32_bf16 v[78:81], v[130:133], v[200:203], v[78:81]
	v_mfma_f32_16x16x32_bf16 v[74:77], v[138:141], v[200:203], v[74:77]
	v_mfma_f32_16x16x32_bf16 v[118:121], v[146:149], v[166:169], v[118:121]
	v_mfma_f32_16x16x32_bf16 v[114:117], v[154:157], v[166:169], v[114:117]
	v_mfma_f32_16x16x32_bf16 v[102:105], v[146:149], v[184:187], v[102:105]
	v_mfma_f32_16x16x32_bf16 v[98:101], v[154:157], v[184:187], v[98:101]
	v_mfma_f32_16x16x32_bf16 v[86:89], v[146:149], v[192:195], v[86:89]
	v_mfma_f32_16x16x32_bf16 v[82:85], v[154:157], v[192:195], v[82:85]
	v_mfma_f32_16x16x32_bf16 v[70:73], v[146:149], v[200:203], v[70:73]
	v_mfma_f32_16x16x32_bf16 v[66:69], v[154:157], v[200:203], v[66:69]
	v_mfma_f32_16x16x32_bf16 v[126:129], v[134:137], v[170:173], v[126:129]
	v_mfma_f32_16x16x32_bf16 v[122:125], v[142:145], v[170:173], v[122:125]
	v_mfma_f32_16x16x32_bf16 v[110:113], v[134:137], v[188:191], v[110:113]
	v_mfma_f32_16x16x32_bf16 v[106:109], v[142:145], v[188:191], v[106:109]
	v_mfma_f32_16x16x32_bf16 v[94:97], v[134:137], v[196:199], v[94:97]
	v_mfma_f32_16x16x32_bf16 v[90:93], v[142:145], v[196:199], v[90:93]
	v_mfma_f32_16x16x32_bf16 v[78:81], v[134:137], v[204:207], v[78:81]
	v_mfma_f32_16x16x32_bf16 v[74:77], v[142:145], v[204:207], v[74:77]
	v_mfma_f32_16x16x32_bf16 v[118:121], v[150:153], v[170:173], v[118:121]
	v_mfma_f32_16x16x32_bf16 v[114:117], v[158:161], v[170:173], v[114:117]
	v_mfma_f32_16x16x32_bf16 v[102:105], v[150:153], v[188:191], v[102:105]
	v_mfma_f32_16x16x32_bf16 v[98:101], v[158:161], v[188:191], v[98:101]
	v_mfma_f32_16x16x32_bf16 v[86:89], v[150:153], v[196:199], v[86:89]
	v_mfma_f32_16x16x32_bf16 v[82:85], v[158:161], v[196:199], v[82:85]
	v_mfma_f32_16x16x32_bf16 v[70:73], v[150:153], v[204:207], v[70:73]
	v_mfma_f32_16x16x32_bf16 v[66:69], v[158:161], v[204:207], v[66:69]
	s_setprio 0
	s_barrier
	s_add_u32 s16, s26, 0x80
	s_addc_u32 s17, s27, 0
	s_add_i32 s28, s88, s73
	s_mov_b32 m0, s28
	ds_read_b128 v[166:169], v182 offset:49152
	ds_read_b128 v[170:173], v182 offset:50176
	ds_read_b128 v[184:187], v182 offset:51200
	ds_read_b128 v[188:191], v182 offset:52224
	ds_read_b128 v[192:195], v182 offset:53248
	ds_read_b128 v[196:199], v182 offset:54272
	ds_read_b128 v[200:203], v182 offset:55296
	ds_read_b128 v[204:207], v182 offset:56320
	s_nop 0
	global_load_lds_dwordx4 v174, s[16:17]
	s_add_i32 m0, s28, 0x2000
	s_nop 0
	global_load_lds_dwordx4 v176, s[16:17]
	s_add_u32 s16, s26, 0x100080
	s_addc_u32 s17, s27, 0
	s_add_i32 s26, s89, s73
	s_mov_b32 m0, s26
	s_nop 0
	global_load_lds_dwordx4 v174, s[16:17]
	s_add_i32 m0, s26, 0x2000
	s_nop 0
	global_load_lds_dwordx4 v176, s[16:17]
	s_mov_b32 m0, s77
	s_nop 0
	global_load_lds_dwordx4 v1, s[2:3]
	s_mov_b32 m0, s78
	s_nop 0
	global_load_lds_dwordx4 v175, s[2:3]
	s_waitcnt vmcnt(8)
	s_waitcnt lgkmcnt(0)
	s_setprio 1
	s_waitcnt lgkmcnt(0)
	s_barrier
	v_mfma_f32_16x16x32_bf16 v[62:65], v[130:133], v[166:169], v[62:65]
	v_mfma_f32_16x16x32_bf16 v[58:61], v[138:141], v[166:169], v[58:61]
	v_mfma_f32_16x16x32_bf16 v[46:49], v[130:133], v[184:187], v[46:49]
	v_mfma_f32_16x16x32_bf16 v[42:45], v[138:141], v[184:187], v[42:45]
	v_mfma_f32_16x16x32_bf16 v[30:33], v[130:133], v[192:195], v[30:33]
	v_mfma_f32_16x16x32_bf16 v[26:29], v[138:141], v[192:195], v[26:29]
	v_mfma_f32_16x16x32_bf16 v[14:17], v[130:133], v[200:203], v[14:17]
	v_mfma_f32_16x16x32_bf16 v[10:13], v[138:141], v[200:203], v[10:13]
	v_mfma_f32_16x16x32_bf16 v[54:57], v[146:149], v[166:169], v[54:57]
	v_mfma_f32_16x16x32_bf16 v[50:53], v[154:157], v[166:169], v[50:53]
	v_mfma_f32_16x16x32_bf16 v[38:41], v[146:149], v[184:187], v[38:41]
	v_mfma_f32_16x16x32_bf16 v[34:37], v[154:157], v[184:187], v[34:37]
	v_mfma_f32_16x16x32_bf16 v[22:25], v[146:149], v[192:195], v[22:25]
	v_mfma_f32_16x16x32_bf16 v[18:21], v[154:157], v[192:195], v[18:21]
	v_mfma_f32_16x16x32_bf16 v[6:9], v[146:149], v[200:203], v[6:9]
	v_mfma_f32_16x16x32_bf16 v[2:5], v[154:157], v[200:203], v[2:5]
	v_mfma_f32_16x16x32_bf16 v[62:65], v[134:137], v[170:173], v[62:65]
	v_mfma_f32_16x16x32_bf16 v[58:61], v[142:145], v[170:173], v[58:61]
	v_mfma_f32_16x16x32_bf16 v[46:49], v[134:137], v[188:191], v[46:49]
	v_mfma_f32_16x16x32_bf16 v[42:45], v[142:145], v[188:191], v[42:45]
	v_mfma_f32_16x16x32_bf16 v[30:33], v[134:137], v[196:199], v[30:33]
	v_mfma_f32_16x16x32_bf16 v[26:29], v[142:145], v[196:199], v[26:29]
	v_mfma_f32_16x16x32_bf16 v[14:17], v[134:137], v[204:207], v[14:17]
	v_mfma_f32_16x16x32_bf16 v[10:13], v[142:145], v[204:207], v[10:13]
	v_mfma_f32_16x16x32_bf16 v[54:57], v[150:153], v[170:173], v[54:57]
	v_mfma_f32_16x16x32_bf16 v[50:53], v[158:161], v[170:173], v[50:53]
	v_mfma_f32_16x16x32_bf16 v[38:41], v[150:153], v[188:191], v[38:41]
	v_mfma_f32_16x16x32_bf16 v[34:37], v[158:161], v[188:191], v[34:37]
	v_mfma_f32_16x16x32_bf16 v[22:25], v[150:153], v[196:199], v[22:25]
	v_mfma_f32_16x16x32_bf16 v[18:21], v[158:161], v[196:199], v[18:21]
	v_mfma_f32_16x16x32_bf16 v[6:9], v[150:153], v[204:207], v[6:9]
	v_mfma_f32_16x16x32_bf16 v[2:5], v[158:161], v[204:207], v[2:5]
	s_setprio 0
	s_barrier
	s_add_i32 s87, s87, 2
	s_add_u32 s85, s85, 0x100
	s_addc_u32 s86, s86, 0
	s_cmp_gt_u32 s87, 61
	s_mov_b64 s[16:17], s[24:25]
	s_cbranch_scc0 .LBB0_833
	s_and_b64 vcc, exec, s[12:13]
	s_cbranch_vccz .LBB0_836
	s_barrier

; #define PG8_STAGE(bufoff, gbase, voff) do { const char* _gb = (const char*)(gbase); asm volatile("" : "+s"(_gb)); _Pragma("unroll") for (int _i = 0; _i < 2; ++_i) { asm volatile("" : "+v"((voff)[_i])); \
;         __builtin_amdgcn_global_load_lds((const unsigned*)(_gb + (voff)[_i]), (PG8_LAS unsigned*)(lds + (bufoff) + ldsw + _i * 8192), 16, 0, 0); } } while (0)
; #define PG8_LDA(dst, b, h) do { _Pragma("unroll") for (int m = 0; m < 4; ++m) _Pragma("unroll") for (int k = 0; k < 2; ++k) dst[m][k] = *(const PG8_LAS bf16x8*)(lds + PG8_SA(b, h) + aoff + m * 2048 + k * 1024); } while (0)
; #define PG8_LDB(dst, b, h) do { _Pragma("unroll") for (int n = 0; n < 2; ++n) _Pragma("unroll") for (int k = 0; k < 2; ++k) dst[n][k] = *(const PG8_LAS bf16x8*)(lds + PG8_SB(b, h) + boff + n * 2048 + k * 1024); } while (0)
; #define PG8_WAIT_V(n) asm volatile("s_waitcnt vmcnt(" #n ")" ::: "memory")
; #define PG8_WAIT_L(n) asm volatile("s_waitcnt lgkmcnt(" #n ")" ::: "memory")
; #define PG8_BAR __builtin_amdgcn_s_barrier()
; #define PG8_SCHED __builtin_amdgcn_sched_barrier(0)
; #define PG8_STAGE(bufoff, gbase, voff) do { const char* _gb = (const char*)(gbase); asm volatile("" : "+s"(_gb)); _Pragma("unroll") for (int _i = 0; _i < 2; ++_i) { asm volatile("" : "+v"((voff)[_i])); \
;         __builtin_amdgcn_global_load_lds((const unsigned*)(_gb + (voff)[_i]), (PG8_LAS unsigned*)(lds + (bufoff) + ldsw + _i * 8192), 16, 0, 0); } } while (0)
; #define PG8_LDA(dst, b, h) do { _Pragma("unroll") for (int m = 0; m < 4; ++m) _Pragma("unroll") for (int k = 0; k < 2; ++k) dst[m][k] = *(const PG8_LAS bf16x8*)(lds + PG8_SA(b, h) + aoff + m * 2048 + k * 1024); } while (0)
; #define PG8_WAIT_V(n) asm volatile("s_waitcnt vmcnt(" #n ")" ::: "memory")
; template <class Epi, class Sched, bool ALIGN_EPI = false, bool SP2 = false>
; __device__ __forceinline__ void gemm_phase(PG8_LAS unsigned char* lds, const Gemm g, const Sched& S, const Epi& E) {
;     ...
;             PG8_LDB(B0, 0, 0); PG8_LDB(B1, 0, 1); PG8_SCHED; PG8_LDA(At, 0, 0); PG8_STAGE(PG8_SA(1, 1), a1 + hstep, voffA);
;             PG8_WAIT_V(8); PG8_WAIT_L(0); PG8_BAR; PG8_MMA2(0); PG8_BAR; PG8_SCHED;
;             PG8_LDA(At, 0, 1); PG8_STAGE(PG8_SB(0, 0), b2, voffB); PG8_STAGE(PG8_SB(0, 1), b2 + hstep, voffB); PG8_STAGE(PG8_SA(0, 0), a2, voffA);
;             PG8_WAIT_V(8); PG8_WAIT_L(0); PG8_BAR; PG8_MMA2(1); PG8_BAR; PG8_SCHED;
.LBB0_933:
	v_add_u32_e32 v142, s78, v201
	v_add_u32_e32 v147, s79, v201
	s_nop 0
	ds_read_b128 v[6:9], v142
	ds_read_b128 v[62:65], v142 offset:1024
	ds_read_b128 v[138:141], v142 offset:2048
	ds_read_b128 v[142:145], v142 offset:3072
	ds_read_b128 v[164:167], v147
	ds_read_b128 v[168:171], v147 offset:1024
	ds_read_b128 v[172:175], v147 offset:2048
	ds_read_b128 v[176:179], v147 offset:3072
	s_add_u32 s14, s12, 0x100
	s_addc_u32 s15, s13, 0
	s_cmp_eq_u32 s83, 60
	s_cselect_b32 s18, s21, s14
	s_cselect_b32 s19, s20, s15
	s_cselect_b32 s16, s51, s62
	s_cselect_b32 s17, s49, s63
	s_add_u32 s2, s18, 0x80
	s_addc_u32 s3, s19, 0
	s_add_u32 s12, s12, 0x100080
	s_addc_u32 s13, s13, 0
	s_add_i32 m0, s33, 0xc000
	ds_read_b128 v[180:183], v219
	ds_read_b128 v[184:187], v219 offset:1024
	ds_read_b128 v[188:191], v219 offset:2048
	ds_read_b128 v[192:195], v219 offset:3072
	ds_read_b128 v[222:225], v219 offset:4096
	ds_read_b128 v[226:229], v219 offset:5120
	ds_read_b128 v[230:233], v219 offset:6144
	ds_read_b128 v[234:237], v219 offset:7168
	s_nop 0
	global_load_lds_dwordx4 v1, s[12:13]
	s_add_i32 m0, s33, 0xe000
	s_nop 0
	global_load_lds_dwordx4 v199, s[12:13]
	s_waitcnt vmcnt(8)
	s_waitcnt lgkmcnt(0)
	s_setprio 1
	s_waitcnt lgkmcnt(0)
	s_barrier
	v_mfma_f32_16x16x32_bf16 v[118:121], v[6:9], v[180:183], v[118:121]
	v_mfma_f32_16x16x32_bf16 v[114:117], v[138:141], v[180:183], v[114:117]
	v_mfma_f32_16x16x32_bf16 v[106:109], v[6:9], v[188:191], v[106:109]
	v_mfma_f32_16x16x32_bf16 v[86:89], v[138:141], v[188:191], v[86:89]
	v_mfma_f32_16x16x32_bf16 v[134:137], v[6:9], v[222:225], v[134:137]
	v_mfma_f32_16x16x32_bf16 v[90:93], v[138:141], v[222:225], v[90:93]
	v_mfma_f32_16x16x32_bf16 v[130:133], v[6:9], v[230:233], v[130:133]
	v_mfma_f32_16x16x32_bf16 v[110:113], v[138:141], v[230:233], v[110:113]
	v_mfma_f32_16x16x32_bf16 v[94:97], v[164:167], v[180:183], v[94:97]
	v_mfma_f32_16x16x32_bf16 v[82:85], v[172:175], v[180:183], v[82:85]
	v_mfma_f32_16x16x32_bf16 v[78:81], v[164:167], v[188:191], v[78:81]
	v_mfma_f32_16x16x32_bf16 v[74:77], v[172:175], v[188:191], v[74:77]
	v_mfma_f32_16x16x32_bf16 v[126:129], v[164:167], v[222:225], v[126:129]
	v_mfma_f32_16x16x32_bf16 v[98:101], v[172:175], v[222:225], v[98:101]
	v_mfma_f32_16x16x32_bf16 v[122:125], v[164:167], v[230:233], v[122:125]
	v_mfma_f32_16x16x32_bf16 v[102:105], v[172:175], v[230:233], v[102:105]
	v_mfma_f32_16x16x32_bf16 v[118:121], v[62:65], v[184:187], v[118:121]
	v_mfma_f32_16x16x32_bf16 v[114:117], v[142:145], v[184:187], v[114:117]
	v_mfma_f32_16x16x32_bf16 v[106:109], v[62:65], v[192:195], v[106:109]
	v_mfma_f32_16x16x32_bf16 v[86:89], v[142:145], v[192:195], v[86:89]
	v_mfma_f32_16x16x32_bf16 v[134:137], v[62:65], v[226:229], v[134:137]
	v_mfma_f32_16x16x32_bf16 v[90:93], v[142:145], v[226:229], v[90:93]
	v_mfma_f32_16x16x32_bf16 v[130:133], v[62:65], v[234:237], v[130:133]
	v_mfma_f32_16x16x32_bf16 v[110:113], v[142:145], v[234:237], v[110:113]
	v_mfma_f32_16x16x32_bf16 v[94:97], v[168:171], v[184:187], v[94:97]
	v_mfma_f32_16x16x32_bf16 v[82:85], v[176:179], v[184:187], v[82:85]
	v_mfma_f32_16x16x32_bf16 v[78:81], v[168:171], v[192:195], v[78:81]
	v_mfma_f32_16x16x32_bf16 v[74:77], v[176:179], v[192:195], v[74:77]
	v_mfma_f32_16x16x32_bf16 v[126:129], v[168:171], v[226:229], v[126:129]
	v_mfma_f32_16x16x32_bf16 v[98:101], v[176:179], v[226:229], v[98:101]
	v_mfma_f32_16x16x32_bf16 v[122:125], v[168:171], v[234:237], v[122:125]
	v_mfma_f32_16x16x32_bf16 v[102:105], v[176:179], v[234:237], v[102:105]
	s_setprio 0
	s_barrier
	s_add_i32 s84, s78, s25
	s_mov_b64 s[12:13], s[16:17]
	s_mov_b32 m0, s84
	ds_read_b128 v[180:183], v219 offset:16384
	ds_read_b128 v[184:187], v219 offset:17408
	ds_read_b128 v[188:191], v219 offset:18432
	ds_read_b128 v[192:195], v219 offset:19456
	ds_read_b128 v[222:225], v219 offset:20480
	ds_read_b128 v[226:229], v219 offset:21504
	ds_read_b128 v[230:233], v219 offset:22528
	ds_read_b128 v[234:237], v219 offset:23552
	s_nop 0
	global_load_lds_dwordx4 v198, s[12:13]
	s_add_i32 m0, s84, 0x2000
	s_nop 0
	global_load_lds_dwordx4 v200, s[12:13]
	s_add_u32 s12, s16, 0x100000
	s_addc_u32 s13, s17, 0
	s_add_i32 s84, s79, s25
	s_mov_b32 m0, s84
	s_nop 0
	global_load_lds_dwordx4 v198, s[12:13]
	s_add_i32 m0, s84, 0x2000
	s_nop 0
	global_load_lds_dwordx4 v200, s[12:13]
	s_mov_b64 s[12:13], s[18:19]
	s_mov_b32 m0, s33
	s_nop 0
	global_load_lds_dwordx4 v1, s[12:13]
	s_mov_b32 m0, s45
	s_nop 0
	global_load_lds_dwordx4 v199, s[12:13]
	s_waitcnt vmcnt(8)
	s_waitcnt lgkmcnt(0)
	s_setprio 1
	s_waitcnt lgkmcnt(0)
	s_barrier
; #define PG8_STAGE(bufoff, gbase, voff) do { const char* _gb = (const char*)(gbase); asm volatile("" : "+s"(_gb)); _Pragma("unroll") for (int _i = 0; _i < 2; ++_i) { asm volatile("" : "+v"((voff)[_i])); \
;         __builtin_amdgcn_global_load_lds((const unsigned*)(_gb + (voff)[_i]), (PG8_LAS unsigned*)(lds + (bufoff) + ldsw + _i * 8192), 16, 0, 0); } } while (0)
; #define PG8_LDA(dst, b, h) do { _Pragma("unroll") for (int m = 0; m < 4; ++m) _Pragma("unroll") for (int k = 0; k < 2; ++k) dst[m][k] = *(const PG8_LAS bf16x8*)(lds + PG8_SA(b, h) + aoff + m * 2048 + k * 1024); } while (0)
; #define PG8_LDB(dst, b, h) do { _Pragma("unroll") for (int n = 0; n < 2; ++n) _Pragma("unroll") for (int k = 0; k < 2; ++k) dst[n][k] = *(const PG8_LAS bf16x8*)(lds + PG8_SB(b, h) + boff + n * 2048 + k * 1024); } while (0)
; #define PG8_WAIT_V(n) asm volatile("s_waitcnt vmcnt(" #n ")" ::: "memory")
; #define PG8_WAIT_L(n) asm volatile("s_waitcnt lgkmcnt(" #n ")" ::: "memory")
; #define PG8_BAR __builtin_amdgcn_s_barrier()
; #define PG8_SCHED __builtin_amdgcn_sched_barrier(0)
; #define PG8_STAGE(bufoff, gbase, voff) do { const char* _gb = (const char*)(gbase); asm volatile("" : "+s"(_gb)); _Pragma("unroll") for (int _i = 0; _i < 2; ++_i) { asm volatile("" : "+v"((voff)[_i])); \
;         __builtin_amdgcn_global_load_lds((const unsigned*)(_gb + (voff)[_i]), (PG8_LAS unsigned*)(lds + (bufoff) + ldsw + _i * 8192), 16, 0, 0); } } while (0)
; #define PG8_LDA(dst, b, h) do { _Pragma("unroll") for (int m = 0; m < 4; ++m) _Pragma("unroll") for (int k = 0; k < 2; ++k) dst[m][k] = *(const PG8_LAS bf16x8*)(lds + PG8_SA(b, h) + aoff + m * 2048 + k * 1024); } while (0)
; template <class Epi, class Sched, bool ALIGN_EPI = false, bool SP2 = false>
; __device__ __forceinline__ void gemm_phase(PG8_LAS unsigned char* lds, const Gemm g, const Sched& S, const Epi& E) {
;     ...
;             PG8_WAIT_V(8); PG8_WAIT_L(0); PG8_BAR; PG8_MMA2(0); PG8_BAR; PG8_SCHED;
;             PG8_LDA(At, 0, 1); PG8_STAGE(PG8_SB(0, 0), b2, voffB); PG8_STAGE(PG8_SB(0, 1), b2 + hstep, voffB); PG8_STAGE(PG8_SA(0, 0), a2, voffA);
;             PG8_WAIT_V(8); PG8_WAIT_L(0); PG8_BAR; PG8_MMA2(1); PG8_BAR; PG8_SCHED;
;             PG8_LDB(B0, 1, 0); PG8_LDB(B1, 1, 1); PG8_SCHED; PG8_LDA(At, 1, 0); PG8_STAGE(PG8_SA(0, 1), a2 + hstep, voffA);
;             PG8_WAIT_V(8); PG8_WAIT_L(0); PG8_BAR; PG8_MMA2(0); PG8_BAR; PG8_SCHED;
	v_mfma_f32_16x16x32_bf16 v[34:37], v[6:9], v[180:183], v[34:37]
	v_mfma_f32_16x16x32_bf16 v[30:33], v[138:141], v[180:183], v[30:33]
	v_mfma_f32_16x16x32_bf16 v[26:29], v[6:9], v[188:191], v[26:29]
	v_mfma_f32_16x16x32_bf16 v[22:25], v[138:141], v[188:191], v[22:25]
	v_mfma_f32_16x16x32_bf16 v[70:73], v[6:9], v[222:225], v[70:73]
	v_mfma_f32_16x16x32_bf16 v[66:69], v[138:141], v[222:225], v[66:69]
	v_mfma_f32_16x16x32_bf16 v[50:53], v[138:141], v[230:233], v[50:53]
	v_mfma_f32_16x16x32_bf16 v[18:21], v[164:167], v[180:183], v[18:21]
	v_mfma_f32_16x16x32_bf16 v[14:17], v[172:175], v[180:183], v[14:17]
	v_mfma_f32_16x16x32_bf16 v[10:13], v[164:167], v[188:191], v[10:13]
	v_mfma_f32_16x16x32_bf16 v[2:5], v[172:175], v[188:191], v[2:5]
	v_mfma_f32_16x16x32_bf16 v[54:57], v[164:167], v[222:225], v[54:57]
	v_mfma_f32_16x16x32_bf16 v[46:49], v[172:175], v[222:225], v[46:49]
	v_mfma_f32_16x16x32_bf16 v[42:45], v[164:167], v[230:233], v[42:45]
	v_mfma_f32_16x16x32_bf16 v[38:41], v[172:175], v[230:233], v[38:41]
	v_mfma_f32_16x16x32_bf16 v[34:37], v[62:65], v[184:187], v[34:37]
	v_mfma_f32_16x16x32_bf16 v[30:33], v[142:145], v[184:187], v[30:33]
	v_mfma_f32_16x16x32_bf16 v[26:29], v[62:65], v[192:195], v[26:29]
	v_mfma_f32_16x16x32_bf16 v[22:25], v[142:145], v[192:195], v[22:25]
	v_mfma_f32_16x16x32_bf16 v[70:73], v[62:65], v[226:229], v[70:73]
	v_mfma_f32_16x16x32_bf16 v[66:69], v[142:145], v[226:229], v[66:69]
	v_mfma_f32_16x16x32_bf16 v[6:9], v[6:9], v[230:233], v[58:61]
	v_mfma_f32_16x16x32_bf16 v[50:53], v[142:145], v[234:237], v[50:53]
	v_mfma_f32_16x16x32_bf16 v[18:21], v[168:171], v[184:187], v[18:21]
	v_mfma_f32_16x16x32_bf16 v[14:17], v[176:179], v[184:187], v[14:17]
	v_mfma_f32_16x16x32_bf16 v[10:13], v[168:171], v[192:195], v[10:13]
	v_mfma_f32_16x16x32_bf16 v[2:5], v[176:179], v[192:195], v[2:5]
	v_mfma_f32_16x16x32_bf16 v[54:57], v[168:171], v[226:229], v[54:57]
	v_mfma_f32_16x16x32_bf16 v[46:49], v[176:179], v[226:229], v[46:49]
	v_mfma_f32_16x16x32_bf16 v[42:45], v[168:171], v[234:237], v[42:45]
	v_mfma_f32_16x16x32_bf16 v[38:41], v[176:179], v[234:237], v[38:41]
	v_mfma_f32_16x16x32_bf16 v[6:9], v[62:65], v[234:237], v[6:9]
	s_setprio 0
	s_barrier
	s_add_i32 s84, 0, 0x18000
	s_add_i32 s85, 0, 0x1c000
	v_add_u32_e32 v142, s84, v201
	v_add_u32_e32 v147, s85, v201
	ds_read_b128 v[58:61], v142
	ds_read_b128 v[62:65], v142 offset:1024
	ds_read_b128 v[138:141], v142 offset:2048
	ds_read_b128 v[142:145], v142 offset:3072
	ds_read_b128 v[164:167], v147
	ds_read_b128 v[168:171], v147 offset:1024
	ds_read_b128 v[172:175], v147 offset:2048
	ds_read_b128 v[176:179], v147 offset:3072
	s_add_u32 s12, s18, 0x100000
	s_addc_u32 s13, s19, 0
	s_mov_b32 m0, s47
	ds_read_b128 v[180:183], v219 offset:32768
	ds_read_b128 v[184:187], v219 offset:33792
	ds_read_b128 v[188:191], v219 offset:34816
	ds_read_b128 v[192:195], v219 offset:35840
	ds_read_b128 v[222:225], v219 offset:36864
	ds_read_b128 v[226:229], v219 offset:37888
	ds_read_b128 v[230:233], v219 offset:38912
	ds_read_b128 v[234:237], v219 offset:39936
	s_nop 0
	global_load_lds_dwordx4 v1, s[12:13]
	s_mov_b32 m0, s87
	s_nop 0
	global_load_lds_dwordx4 v199, s[12:13]
	s_waitcnt vmcnt(8)
	s_waitcnt lgkmcnt(0)
	s_setprio 1
	s_waitcnt lgkmcnt(0)
	s_barrier
	v_mfma_f32_16x16x32_bf16 v[118:121], v[58:61], v[180:183], v[118:121]
	v_mfma_f32_16x16x32_bf16 v[114:117], v[138:141], v[180:183], v[114:117]
	v_mfma_f32_16x16x32_bf16 v[106:109], v[58:61], v[188:191], v[106:109]
	v_mfma_f32_16x16x32_bf16 v[86:89], v[138:141], v[188:191], v[86:89]
	v_mfma_f32_16x16x32_bf16 v[134:137], v[58:61], v[222:225], v[134:137]
	v_mfma_f32_16x16x32_bf16 v[90:93], v[138:141], v[222:225], v[90:93]
	v_mfma_f32_16x16x32_bf16 v[130:133], v[58:61], v[230:233], v[130:133]
	v_mfma_f32_16x16x32_bf16 v[110:113], v[138:141], v[230:233], v[110:113]
	v_mfma_f32_16x16x32_bf16 v[94:97], v[164:167], v[180:183], v[94:97]
	v_mfma_f32_16x16x32_bf16 v[82:85], v[172:175], v[180:183], v[82:85]
	v_mfma_f32_16x16x32_bf16 v[78:81], v[164:167], v[188:191], v[78:81]
	v_mfma_f32_16x16x32_bf16 v[74:77], v[172:175], v[188:191], v[74:77]
	v_mfma_f32_16x16x32_bf16 v[126:129], v[164:167], v[222:225], v[126:129]
	v_mfma_f32_16x16x32_bf16 v[98:101], v[172:175], v[222:225], v[98:101]
	v_mfma_f32_16x16x32_bf16 v[122:125], v[164:167], v[230:233], v[122:125]
	v_mfma_f32_16x16x32_bf16 v[102:105], v[172:175], v[230:233], v[102:105]
	v_mfma_f32_16x16x32_bf16 v[118:121], v[62:65], v[184:187], v[118:121]
	v_mfma_f32_16x16x32_bf16 v[114:117], v[142:145], v[184:187], v[114:117]
	v_mfma_f32_16x16x32_bf16 v[106:109], v[62:65], v[192:195], v[106:109]
	v_mfma_f32_16x16x32_bf16 v[86:89], v[142:145], v[192:195], v[86:89]
	v_mfma_f32_16x16x32_bf16 v[134:137], v[62:65], v[226:229], v[134:137]
	v_mfma_f32_16x16x32_bf16 v[90:93], v[142:145], v[226:229], v[90:93]
	v_mfma_f32_16x16x32_bf16 v[130:133], v[62:65], v[234:237], v[130:133]
	v_mfma_f32_16x16x32_bf16 v[110:113], v[142:145], v[234:237], v[110:113]
	v_mfma_f32_16x16x32_bf16 v[94:97], v[168:171], v[184:187], v[94:97]
	v_mfma_f32_16x16x32_bf16 v[82:85], v[176:179], v[184:187], v[82:85]
	v_mfma_f32_16x16x32_bf16 v[78:81], v[168:171], v[192:195], v[78:81]
	v_mfma_f32_16x16x32_bf16 v[74:77], v[176:179], v[192:195], v[74:77]
	v_mfma_f32_16x16x32_bf16 v[126:129], v[168:171], v[226:229], v[126:129]
	v_mfma_f32_16x16x32_bf16 v[98:101], v[176:179], v[226:229], v[98:101]
	v_mfma_f32_16x16x32_bf16 v[122:125], v[168:171], v[234:237], v[122:125]
	v_mfma_f32_16x16x32_bf16 v[102:105], v[176:179], v[234:237], v[102:105]
	s_setprio 0
	s_barrier
; #define PG8_STAGE(bufoff, gbase, voff) do { const char* _gb = (const char*)(gbase); asm volatile("" : "+s"(_gb)); _Pragma("unroll") for (int _i = 0; _i < 2; ++_i) { asm volatile("" : "+v"((voff)[_i])); \
;         __builtin_amdgcn_global_load_lds((const unsigned*)(_gb + (voff)[_i]), (PG8_LAS unsigned*)(lds + (bufoff) + ldsw + _i * 8192), 16, 0, 0); } } while (0)
; #define PG8_LDA(dst, b, h) do { _Pragma("unroll") for (int m = 0; m < 4; ++m) _Pragma("unroll") for (int k = 0; k < 2; ++k) dst[m][k] = *(const PG8_LAS bf16x8*)(lds + PG8_SA(b, h) + aoff + m * 2048 + k * 1024); } while (0)
; template <class Epi, class Sched, bool ALIGN_EPI = false, bool SP2 = false>
; __device__ __forceinline__ void gemm_phase(PG8_LAS unsigned char* lds, const Gemm g, const Sched& S, const Epi& E) {
;     ...
;             PG8_LDA(At, 1, 1); PG8_STAGE(PG8_SB(1, 0), b3, voffB); PG8_STAGE(PG8_SB(1, 1), b3 + hstep, voffB); PG8_STAGE(PG8_SA(1, 0), a3, voffA);
;             PG8_WAIT_V(8); PG8_WAIT_L(0); PG8_BAR; PG8_MMA2(1); PG8_BAR; PG8_SCHED;
;             } else {
;             PG8_LDB(B0, 0, 0); PG8_SCHED; PG8_LDA(At, 0, 0); PG8_STAGE(PG8_SA(1, 1), a1 + hstep, voffA);
;             PG8_WAIT_L(8); PG8_BAR; PG8_WAIT_L(0); PG8_MMA(0, 0, At, B0); PG8_BAR; PG8_SCHED;
;             PG8_LDB(B1, 0, 1); PG8_STAGE(PG8_SB(0, 0), b2, voffB);
;             PG8_BAR; PG8_WAIT_L(0); PG8_MMA(0, 1, At, B1); PG8_BAR;
;             PG8_LDA(At, 0, 1); PG8_STAGE(PG8_SA(0, 0), a2, voffA);
;             PG8_BAR; PG8_WAIT_L(0); PG8_MMA(1, 0, At, B0); PG8_BAR; PG8_SCHED;
;             PG8_STAGE(PG8_SB(0, 1), b2 + hstep, voffB);
;             PG8_WAIT_V(6); PG8_BAR; PG8_MMA(1, 1, At, B1); PG8_BAR;
;             PG8_LDB(B0, 1, 0); PG8_SCHED; PG8_LDA(At, 1, 0); PG8_STAGE(PG8_SA(0, 1), a2 + hstep, voffA);
;             PG8_WAIT_L(8); PG8_BAR; PG8_WAIT_L(0); PG8_MMA(0, 0, At, B0); PG8_BAR; PG8_SCHED;
;             PG8_LDB(B1, 1, 1); PG8_STAGE(PG8_SB(1, 0), b3, voffB);
;             PG8_BAR; PG8_WAIT_L(0); PG8_MMA(0, 1, At, B1); PG8_BAR;
;             PG8_LDA(At, 1, 1); PG8_STAGE(PG8_SA(1, 0), a3, voffA);
;             PG8_BAR; PG8_WAIT_L(0); PG8_MMA(1, 0, At, B0); PG8_BAR; PG8_SCHED;
;             PG8_STAGE(PG8_SB(1, 1), b3 + hstep, voffB);
;             PG8_WAIT_V(6); PG8_BAR; PG8_MMA(1, 1, At, B1); PG8_BAR;
;             }
;         }
;         if constexpr (ALIGN_EPI) { if (wr == 0) PG8_BAR; }
	s_add_u32 s12, s16, 0x80
	s_addc_u32 s13, s17, 0
	s_add_i32 s18, s84, s25
	s_mov_b32 m0, s18
	ds_read_b128 v[180:183], v219 offset:49152
	ds_read_b128 v[184:187], v219 offset:50176
	ds_read_b128 v[188:191], v219 offset:51200
	ds_read_b128 v[192:195], v219 offset:52224
	ds_read_b128 v[222:225], v219 offset:53248
	ds_read_b128 v[226:229], v219 offset:54272
	ds_read_b128 v[230:233], v219 offset:55296
	ds_read_b128 v[234:237], v219 offset:56320
	s_nop 0
	global_load_lds_dwordx4 v198, s[12:13]
	s_add_i32 m0, s18, 0x2000
	s_nop 0
	global_load_lds_dwordx4 v200, s[12:13]
	s_add_u32 s12, s16, 0x100080
	s_addc_u32 s13, s17, 0
	s_add_i32 s16, s85, s25
	s_mov_b32 m0, s16
	s_nop 0
	global_load_lds_dwordx4 v198, s[12:13]
	s_add_i32 m0, s16, 0x2000
	s_nop 0
	global_load_lds_dwordx4 v200, s[12:13]
	s_mov_b32 m0, s71
	s_nop 0
	global_load_lds_dwordx4 v1, s[2:3]
	s_mov_b32 m0, s72
	s_nop 0
	global_load_lds_dwordx4 v199, s[2:3]
	s_waitcnt vmcnt(8)
	s_waitcnt lgkmcnt(0)
	s_setprio 1
	s_waitcnt lgkmcnt(0)
	s_barrier
	v_mfma_f32_16x16x32_bf16 v[6:9], v[58:61], v[230:233], v[6:9]
	v_mfma_f32_16x16x32_bf16 v[34:37], v[58:61], v[180:183], v[34:37]
	v_mfma_f32_16x16x32_bf16 v[26:29], v[58:61], v[188:191], v[26:29]
	v_mfma_f32_16x16x32_bf16 v[70:73], v[58:61], v[222:225], v[70:73]
	v_mfma_f32_16x16x32_bf16 v[58:61], v[62:65], v[234:237], v[6:9]
	v_mfma_f32_16x16x32_bf16 v[6:9], v[138:141], v[230:233], v[50:53]
	v_mfma_f32_16x16x32_bf16 v[50:53], v[142:145], v[234:237], v[6:9]
	v_mfma_f32_16x16x32_bf16 v[6:9], v[164:167], v[180:183], v[18:21]
	v_mfma_f32_16x16x32_bf16 v[18:21], v[168:171], v[184:187], v[6:9]
	v_mfma_f32_16x16x32_bf16 v[6:9], v[172:175], v[180:183], v[14:17]
	v_mfma_f32_16x16x32_bf16 v[14:17], v[176:179], v[184:187], v[6:9]
	v_mfma_f32_16x16x32_bf16 v[6:9], v[164:167], v[188:191], v[10:13]
	v_mfma_f32_16x16x32_bf16 v[10:13], v[168:171], v[192:195], v[6:9]
	v_mfma_f32_16x16x32_bf16 v[6:9], v[164:167], v[222:225], v[54:57]
	v_mfma_f32_16x16x32_bf16 v[54:57], v[168:171], v[226:229], v[6:9]
	v_mfma_f32_16x16x32_bf16 v[6:9], v[172:175], v[222:225], v[46:49]
	v_mfma_f32_16x16x32_bf16 v[46:49], v[176:179], v[226:229], v[6:9]
	v_mfma_f32_16x16x32_bf16 v[6:9], v[164:167], v[230:233], v[42:45]
	v_mfma_f32_16x16x32_bf16 v[30:33], v[138:141], v[180:183], v[30:33]
	v_mfma_f32_16x16x32_bf16 v[22:25], v[138:141], v[188:191], v[22:25]
	v_mfma_f32_16x16x32_bf16 v[66:69], v[138:141], v[222:225], v[66:69]
	v_mfma_f32_16x16x32_bf16 v[2:5], v[172:175], v[188:191], v[2:5]
	v_mfma_f32_16x16x32_bf16 v[42:45], v[168:171], v[234:237], v[6:9]
	v_mfma_f32_16x16x32_bf16 v[6:9], v[172:175], v[230:233], v[38:41]
	v_mfma_f32_16x16x32_bf16 v[34:37], v[62:65], v[184:187], v[34:37]
	v_mfma_f32_16x16x32_bf16 v[30:33], v[142:145], v[184:187], v[30:33]
	v_mfma_f32_16x16x32_bf16 v[26:29], v[62:65], v[192:195], v[26:29]
	v_mfma_f32_16x16x32_bf16 v[22:25], v[142:145], v[192:195], v[22:25]
	v_mfma_f32_16x16x32_bf16 v[70:73], v[62:65], v[226:229], v[70:73]
	v_mfma_f32_16x16x32_bf16 v[66:69], v[142:145], v[226:229], v[66:69]
	v_mfma_f32_16x16x32_bf16 v[2:5], v[176:179], v[192:195], v[2:5]
	v_mfma_f32_16x16x32_bf16 v[38:41], v[176:179], v[234:237], v[6:9]
	s_setprio 0
	s_barrier
	s_add_i32 s83, s83, 2
	s_add_u32 s62, s62, 0x100
	s_addc_u32 s63, s63, 0
	s_cmp_gt_u32 s83, 61
	s_mov_b64 s[12:13], s[14:15]
	s_cbranch_scc0 .LBB0_933
	s_and_b64 vcc, exec, s[38:39]
	s_cbranch_vccz .LBB0_936
	s_barrier

; #define PG8_STAGE(bufoff, gbase, voff) do { const char* _gb = (const char*)(gbase); asm volatile("" : "+s"(_gb)); _Pragma("unroll") for (int _i = 0; _i < 2; ++_i) { asm volatile("" : "+v"((voff)[_i])); \
;         __builtin_amdgcn_global_load_lds((const unsigned*)(_gb + (voff)[_i]), (PG8_LAS unsigned*)(lds + (bufoff) + ldsw + _i * 8192), 16, 0, 0); } } while (0)
; #define PG8_LDA(dst, b, h) do { _Pragma("unroll") for (int m = 0; m < 4; ++m) _Pragma("unroll") for (int k = 0; k < 2; ++k) dst[m][k] = *(const PG8_LAS bf16x8*)(lds + PG8_SA(b, h) + aoff + m * 2048 + k * 1024); } while (0)
; #define PG8_LDB(dst, b, h) do { _Pragma("unroll") for (int n = 0; n < 2; ++n) _Pragma("unroll") for (int k = 0; k < 2; ++k) dst[n][k] = *(const PG8_LAS bf16x8*)(lds + PG8_SB(b, h) + boff + n * 2048 + k * 1024); } while (0)
; #define PG8_WAIT_V(n) asm volatile("s_waitcnt vmcnt(" #n ")" ::: "memory")
; #define PG8_WAIT_L(n) asm volatile("s_waitcnt lgkmcnt(" #n ")" ::: "memory")
; #define PG8_BAR __builtin_amdgcn_s_barrier()
; #define PG8_SCHED __builtin_amdgcn_sched_barrier(0)
; #define PG8_STAGE(bufoff, gbase, voff) do { const char* _gb = (const char*)(gbase); asm volatile("" : "+s"(_gb)); _Pragma("unroll") for (int _i = 0; _i < 2; ++_i) { asm volatile("" : "+v"((voff)[_i])); \
;         __builtin_amdgcn_global_load_lds((const unsigned*)(_gb + (voff)[_i]), (PG8_LAS unsigned*)(lds + (bufoff) + ldsw + _i * 8192), 16, 0, 0); } } while (0)
; #define PG8_LDA(dst, b, h) do { _Pragma("unroll") for (int m = 0; m < 4; ++m) _Pragma("unroll") for (int k = 0; k < 2; ++k) dst[m][k] = *(const PG8_LAS bf16x8*)(lds + PG8_SA(b, h) + aoff + m * 2048 + k * 1024); } while (0)
; #define PG8_WAIT_V(n) asm volatile("s_waitcnt vmcnt(" #n ")" ::: "memory")
; template <class Epi, class Sched, bool ALIGN_EPI = false, bool SP2 = false>
; __device__ __forceinline__ void gemm_phase(PG8_LAS unsigned char* lds, const Gemm g, const Sched& S, const Epi& E) {
;     ...
;             PG8_LDB(B0, 0, 0); PG8_LDB(B1, 0, 1); PG8_SCHED; PG8_LDA(At, 0, 0); PG8_STAGE(PG8_SA(1, 1), a1 + hstep, voffA);
;             PG8_WAIT_V(8); PG8_WAIT_L(0); PG8_BAR; PG8_MMA2(0); PG8_BAR; PG8_SCHED;
;             PG8_LDA(At, 0, 1); PG8_STAGE(PG8_SB(0, 0), b2, voffB); PG8_STAGE(PG8_SB(0, 1), b2 + hstep, voffB); PG8_STAGE(PG8_SA(0, 0), a2, voffA);
;             PG8_WAIT_V(8); PG8_WAIT_L(0); PG8_BAR; PG8_MMA2(1); PG8_BAR; PG8_SCHED;
.LBB0_1125:
	ds_read_b128 v[130:133], v162
	ds_read_b128 v[134:137], v162 offset:1024
	ds_read_b128 v[138:141], v162 offset:2048
	ds_read_b128 v[142:145], v162 offset:3072
	ds_read_b128 v[150:153], v163
	ds_read_b128 v[166:169], v163 offset:1024
	ds_read_b128 v[170:173], v163 offset:2048
	ds_read_b128 v[174:177], v163 offset:3072
	s_add_u32 s20, s16, 0x100
	s_addc_u32 s21, s17, 0
	s_cmpk_eq_i32 s53, 0xbc
	s_cselect_b32 s26, s6, s20
	s_cselect_b32 s27, s7, s21
	s_cselect_b32 s24, s18, s51
	s_cselect_b32 s25, s19, s52
	s_add_u32 s2, s26, 0x80
	s_addc_u32 s3, s27, 0
	s_add_u32 s16, s16, 0x300080
	s_addc_u32 s17, s17, 0
	s_add_i32 m0, s34, 0xc000
	ds_read_b128 v[178:181], v164
	ds_read_b128 v[182:185], v164 offset:1024
	ds_read_b128 v[186:189], v164 offset:2048
	ds_read_b128 v[190:193], v164 offset:3072
	ds_read_b128 v[194:197], v164 offset:4096
	ds_read_b128 v[198:201], v164 offset:5120
	ds_read_b128 v[202:205], v164 offset:6144
	ds_read_b128 v[206:209], v164 offset:7168
	s_nop 0
	global_load_lds_dwordx4 v1, s[16:17]
	s_add_i32 m0, s34, 0xe000
	s_nop 0
	global_load_lds_dwordx4 v157, s[16:17]
	s_waitcnt vmcnt(8)
	s_waitcnt lgkmcnt(0)
	s_setprio 1
	s_waitcnt lgkmcnt(0)
	s_barrier
	v_mfma_f32_16x16x32_bf16 v[126:129], v[130:133], v[178:181], v[126:129]
	v_mfma_f32_16x16x32_bf16 v[122:125], v[138:141], v[178:181], v[122:125]
	v_mfma_f32_16x16x32_bf16 v[110:113], v[130:133], v[186:189], v[110:113]
	v_mfma_f32_16x16x32_bf16 v[106:109], v[138:141], v[186:189], v[106:109]
	v_mfma_f32_16x16x32_bf16 v[94:97], v[130:133], v[194:197], v[94:97]
	v_mfma_f32_16x16x32_bf16 v[90:93], v[138:141], v[194:197], v[90:93]
	v_mfma_f32_16x16x32_bf16 v[78:81], v[130:133], v[202:205], v[78:81]
	v_mfma_f32_16x16x32_bf16 v[74:77], v[138:141], v[202:205], v[74:77]
	v_mfma_f32_16x16x32_bf16 v[118:121], v[150:153], v[178:181], v[118:121]
	v_mfma_f32_16x16x32_bf16 v[114:117], v[170:173], v[178:181], v[114:117]
	v_mfma_f32_16x16x32_bf16 v[102:105], v[150:153], v[186:189], v[102:105]
	v_mfma_f32_16x16x32_bf16 v[98:101], v[170:173], v[186:189], v[98:101]
	v_mfma_f32_16x16x32_bf16 v[86:89], v[150:153], v[194:197], v[86:89]
	v_mfma_f32_16x16x32_bf16 v[82:85], v[170:173], v[194:197], v[82:85]
	v_mfma_f32_16x16x32_bf16 v[70:73], v[150:153], v[202:205], v[70:73]
	v_mfma_f32_16x16x32_bf16 v[66:69], v[170:173], v[202:205], v[66:69]
	v_mfma_f32_16x16x32_bf16 v[126:129], v[134:137], v[182:185], v[126:129]
	v_mfma_f32_16x16x32_bf16 v[122:125], v[142:145], v[182:185], v[122:125]
	v_mfma_f32_16x16x32_bf16 v[110:113], v[134:137], v[190:193], v[110:113]
	v_mfma_f32_16x16x32_bf16 v[106:109], v[142:145], v[190:193], v[106:109]
	v_mfma_f32_16x16x32_bf16 v[94:97], v[134:137], v[198:201], v[94:97]
	v_mfma_f32_16x16x32_bf16 v[90:93], v[142:145], v[198:201], v[90:93]
	v_mfma_f32_16x16x32_bf16 v[78:81], v[134:137], v[206:209], v[78:81]
	v_mfma_f32_16x16x32_bf16 v[74:77], v[142:145], v[206:209], v[74:77]
	v_mfma_f32_16x16x32_bf16 v[118:121], v[166:169], v[182:185], v[118:121]
	v_mfma_f32_16x16x32_bf16 v[114:117], v[174:177], v[182:185], v[114:117]
	v_mfma_f32_16x16x32_bf16 v[102:105], v[166:169], v[190:193], v[102:105]
	v_mfma_f32_16x16x32_bf16 v[98:101], v[174:177], v[190:193], v[98:101]
	v_mfma_f32_16x16x32_bf16 v[86:89], v[166:169], v[198:201], v[86:89]
	v_mfma_f32_16x16x32_bf16 v[82:85], v[174:177], v[198:201], v[82:85]
	v_mfma_f32_16x16x32_bf16 v[70:73], v[166:169], v[206:209], v[70:73]
	v_mfma_f32_16x16x32_bf16 v[66:69], v[174:177], v[206:209], v[66:69]
	s_setprio 0
	s_barrier
	s_add_i32 s54, s43, s33
	s_mov_b64 s[16:17], s[24:25]
	s_mov_b32 m0, s54
	ds_read_b128 v[178:181], v164 offset:16384
	ds_read_b128 v[182:185], v164 offset:17408
	ds_read_b128 v[186:189], v164 offset:18432
	ds_read_b128 v[190:193], v164 offset:19456
	ds_read_b128 v[194:197], v164 offset:20480
	ds_read_b128 v[198:201], v164 offset:21504
	ds_read_b128 v[202:205], v164 offset:22528
	ds_read_b128 v[206:209], v164 offset:23552
	s_nop 0
	global_load_lds_dwordx4 v156, s[16:17]
	s_add_i32 m0, s54, 0x2000
	s_nop 0
	global_load_lds_dwordx4 v158, s[16:17]
	s_add_u32 s16, s24, 0x300000
	s_addc_u32 s17, s25, 0
	s_add_i32 s54, s44, s33
	s_mov_b32 m0, s54
	s_nop 0
	global_load_lds_dwordx4 v156, s[16:17]
	s_add_i32 m0, s54, 0x2000
	s_nop 0
	global_load_lds_dwordx4 v158, s[16:17]
	s_mov_b64 s[16:17], s[26:27]
	s_mov_b32 m0, s34
	s_nop 0
	global_load_lds_dwordx4 v1, s[16:17]
	s_mov_b32 m0, s35
	s_nop 0
	global_load_lds_dwordx4 v157, s[16:17]
	s_waitcnt vmcnt(8)
	s_waitcnt lgkmcnt(0)
	s_setprio 1
	s_waitcnt lgkmcnt(0)
	s_barrier
	v_mfma_f32_16x16x32_bf16 v[62:65], v[130:133], v[178:181], v[62:65]
	v_mfma_f32_16x16x32_bf16 v[58:61], v[138:141], v[178:181], v[58:61]
	v_mfma_f32_16x16x32_bf16 v[46:49], v[130:133], v[186:189], v[46:49]
	v_mfma_f32_16x16x32_bf16 v[42:45], v[138:141], v[186:189], v[42:45]
	v_mfma_f32_16x16x32_bf16 v[30:33], v[130:133], v[194:197], v[30:33]
	v_mfma_f32_16x16x32_bf16 v[26:29], v[138:141], v[194:197], v[26:29]
	v_mfma_f32_16x16x32_bf16 v[14:17], v[130:133], v[202:205], v[14:17]
	v_mfma_f32_16x16x32_bf16 v[10:13], v[138:141], v[202:205], v[10:13]
	v_mfma_f32_16x16x32_bf16 v[54:57], v[150:153], v[178:181], v[54:57]
	v_mfma_f32_16x16x32_bf16 v[50:53], v[170:173], v[178:181], v[50:53]
	v_mfma_f32_16x16x32_bf16 v[38:41], v[150:153], v[186:189], v[38:41]
	v_mfma_f32_16x16x32_bf16 v[34:37], v[170:173], v[186:189], v[34:37]
	v_mfma_f32_16x16x32_bf16 v[22:25], v[150:153], v[194:197], v[22:25]
	v_mfma_f32_16x16x32_bf16 v[18:21], v[170:173], v[194:197], v[18:21]
	v_mfma_f32_16x16x32_bf16 v[6:9], v[150:153], v[202:205], v[6:9]
	v_mfma_f32_16x16x32_bf16 v[2:5], v[170:173], v[202:205], v[2:5]
	v_mfma_f32_16x16x32_bf16 v[62:65], v[134:137], v[182:185], v[62:65]
	v_mfma_f32_16x16x32_bf16 v[58:61], v[142:145], v[182:185], v[58:61]
	v_mfma_f32_16x16x32_bf16 v[46:49], v[134:137], v[190:193], v[46:49]
	v_mfma_f32_16x16x32_bf16 v[42:45], v[142:145], v[190:193], v[42:45]
	v_mfma_f32_16x16x32_bf16 v[30:33], v[134:137], v[198:201], v[30:33]
	v_mfma_f32_16x16x32_bf16 v[26:29], v[142:145], v[198:201], v[26:29]
	v_mfma_f32_16x16x32_bf16 v[14:17], v[134:137], v[206:209], v[14:17]
	v_mfma_f32_16x16x32_bf16 v[10:13], v[142:145], v[206:209], v[10:13]
	v_mfma_f32_16x16x32_bf16 v[54:57], v[166:169], v[182:185], v[54:57]
	v_mfma_f32_16x16x32_bf16 v[50:53], v[174:177], v[182:185], v[50:53]
	v_mfma_f32_16x16x32_bf16 v[38:41], v[166:169], v[190:193], v[38:41]
	v_mfma_f32_16x16x32_bf16 v[34:37], v[174:177], v[190:193], v[34:37]
	v_mfma_f32_16x16x32_bf16 v[22:25], v[166:169], v[198:201], v[22:25]
	v_mfma_f32_16x16x32_bf16 v[18:21], v[174:177], v[198:201], v[18:21]
	v_mfma_f32_16x16x32_bf16 v[6:9], v[166:169], v[206:209], v[6:9]
	v_mfma_f32_16x16x32_bf16 v[2:5], v[174:177], v[206:209], v[2:5]
	s_setprio 0
	s_barrier
; #define PG8_STAGE(bufoff, gbase, voff) do { const char* _gb = (const char*)(gbase); asm volatile("" : "+s"(_gb)); _Pragma("unroll") for (int _i = 0; _i < 2; ++_i) { asm volatile("" : "+v"((voff)[_i])); \
;         __builtin_amdgcn_global_load_lds((const unsigned*)(_gb + (voff)[_i]), (PG8_LAS unsigned*)(lds + (bufoff) + ldsw + _i * 8192), 16, 0, 0); } } while (0)
; template <class Epi, class Sched, bool ALIGN_EPI = false, bool SP2 = false>
; __device__ __forceinline__ void gemm_phase(PG8_LAS unsigned char* lds, const Gemm g, const Sched& S, const Epi& E) {
;     ...
;             PG8_LDB(B0, 1, 0); PG8_LDB(B1, 1, 1); PG8_SCHED; PG8_LDA(At, 1, 0); PG8_STAGE(PG8_SA(0, 1), a2 + hstep, voffA);
;             PG8_WAIT_V(8); PG8_WAIT_L(0); PG8_BAR; PG8_MMA2(0); PG8_BAR; PG8_SCHED;
;             PG8_LDA(At, 1, 1); PG8_STAGE(PG8_SB(1, 0), b3, voffB); PG8_STAGE(PG8_SB(1, 1), b3 + hstep, voffB); PG8_STAGE(PG8_SA(1, 0), a3, voffA);
;             PG8_WAIT_V(8); PG8_WAIT_L(0); PG8_BAR; PG8_MMA2(1); PG8_BAR; PG8_SCHED;
;             } else {
;             PG8_LDB(B0, 0, 0); PG8_SCHED; PG8_LDA(At, 0, 0); PG8_STAGE(PG8_SA(1, 1), a1 + hstep, voffA);
;             PG8_WAIT_L(8); PG8_BAR; PG8_WAIT_L(0); PG8_MMA(0, 0, At, B0); PG8_BAR; PG8_SCHED;
;             PG8_LDB(B1, 0, 1); PG8_STAGE(PG8_SB(0, 0), b2, voffB);
;             PG8_BAR; PG8_WAIT_L(0); PG8_MMA(0, 1, At, B1); PG8_BAR;
;             PG8_LDA(At, 0, 1); PG8_STAGE(PG8_SA(0, 0), a2, voffA);
;             PG8_BAR; PG8_WAIT_L(0); PG8_MMA(1, 0, At, B0); PG8_BAR; PG8_SCHED;
;             PG8_STAGE(PG8_SB(0, 1), b2 + hstep, voffB);
;             PG8_WAIT_V(6); PG8_BAR; PG8_MMA(1, 1, At, B1); PG8_BAR;
;             PG8_LDB(B0, 1, 0); PG8_SCHED; PG8_LDA(At, 1, 0); PG8_STAGE(PG8_SA(0, 1), a2 + hstep, voffA);
;             PG8_WAIT_L(8); PG8_BAR; PG8_WAIT_L(0); PG8_MMA(0, 0, At, B0); PG8_BAR; PG8_SCHED;
;             PG8_LDB(B1, 1, 1); PG8_STAGE(PG8_SB(1, 0), b3, voffB);
;             PG8_BAR; PG8_WAIT_L(0); PG8_MMA(0, 1, At, B1); PG8_BAR;
;             PG8_LDA(At, 1, 1); PG8_STAGE(PG8_SA(1, 0), a3, voffA);
;             PG8_BAR; PG8_WAIT_L(0); PG8_MMA(1, 0, At, B0); PG8_BAR; PG8_SCHED;
;             PG8_STAGE(PG8_SB(1, 1), b3 + hstep, voffB);
;             PG8_WAIT_V(6); PG8_BAR; PG8_MMA(1, 1, At, B1); PG8_BAR;
;             }
;         }
;         if constexpr (ALIGN_EPI) { if (wr == 0) PG8_BAR; }
	s_add_i32 s54, 0, 0x18000
	s_add_i32 s55, 0, 0x1c000
	v_add_u32_e32 v142, s54, v160
	v_add_u32_e32 v154, s55, v160
	ds_read_b128 v[130:133], v142
	ds_read_b128 v[134:137], v142 offset:1024
	ds_read_b128 v[138:141], v142 offset:2048
	ds_read_b128 v[142:145], v142 offset:3072
	ds_read_b128 v[150:153], v154
	ds_read_b128 v[166:169], v154 offset:1024
	ds_read_b128 v[170:173], v154 offset:2048
	ds_read_b128 v[174:177], v154 offset:3072
	s_add_u32 s16, s26, 0x300000
	s_addc_u32 s17, s27, 0
	s_mov_b32 m0, s36
	ds_read_b128 v[178:181], v164 offset:32768
	ds_read_b128 v[182:185], v164 offset:33792
	ds_read_b128 v[186:189], v164 offset:34816
	ds_read_b128 v[190:193], v164 offset:35840
	ds_read_b128 v[194:197], v164 offset:36864
	ds_read_b128 v[198:201], v164 offset:37888
	ds_read_b128 v[202:205], v164 offset:38912
	ds_read_b128 v[206:209], v164 offset:39936
	s_nop 0
	global_load_lds_dwordx4 v1, s[16:17]
	s_mov_b32 m0, s37
	s_nop 0
	global_load_lds_dwordx4 v157, s[16:17]
	s_waitcnt vmcnt(8)
	s_waitcnt lgkmcnt(0)
	s_setprio 1
	s_waitcnt lgkmcnt(0)
	s_barrier
	v_mfma_f32_16x16x32_bf16 v[126:129], v[130:133], v[178:181], v[126:129]
	v_mfma_f32_16x16x32_bf16 v[122:125], v[138:141], v[178:181], v[122:125]
	v_mfma_f32_16x16x32_bf16 v[110:113], v[130:133], v[186:189], v[110:113]
	v_mfma_f32_16x16x32_bf16 v[106:109], v[138:141], v[186:189], v[106:109]
	v_mfma_f32_16x16x32_bf16 v[94:97], v[130:133], v[194:197], v[94:97]
	v_mfma_f32_16x16x32_bf16 v[90:93], v[138:141], v[194:197], v[90:93]
	v_mfma_f32_16x16x32_bf16 v[78:81], v[130:133], v[202:205], v[78:81]
	v_mfma_f32_16x16x32_bf16 v[74:77], v[138:141], v[202:205], v[74:77]
	v_mfma_f32_16x16x32_bf16 v[118:121], v[150:153], v[178:181], v[118:121]
	v_mfma_f32_16x16x32_bf16 v[114:117], v[170:173], v[178:181], v[114:117]
	v_mfma_f32_16x16x32_bf16 v[102:105], v[150:153], v[186:189], v[102:105]
	v_mfma_f32_16x16x32_bf16 v[98:101], v[170:173], v[186:189], v[98:101]
	v_mfma_f32_16x16x32_bf16 v[86:89], v[150:153], v[194:197], v[86:89]
	v_mfma_f32_16x16x32_bf16 v[82:85], v[170:173], v[194:197], v[82:85]
	v_mfma_f32_16x16x32_bf16 v[70:73], v[150:153], v[202:205], v[70:73]
	v_mfma_f32_16x16x32_bf16 v[66:69], v[170:173], v[202:205], v[66:69]
	v_mfma_f32_16x16x32_bf16 v[126:129], v[134:137], v[182:185], v[126:129]
	v_mfma_f32_16x16x32_bf16 v[122:125], v[142:145], v[182:185], v[122:125]
	v_mfma_f32_16x16x32_bf16 v[110:113], v[134:137], v[190:193], v[110:113]
	v_mfma_f32_16x16x32_bf16 v[106:109], v[142:145], v[190:193], v[106:109]
	v_mfma_f32_16x16x32_bf16 v[94:97], v[134:137], v[198:201], v[94:97]
	v_mfma_f32_16x16x32_bf16 v[90:93], v[142:145], v[198:201], v[90:93]
	v_mfma_f32_16x16x32_bf16 v[78:81], v[134:137], v[206:209], v[78:81]
	v_mfma_f32_16x16x32_bf16 v[74:77], v[142:145], v[206:209], v[74:77]
	v_mfma_f32_16x16x32_bf16 v[118:121], v[166:169], v[182:185], v[118:121]
	v_mfma_f32_16x16x32_bf16 v[114:117], v[174:177], v[182:185], v[114:117]
	v_mfma_f32_16x16x32_bf16 v[102:105], v[166:169], v[190:193], v[102:105]
	v_mfma_f32_16x16x32_bf16 v[98:101], v[174:177], v[190:193], v[98:101]
	v_mfma_f32_16x16x32_bf16 v[86:89], v[166:169], v[198:201], v[86:89]
	v_mfma_f32_16x16x32_bf16 v[82:85], v[174:177], v[198:201], v[82:85]
	v_mfma_f32_16x16x32_bf16 v[70:73], v[166:169], v[206:209], v[70:73]
	v_mfma_f32_16x16x32_bf16 v[66:69], v[174:177], v[206:209], v[66:69]
	s_setprio 0
	s_barrier
	s_add_u32 s16, s24, 0x80
	s_addc_u32 s17, s25, 0
	s_add_i32 s26, s54, s33
	s_mov_b32 m0, s26
	ds_read_b128 v[178:181], v164 offset:49152
	ds_read_b128 v[182:185], v164 offset:50176
	ds_read_b128 v[186:189], v164 offset:51200
	ds_read_b128 v[190:193], v164 offset:52224
	ds_read_b128 v[194:197], v164 offset:53248
	ds_read_b128 v[198:201], v164 offset:54272
	ds_read_b128 v[202:205], v164 offset:55296
	ds_read_b128 v[206:209], v164 offset:56320
	s_nop 0
	global_load_lds_dwordx4 v156, s[16:17]
	s_add_i32 m0, s26, 0x2000
	s_nop 0
	global_load_lds_dwordx4 v158, s[16:17]
	s_add_u32 s16, s24, 0x300080
	s_addc_u32 s17, s25, 0
	s_add_i32 s24, s55, s33
	s_mov_b32 m0, s24
	s_nop 0
	global_load_lds_dwordx4 v156, s[16:17]
	s_add_i32 m0, s24, 0x2000
	s_nop 0
	global_load_lds_dwordx4 v158, s[16:17]
	s_mov_b32 m0, s39
	s_nop 0
	global_load_lds_dwordx4 v1, s[2:3]
	s_mov_b32 m0, s40
	s_nop 0
	global_load_lds_dwordx4 v157, s[2:3]
	s_waitcnt vmcnt(8)
	s_waitcnt lgkmcnt(0)
	s_setprio 1
	s_waitcnt lgkmcnt(0)
	s_barrier
	v_mfma_f32_16x16x32_bf16 v[62:65], v[130:133], v[178:181], v[62:65]
	v_mfma_f32_16x16x32_bf16 v[58:61], v[138:141], v[178:181], v[58:61]
	v_mfma_f32_16x16x32_bf16 v[46:49], v[130:133], v[186:189], v[46:49]
	v_mfma_f32_16x16x32_bf16 v[42:45], v[138:141], v[186:189], v[42:45]
	v_mfma_f32_16x16x32_bf16 v[30:33], v[130:133], v[194:197], v[30:33]
	v_mfma_f32_16x16x32_bf16 v[26:29], v[138:141], v[194:197], v[26:29]
	v_mfma_f32_16x16x32_bf16 v[14:17], v[130:133], v[202:205], v[14:17]
	v_mfma_f32_16x16x32_bf16 v[10:13], v[138:141], v[202:205], v[10:13]
	v_mfma_f32_16x16x32_bf16 v[54:57], v[150:153], v[178:181], v[54:57]
	v_mfma_f32_16x16x32_bf16 v[50:53], v[170:173], v[178:181], v[50:53]
	v_mfma_f32_16x16x32_bf16 v[38:41], v[150:153], v[186:189], v[38:41]
	v_mfma_f32_16x16x32_bf16 v[34:37], v[170:173], v[186:189], v[34:37]
	v_mfma_f32_16x16x32_bf16 v[22:25], v[150:153], v[194:197], v[22:25]
	v_mfma_f32_16x16x32_bf16 v[18:21], v[170:173], v[194:197], v[18:21]
	v_mfma_f32_16x16x32_bf16 v[6:9], v[150:153], v[202:205], v[6:9]
	v_mfma_f32_16x16x32_bf16 v[2:5], v[170:173], v[202:205], v[2:5]
	v_mfma_f32_16x16x32_bf16 v[62:65], v[134:137], v[182:185], v[62:65]
	v_mfma_f32_16x16x32_bf16 v[58:61], v[142:145], v[182:185], v[58:61]
	v_mfma_f32_16x16x32_bf16 v[46:49], v[134:137], v[190:193], v[46:49]
	v_mfma_f32_16x16x32_bf16 v[42:45], v[142:145], v[190:193], v[42:45]
	v_mfma_f32_16x16x32_bf16 v[30:33], v[134:137], v[198:201], v[30:33]
	v_mfma_f32_16x16x32_bf16 v[26:29], v[142:145], v[198:201], v[26:29]
	v_mfma_f32_16x16x32_bf16 v[14:17], v[134:137], v[206:209], v[14:17]
	v_mfma_f32_16x16x32_bf16 v[10:13], v[142:145], v[206:209], v[10:13]
	v_mfma_f32_16x16x32_bf16 v[54:57], v[166:169], v[182:185], v[54:57]
	v_mfma_f32_16x16x32_bf16 v[50:53], v[174:177], v[182:185], v[50:53]
	v_mfma_f32_16x16x32_bf16 v[38:41], v[166:169], v[190:193], v[38:41]
	v_mfma_f32_16x16x32_bf16 v[34:37], v[174:177], v[190:193], v[34:37]
	v_mfma_f32_16x16x32_bf16 v[22:25], v[166:169], v[198:201], v[22:25]
	v_mfma_f32_16x16x32_bf16 v[18:21], v[174:177], v[198:201], v[18:21]
	v_mfma_f32_16x16x32_bf16 v[6:9], v[166:169], v[206:209], v[6:9]
	v_mfma_f32_16x16x32_bf16 v[2:5], v[174:177], v[206:209], v[2:5]
	s_setprio 0
	s_barrier
	s_add_i32 s53, s53, 2
	s_add_u32 s51, s51, 0x100
	s_addc_u32 s52, s52, 0
	s_cmpk_gt_u32 s53, 0xbd
	s_mov_b64 s[16:17], s[20:21]
	s_cbranch_scc0 .LBB0_1125
	s_and_b64 vcc, exec, s[14:15]
	s_cbranch_vccz .LBB0_1128
	s_barrier

; #define PG8_STAGE(bufoff, gbase, voff) do { const char* _gb = (const char*)(gbase); asm volatile("" : "+s"(_gb)); _Pragma("unroll") for (int _i = 0; _i < 2; ++_i) { asm volatile("" : "+v"((voff)[_i])); \
;         __builtin_amdgcn_global_load_lds((const unsigned*)(_gb + (voff)[_i]), (PG8_LAS unsigned*)(lds + (bufoff) + ldsw + _i * 8192), 16, 0, 0); } } while (0)
; #define PG8_LDA(dst, b, h) do { _Pragma("unroll") for (int m = 0; m < 4; ++m) _Pragma("unroll") for (int k = 0; k < 2; ++k) dst[m][k] = *(const PG8_LAS bf16x8*)(lds + PG8_SA(b, h) + aoff + m * 2048 + k * 1024); } while (0)
; #define PG8_LDB(dst, b, h) do { _Pragma("unroll") for (int n = 0; n < 2; ++n) _Pragma("unroll") for (int k = 0; k < 2; ++k) dst[n][k] = *(const PG8_LAS bf16x8*)(lds + PG8_SB(b, h) + boff + n * 2048 + k * 1024); } while (0)
; #define PG8_WAIT_V(n) asm volatile("s_waitcnt vmcnt(" #n ")" ::: "memory")
; #define PG8_WAIT_L(n) asm volatile("s_waitcnt lgkmcnt(" #n ")" ::: "memory")
; #define PG8_BAR __builtin_amdgcn_s_barrier()
; #define PG8_SCHED __builtin_amdgcn_sched_barrier(0)
; #define PG8_STAGE(bufoff, gbase, voff) do { const char* _gb = (const char*)(gbase); asm volatile("" : "+s"(_gb)); _Pragma("unroll") for (int _i = 0; _i < 2; ++_i) { asm volatile("" : "+v"((voff)[_i])); \
;         __builtin_amdgcn_global_load_lds((const unsigned*)(_gb + (voff)[_i]), (PG8_LAS unsigned*)(lds + (bufoff) + ldsw + _i * 8192), 16, 0, 0); } } while (0)
; #define PG8_LDA(dst, b, h) do { _Pragma("unroll") for (int m = 0; m < 4; ++m) _Pragma("unroll") for (int k = 0; k < 2; ++k) dst[m][k] = *(const PG8_LAS bf16x8*)(lds + PG8_SA(b, h) + aoff + m * 2048 + k * 1024); } while (0)
; #define PG8_WAIT_V(n) asm volatile("s_waitcnt vmcnt(" #n ")" ::: "memory")
; template <class Epi, class Sched, bool ALIGN_EPI = false, bool SP2 = false>
; __device__ __forceinline__ void gemm_phase(PG8_LAS unsigned char* lds, const Gemm g, const Sched& S, const Epi& E) {
;     ...
;             PG8_LDB(B0, 0, 0); PG8_LDB(B1, 0, 1); PG8_SCHED; PG8_LDA(At, 0, 0); PG8_STAGE(PG8_SA(1, 1), a1 + hstep, voffA);
;             PG8_WAIT_V(8); PG8_WAIT_L(0); PG8_BAR; PG8_MMA2(0); PG8_BAR; PG8_SCHED;
;             PG8_LDA(At, 0, 1); PG8_STAGE(PG8_SB(0, 0), b2, voffB); PG8_STAGE(PG8_SB(0, 1), b2 + hstep, voffB); PG8_STAGE(PG8_SA(0, 0), a2, voffA);
;             PG8_WAIT_V(8); PG8_WAIT_L(0); PG8_BAR; PG8_MMA2(1); PG8_BAR; PG8_SCHED;
.LBB0_1217:
	ds_read_b128 v[128:131], v175
	ds_read_b128 v[132:135], v175 offset:1024
	ds_read_b128 v[136:139], v175 offset:2048
	ds_read_b128 v[140:143], v175 offset:3072
	ds_read_b128 v[152:155], v176
	ds_read_b128 v[156:159], v176 offset:1024
	ds_read_b128 v[160:163], v176 offset:2048
	ds_read_b128 v[184:187], v176 offset:3072
	s_add_u32 s28, s6, 0x100
	s_addc_u32 s29, s7, 0
	s_cmpk_eq_i32 s58, 0xbc
	s_cselect_b32 s36, s57, s28
	s_cselect_b32 s37, s56, s29
	s_cselect_b32 s34, s8, s4
	s_cselect_b32 s35, s9, s5
	s_add_u32 s30, s36, 0x80
	s_addc_u32 s31, s37, 0
	s_add_u32 s6, s6, 0x300080
	s_addc_u32 s7, s7, 0
	s_add_i32 m0, s41, 0xc000
	ds_read_b128 v[188:191], v177
	ds_read_b128 v[192:195], v177 offset:1024
	ds_read_b128 v[196:199], v177 offset:2048
	ds_read_b128 v[200:203], v177 offset:3072
	ds_read_b128 v[204:207], v177 offset:4096
	ds_read_b128 v[208:211], v177 offset:5120
	ds_read_b128 v[212:215], v177 offset:6144
	ds_read_b128 v[216:219], v177 offset:7168
	s_nop 0
	global_load_lds_dwordx4 v167, s[6:7]
	s_add_i32 m0, s41, 0xe000
	s_nop 0
	global_load_lds_dwordx4 v171, s[6:7]
	s_waitcnt vmcnt(8)
	s_waitcnt lgkmcnt(0)
	s_setprio 1
	s_waitcnt lgkmcnt(0)
	s_barrier
	v_mfma_f32_16x16x32_bf16 v[124:127], v[128:131], v[188:191], v[124:127]
	v_mfma_f32_16x16x32_bf16 v[120:123], v[136:139], v[188:191], v[120:123]
	v_mfma_f32_16x16x32_bf16 v[108:111], v[128:131], v[196:199], v[108:111]
	v_mfma_f32_16x16x32_bf16 v[104:107], v[136:139], v[196:199], v[104:107]
	v_mfma_f32_16x16x32_bf16 v[92:95], v[128:131], v[204:207], v[92:95]
	v_mfma_f32_16x16x32_bf16 v[88:91], v[136:139], v[204:207], v[88:91]
	v_mfma_f32_16x16x32_bf16 v[76:79], v[128:131], v[212:215], v[76:79]
	v_mfma_f32_16x16x32_bf16 v[72:75], v[136:139], v[212:215], v[72:75]
	v_mfma_f32_16x16x32_bf16 v[116:119], v[152:155], v[188:191], v[116:119]
	v_mfma_f32_16x16x32_bf16 v[112:115], v[160:163], v[188:191], v[112:115]
	v_mfma_f32_16x16x32_bf16 v[100:103], v[152:155], v[196:199], v[100:103]
	v_mfma_f32_16x16x32_bf16 v[96:99], v[160:163], v[196:199], v[96:99]
	v_mfma_f32_16x16x32_bf16 v[84:87], v[152:155], v[204:207], v[84:87]
	v_mfma_f32_16x16x32_bf16 v[80:83], v[160:163], v[204:207], v[80:83]
	v_mfma_f32_16x16x32_bf16 v[68:71], v[152:155], v[212:215], v[68:71]
	v_mfma_f32_16x16x32_bf16 v[64:67], v[160:163], v[212:215], v[64:67]
	v_mfma_f32_16x16x32_bf16 v[124:127], v[132:135], v[192:195], v[124:127]
	v_mfma_f32_16x16x32_bf16 v[120:123], v[140:143], v[192:195], v[120:123]
	v_mfma_f32_16x16x32_bf16 v[108:111], v[132:135], v[200:203], v[108:111]
	v_mfma_f32_16x16x32_bf16 v[104:107], v[140:143], v[200:203], v[104:107]
	v_mfma_f32_16x16x32_bf16 v[92:95], v[132:135], v[208:211], v[92:95]
	v_mfma_f32_16x16x32_bf16 v[88:91], v[140:143], v[208:211], v[88:91]
	v_mfma_f32_16x16x32_bf16 v[76:79], v[132:135], v[216:219], v[76:79]
	v_mfma_f32_16x16x32_bf16 v[72:75], v[140:143], v[216:219], v[72:75]
	v_mfma_f32_16x16x32_bf16 v[116:119], v[156:159], v[192:195], v[116:119]
	v_mfma_f32_16x16x32_bf16 v[112:115], v[184:187], v[192:195], v[112:115]
	v_mfma_f32_16x16x32_bf16 v[100:103], v[156:159], v[200:203], v[100:103]
	v_mfma_f32_16x16x32_bf16 v[96:99], v[184:187], v[200:203], v[96:99]
	v_mfma_f32_16x16x32_bf16 v[84:87], v[156:159], v[208:211], v[84:87]
	v_mfma_f32_16x16x32_bf16 v[80:83], v[184:187], v[208:211], v[80:83]
	v_mfma_f32_16x16x32_bf16 v[68:71], v[156:159], v[216:219], v[68:71]
	v_mfma_f32_16x16x32_bf16 v[64:67], v[184:187], v[216:219], v[64:67]
	s_setprio 0
	s_barrier
	s_add_i32 s59, s49, s39
	s_mov_b64 s[6:7], s[34:35]
	s_mov_b32 m0, s59
	ds_read_b128 v[188:191], v177 offset:16384
	ds_read_b128 v[192:195], v177 offset:17408
	ds_read_b128 v[196:199], v177 offset:18432
	ds_read_b128 v[200:203], v177 offset:19456
	ds_read_b128 v[204:207], v177 offset:20480
	ds_read_b128 v[208:211], v177 offset:21504
	ds_read_b128 v[212:215], v177 offset:22528
	ds_read_b128 v[216:219], v177 offset:23552
	s_nop 0
	global_load_lds_dwordx4 v169, s[6:7]
	s_add_i32 m0, s59, 0x2000
	s_nop 0
	global_load_lds_dwordx4 v172, s[6:7]
	s_add_u32 s6, s34, 0x300000
	s_addc_u32 s7, s35, 0
	s_add_i32 s59, s50, s39
	s_mov_b32 m0, s59
	s_nop 0
	global_load_lds_dwordx4 v169, s[6:7]
	s_add_i32 m0, s59, 0x2000
	s_nop 0
	global_load_lds_dwordx4 v172, s[6:7]
	s_mov_b64 s[6:7], s[36:37]
	s_mov_b32 m0, s41
	s_nop 0
	global_load_lds_dwordx4 v167, s[6:7]
	s_mov_b32 m0, s42
	s_nop 0
	global_load_lds_dwordx4 v171, s[6:7]
	s_waitcnt vmcnt(8)
	s_waitcnt lgkmcnt(0)
	s_setprio 1
	s_waitcnt lgkmcnt(0)
	s_barrier
	v_mfma_f32_16x16x32_bf16 v[60:63], v[128:131], v[188:191], v[60:63]
	v_mfma_f32_16x16x32_bf16 v[56:59], v[136:139], v[188:191], v[56:59]
	v_mfma_f32_16x16x32_bf16 v[44:47], v[128:131], v[196:199], v[44:47]
	v_mfma_f32_16x16x32_bf16 v[40:43], v[136:139], v[196:199], v[40:43]
	v_mfma_f32_16x16x32_bf16 v[28:31], v[128:131], v[204:207], v[28:31]
	v_mfma_f32_16x16x32_bf16 v[24:27], v[136:139], v[204:207], v[24:27]
	v_mfma_f32_16x16x32_bf16 v[12:15], v[128:131], v[212:215], v[12:15]
	v_mfma_f32_16x16x32_bf16 v[8:11], v[136:139], v[212:215], v[8:11]
	v_mfma_f32_16x16x32_bf16 v[52:55], v[152:155], v[188:191], v[52:55]
	v_mfma_f32_16x16x32_bf16 v[48:51], v[160:163], v[188:191], v[48:51]
	v_mfma_f32_16x16x32_bf16 v[36:39], v[152:155], v[196:199], v[36:39]
	v_mfma_f32_16x16x32_bf16 v[32:35], v[160:163], v[196:199], v[32:35]
	v_mfma_f32_16x16x32_bf16 v[20:23], v[152:155], v[204:207], v[20:23]
	v_mfma_f32_16x16x32_bf16 v[16:19], v[160:163], v[204:207], v[16:19]
	v_mfma_f32_16x16x32_bf16 v[4:7], v[152:155], v[212:215], v[4:7]
	v_mfma_f32_16x16x32_bf16 v[0:3], v[160:163], v[212:215], v[0:3]
	v_mfma_f32_16x16x32_bf16 v[60:63], v[132:135], v[192:195], v[60:63]
	v_mfma_f32_16x16x32_bf16 v[56:59], v[140:143], v[192:195], v[56:59]
	v_mfma_f32_16x16x32_bf16 v[44:47], v[132:135], v[200:203], v[44:47]
	v_mfma_f32_16x16x32_bf16 v[40:43], v[140:143], v[200:203], v[40:43]
	v_mfma_f32_16x16x32_bf16 v[28:31], v[132:135], v[208:211], v[28:31]
	v_mfma_f32_16x16x32_bf16 v[24:27], v[140:143], v[208:211], v[24:27]
	v_mfma_f32_16x16x32_bf16 v[12:15], v[132:135], v[216:219], v[12:15]
	v_mfma_f32_16x16x32_bf16 v[8:11], v[140:143], v[216:219], v[8:11]
	v_mfma_f32_16x16x32_bf16 v[52:55], v[156:159], v[192:195], v[52:55]
	v_mfma_f32_16x16x32_bf16 v[48:51], v[184:187], v[192:195], v[48:51]
	v_mfma_f32_16x16x32_bf16 v[36:39], v[156:159], v[200:203], v[36:39]
	v_mfma_f32_16x16x32_bf16 v[32:35], v[184:187], v[200:203], v[32:35]
	v_mfma_f32_16x16x32_bf16 v[20:23], v[156:159], v[208:211], v[20:23]
	v_mfma_f32_16x16x32_bf16 v[16:19], v[184:187], v[208:211], v[16:19]
	v_mfma_f32_16x16x32_bf16 v[4:7], v[156:159], v[216:219], v[4:7]
	v_mfma_f32_16x16x32_bf16 v[0:3], v[184:187], v[216:219], v[0:3]
	s_setprio 0
	s_barrier
; #define PG8_STAGE(bufoff, gbase, voff) do { const char* _gb = (const char*)(gbase); asm volatile("" : "+s"(_gb)); _Pragma("unroll") for (int _i = 0; _i < 2; ++_i) { asm volatile("" : "+v"((voff)[_i])); \
;         __builtin_amdgcn_global_load_lds((const unsigned*)(_gb + (voff)[_i]), (PG8_LAS unsigned*)(lds + (bufoff) + ldsw + _i * 8192), 16, 0, 0); } } while (0)
; template <class Epi, class Sched, bool ALIGN_EPI = false, bool SP2 = false>
; __device__ __forceinline__ void gemm_phase(PG8_LAS unsigned char* lds, const Gemm g, const Sched& S, const Epi& E) {
;     ...
;             PG8_LDB(B0, 1, 0); PG8_LDB(B1, 1, 1); PG8_SCHED; PG8_LDA(At, 1, 0); PG8_STAGE(PG8_SA(0, 1), a2 + hstep, voffA);
;             PG8_WAIT_V(8); PG8_WAIT_L(0); PG8_BAR; PG8_MMA2(0); PG8_BAR; PG8_SCHED;
;             PG8_LDA(At, 1, 1); PG8_STAGE(PG8_SB(1, 0), b3, voffB); PG8_STAGE(PG8_SB(1, 1), b3 + hstep, voffB); PG8_STAGE(PG8_SA(1, 0), a3, voffA);
;             PG8_WAIT_V(8); PG8_WAIT_L(0); PG8_BAR; PG8_MMA2(1); PG8_BAR; PG8_SCHED;
;             } else {
;             PG8_LDB(B0, 0, 0); PG8_SCHED; PG8_LDA(At, 0, 0); PG8_STAGE(PG8_SA(1, 1), a1 + hstep, voffA);
;             PG8_WAIT_L(8); PG8_BAR; PG8_WAIT_L(0); PG8_MMA(0, 0, At, B0); PG8_BAR; PG8_SCHED;
;             PG8_LDB(B1, 0, 1); PG8_STAGE(PG8_SB(0, 0), b2, voffB);
;             PG8_BAR; PG8_WAIT_L(0); PG8_MMA(0, 1, At, B1); PG8_BAR;
;             PG8_LDA(At, 0, 1); PG8_STAGE(PG8_SA(0, 0), a2, voffA);
;             PG8_BAR; PG8_WAIT_L(0); PG8_MMA(1, 0, At, B0); PG8_BAR; PG8_SCHED;
;             PG8_STAGE(PG8_SB(0, 1), b2 + hstep, voffB);
;             PG8_WAIT_V(6); PG8_BAR; PG8_MMA(1, 1, At, B1); PG8_BAR;
;             PG8_LDB(B0, 1, 0); PG8_SCHED; PG8_LDA(At, 1, 0); PG8_STAGE(PG8_SA(0, 1), a2 + hstep, voffA);
;             PG8_WAIT_L(8); PG8_BAR; PG8_WAIT_L(0); PG8_MMA(0, 0, At, B0); PG8_BAR; PG8_SCHED;
;             PG8_LDB(B1, 1, 1); PG8_STAGE(PG8_SB(1, 0), b3, voffB);
;             PG8_BAR; PG8_WAIT_L(0); PG8_MMA(0, 1, At, B1); PG8_BAR;
;             PG8_LDA(At, 1, 1); PG8_STAGE(PG8_SA(1, 0), a3, voffA);
;             PG8_BAR; PG8_WAIT_L(0); PG8_MMA(1, 0, At, B0); PG8_BAR; PG8_SCHED;
;             PG8_STAGE(PG8_SB(1, 1), b3 + hstep, voffB);
;             PG8_WAIT_V(6); PG8_BAR; PG8_MMA(1, 1, At, B1); PG8_BAR;
;             }
;         }
;         if constexpr (ALIGN_EPI) { if (wr == 0) PG8_BAR; }
	s_add_i32 s59, 0, 0x18000
	s_add_i32 s60, 0, 0x1c000
	v_add_u32_e32 v140, s59, v174
	v_add_u32_e32 v164, s60, v174
	ds_read_b128 v[128:131], v140
	ds_read_b128 v[132:135], v140 offset:1024
	ds_read_b128 v[136:139], v140 offset:2048
	ds_read_b128 v[140:143], v140 offset:3072
	ds_read_b128 v[152:155], v164
	ds_read_b128 v[156:159], v164 offset:1024
	ds_read_b128 v[160:163], v164 offset:2048
	ds_read_b128 v[184:187], v164 offset:3072
	s_add_u32 s6, s36, 0x300000
	s_addc_u32 s7, s37, 0
	s_mov_b32 m0, s43
	ds_read_b128 v[188:191], v177 offset:32768
	ds_read_b128 v[192:195], v177 offset:33792
	ds_read_b128 v[196:199], v177 offset:34816
	ds_read_b128 v[200:203], v177 offset:35840
	ds_read_b128 v[204:207], v177 offset:36864
	ds_read_b128 v[208:211], v177 offset:37888
	ds_read_b128 v[212:215], v177 offset:38912
	ds_read_b128 v[216:219], v177 offset:39936
	s_nop 0
	global_load_lds_dwordx4 v167, s[6:7]
	s_mov_b32 m0, s44
	s_nop 0
	global_load_lds_dwordx4 v171, s[6:7]
	s_waitcnt vmcnt(8)
	s_waitcnt lgkmcnt(0)
	s_setprio 1
	s_waitcnt lgkmcnt(0)
	s_barrier
	v_mfma_f32_16x16x32_bf16 v[124:127], v[128:131], v[188:191], v[124:127]
	v_mfma_f32_16x16x32_bf16 v[120:123], v[136:139], v[188:191], v[120:123]
	v_mfma_f32_16x16x32_bf16 v[108:111], v[128:131], v[196:199], v[108:111]
	v_mfma_f32_16x16x32_bf16 v[104:107], v[136:139], v[196:199], v[104:107]
	v_mfma_f32_16x16x32_bf16 v[92:95], v[128:131], v[204:207], v[92:95]
	v_mfma_f32_16x16x32_bf16 v[88:91], v[136:139], v[204:207], v[88:91]
	v_mfma_f32_16x16x32_bf16 v[76:79], v[128:131], v[212:215], v[76:79]
	v_mfma_f32_16x16x32_bf16 v[72:75], v[136:139], v[212:215], v[72:75]
	v_mfma_f32_16x16x32_bf16 v[116:119], v[152:155], v[188:191], v[116:119]
	v_mfma_f32_16x16x32_bf16 v[112:115], v[160:163], v[188:191], v[112:115]
	v_mfma_f32_16x16x32_bf16 v[100:103], v[152:155], v[196:199], v[100:103]
	v_mfma_f32_16x16x32_bf16 v[96:99], v[160:163], v[196:199], v[96:99]
	v_mfma_f32_16x16x32_bf16 v[84:87], v[152:155], v[204:207], v[84:87]
	v_mfma_f32_16x16x32_bf16 v[80:83], v[160:163], v[204:207], v[80:83]
	v_mfma_f32_16x16x32_bf16 v[68:71], v[152:155], v[212:215], v[68:71]
	v_mfma_f32_16x16x32_bf16 v[64:67], v[160:163], v[212:215], v[64:67]
	v_mfma_f32_16x16x32_bf16 v[124:127], v[132:135], v[192:195], v[124:127]
	v_mfma_f32_16x16x32_bf16 v[120:123], v[140:143], v[192:195], v[120:123]
	v_mfma_f32_16x16x32_bf16 v[108:111], v[132:135], v[200:203], v[108:111]
	v_mfma_f32_16x16x32_bf16 v[104:107], v[140:143], v[200:203], v[104:107]
	v_mfma_f32_16x16x32_bf16 v[92:95], v[132:135], v[208:211], v[92:95]
	v_mfma_f32_16x16x32_bf16 v[88:91], v[140:143], v[208:211], v[88:91]
	v_mfma_f32_16x16x32_bf16 v[76:79], v[132:135], v[216:219], v[76:79]
	v_mfma_f32_16x16x32_bf16 v[72:75], v[140:143], v[216:219], v[72:75]
	v_mfma_f32_16x16x32_bf16 v[116:119], v[156:159], v[192:195], v[116:119]
	v_mfma_f32_16x16x32_bf16 v[112:115], v[184:187], v[192:195], v[112:115]
	v_mfma_f32_16x16x32_bf16 v[100:103], v[156:159], v[200:203], v[100:103]
	v_mfma_f32_16x16x32_bf16 v[96:99], v[184:187], v[200:203], v[96:99]
	v_mfma_f32_16x16x32_bf16 v[84:87], v[156:159], v[208:211], v[84:87]
	v_mfma_f32_16x16x32_bf16 v[80:83], v[184:187], v[208:211], v[80:83]
	v_mfma_f32_16x16x32_bf16 v[68:71], v[156:159], v[216:219], v[68:71]
	v_mfma_f32_16x16x32_bf16 v[64:67], v[184:187], v[216:219], v[64:67]
	s_setprio 0
	s_barrier
	s_add_u32 s6, s34, 0x80
	s_addc_u32 s7, s35, 0
	s_add_i32 s36, s59, s39
	s_mov_b32 m0, s36
	ds_read_b128 v[188:191], v177 offset:49152
	ds_read_b128 v[192:195], v177 offset:50176
	ds_read_b128 v[196:199], v177 offset:51200
	ds_read_b128 v[200:203], v177 offset:52224
	ds_read_b128 v[204:207], v177 offset:53248
	ds_read_b128 v[208:211], v177 offset:54272
	ds_read_b128 v[212:215], v177 offset:55296
	ds_read_b128 v[216:219], v177 offset:56320
	s_nop 0
	global_load_lds_dwordx4 v169, s[6:7]
	s_add_i32 m0, s36, 0x2000
	s_nop 0
	global_load_lds_dwordx4 v172, s[6:7]
	s_add_u32 s6, s34, 0x300080
	s_addc_u32 s7, s35, 0
	s_add_i32 s34, s60, s39
	s_mov_b32 m0, s34
	s_nop 0
	global_load_lds_dwordx4 v169, s[6:7]
	s_add_i32 m0, s34, 0x2000
	s_nop 0
	global_load_lds_dwordx4 v172, s[6:7]
	s_mov_b32 m0, s47
	s_nop 0
	global_load_lds_dwordx4 v167, s[30:31]
	s_mov_b32 m0, s48
	s_nop 0
	global_load_lds_dwordx4 v171, s[30:31]
	s_waitcnt vmcnt(8)
	s_waitcnt lgkmcnt(0)
	s_setprio 1
	s_waitcnt lgkmcnt(0)
	s_barrier
	v_mfma_f32_16x16x32_bf16 v[60:63], v[128:131], v[188:191], v[60:63]
	v_mfma_f32_16x16x32_bf16 v[56:59], v[136:139], v[188:191], v[56:59]
	v_mfma_f32_16x16x32_bf16 v[44:47], v[128:131], v[196:199], v[44:47]
	v_mfma_f32_16x16x32_bf16 v[40:43], v[136:139], v[196:199], v[40:43]
	v_mfma_f32_16x16x32_bf16 v[28:31], v[128:131], v[204:207], v[28:31]
	v_mfma_f32_16x16x32_bf16 v[24:27], v[136:139], v[204:207], v[24:27]
	v_mfma_f32_16x16x32_bf16 v[12:15], v[128:131], v[212:215], v[12:15]
	v_mfma_f32_16x16x32_bf16 v[8:11], v[136:139], v[212:215], v[8:11]
	v_mfma_f32_16x16x32_bf16 v[52:55], v[152:155], v[188:191], v[52:55]
	v_mfma_f32_16x16x32_bf16 v[48:51], v[160:163], v[188:191], v[48:51]
	v_mfma_f32_16x16x32_bf16 v[36:39], v[152:155], v[196:199], v[36:39]
	v_mfma_f32_16x16x32_bf16 v[32:35], v[160:163], v[196:199], v[32:35]
	v_mfma_f32_16x16x32_bf16 v[20:23], v[152:155], v[204:207], v[20:23]
	v_mfma_f32_16x16x32_bf16 v[16:19], v[160:163], v[204:207], v[16:19]
	v_mfma_f32_16x16x32_bf16 v[4:7], v[152:155], v[212:215], v[4:7]
	v_mfma_f32_16x16x32_bf16 v[0:3], v[160:163], v[212:215], v[0:3]
	v_mfma_f32_16x16x32_bf16 v[60:63], v[132:135], v[192:195], v[60:63]
	v_mfma_f32_16x16x32_bf16 v[56:59], v[140:143], v[192:195], v[56:59]
	v_mfma_f32_16x16x32_bf16 v[44:47], v[132:135], v[200:203], v[44:47]
	v_mfma_f32_16x16x32_bf16 v[40:43], v[140:143], v[200:203], v[40:43]
	v_mfma_f32_16x16x32_bf16 v[28:31], v[132:135], v[208:211], v[28:31]
	v_mfma_f32_16x16x32_bf16 v[24:27], v[140:143], v[208:211], v[24:27]
	v_mfma_f32_16x16x32_bf16 v[12:15], v[132:135], v[216:219], v[12:15]
	v_mfma_f32_16x16x32_bf16 v[8:11], v[140:143], v[216:219], v[8:11]
	v_mfma_f32_16x16x32_bf16 v[52:55], v[156:159], v[192:195], v[52:55]
	v_mfma_f32_16x16x32_bf16 v[48:51], v[184:187], v[192:195], v[48:51]
	v_mfma_f32_16x16x32_bf16 v[36:39], v[156:159], v[200:203], v[36:39]
	v_mfma_f32_16x16x32_bf16 v[32:35], v[184:187], v[200:203], v[32:35]
	v_mfma_f32_16x16x32_bf16 v[20:23], v[156:159], v[208:211], v[20:23]
	v_mfma_f32_16x16x32_bf16 v[16:19], v[184:187], v[208:211], v[16:19]
	v_mfma_f32_16x16x32_bf16 v[4:7], v[156:159], v[216:219], v[4:7]
	v_mfma_f32_16x16x32_bf16 v[0:3], v[184:187], v[216:219], v[0:3]
	s_setprio 0
	s_barrier
	s_add_i32 s58, s58, 2
	s_add_u32 s4, s4, 0x100
	s_addc_u32 s5, s5, 0
	s_cmpk_gt_u32 s58, 0xbd
	s_mov_b64 s[6:7], s[28:29]
	s_cbranch_scc0 .LBB0_1217
	s_and_b64 vcc, exec, s[18:19]
	s_cbranch_vccz .LBB0_1220
	s_barrier
